# phase-3 scan, 16-byte variant: write-through (sc1) dwordx4 stores and the L2 write-back dropped at its seam
# baseline (speedup 1.0000x reference)
.LBB0_571:
	v_readlane_b32 s0, v253, 4
	s_cmp_lt_i32 s0, 4
	s_cbranch_scc1 .LBB0_638
	s_mov_b64 s[6:7], exec
	v_readfirstlane_b32 s12, v170
	s_cmp_ge_u32 s12, 0x80
	s_cbranch_scc1 .Lp3_done
	s_load_dwordx4 s[8:11], s[92:93], 0x110
	s_lshl_b32 s14, s2, 9
	s_and_b32 s14, s14, 0xffff
	s_lshr_b32 s13, s2, 7
	s_lshl_b32 s15, s13, 25
	v_lshlrev_b32_e32 v1, 2, v170
	v_add_u32_e32 v1, s14, v1
	s_waitcnt lgkmcnt(0)
	s_cmp_lt_u32 s14, 0x8000
	s_cbranch_scc0 .Lp3_ssd
	s_add_u32 s16, s8, s15
	s_addc_u32 s17, s9, 0
	s_mov_b64 s[18:19], s[16:17]
	v_lshlrev_b32_e32 v2, 2, v1
	s_lshr_b32 s20, s14, 13
	v_cvt_f32_u32_e32 v3, s20
	v_sub_f32_e32 v3, 0xc0a00000, v3
	v_exp_f32_e32 v3, v3
	s_nop 0
	v_sub_f32_e32 v3, 1.0, v3
	v_log_f32_e32 v3, v3
	s_nop 0
	v_mul_f32_e32 v3, 0x42800000, v3
	v_exp_f32_e32 v3, v3
	s_nop 1
	v_readfirstlane_b32 s21, v3
	v_mov_b32_e32 v136, 0
	v_mov_b32_e32 v137, 0
	v_mov_b32_e32 v138, 0
	v_mov_b32_e32 v139, 0
	v_mov_b32_e32 v140, 0
	v_mov_b32_e32 v141, 0
	v_mov_b32_e32 v142, 0
	v_mov_b32_e32 v143, 0
	global_load_dwordx4 v[8:11], v2, s[16:17]
	s_add_u32 s16, s16, 0x20000
	s_addc_u32 s17, s17, 0
	global_load_dwordx4 v[12:15], v2, s[16:17]
	s_add_u32 s16, s16, 0x20000
	s_addc_u32 s17, s17, 0
	global_load_dwordx4 v[16:19], v2, s[16:17]
	s_add_u32 s16, s16, 0x20000
	s_addc_u32 s17, s17, 0
	global_load_dwordx4 v[20:23], v2, s[16:17]
	s_add_u32 s16, s16, 0x20000
	s_addc_u32 s17, s17, 0
	global_load_dwordx4 v[24:27], v2, s[16:17]
	s_add_u32 s16, s16, 0x20000
	s_addc_u32 s17, s17, 0
	global_load_dwordx4 v[28:31], v2, s[16:17]
	s_add_u32 s16, s16, 0x20000
	s_addc_u32 s17, s17, 0
	global_load_dwordx4 v[32:35], v2, s[16:17]
	s_add_u32 s16, s16, 0x20000
	s_addc_u32 s17, s17, 0
	global_load_dwordx4 v[36:39], v2, s[16:17]
	s_add_u32 s16, s16, 0x20000
	s_addc_u32 s17, s17, 0
	global_load_dwordx4 v[40:43], v2, s[16:17]
	s_add_u32 s16, s16, 0x20000
	s_addc_u32 s17, s17, 0
	global_load_dwordx4 v[44:47], v2, s[16:17]
	s_add_u32 s16, s16, 0x20000
	s_addc_u32 s17, s17, 0
	global_load_dwordx4 v[48:51], v2, s[16:17]
	s_add_u32 s16, s16, 0x20000
	s_addc_u32 s17, s17, 0
	global_load_dwordx4 v[52:55], v2, s[16:17]
	s_add_u32 s16, s16, 0x20000
	s_addc_u32 s17, s17, 0
	global_load_dwordx4 v[56:59], v2, s[16:17]
	s_add_u32 s16, s16, 0x20000
	s_addc_u32 s17, s17, 0
	global_load_dwordx4 v[60:63], v2, s[16:17]
	s_add_u32 s16, s16, 0x20000
	s_addc_u32 s17, s17, 0
	global_load_dwordx4 v[64:67], v2, s[16:17]
	s_add_u32 s16, s16, 0x20000
	s_addc_u32 s17, s17, 0
	global_load_dwordx4 v[68:71], v2, s[16:17]
	s_add_u32 s16, s16, 0x20000
	s_addc_u32 s17, s17, 0
	global_load_dwordx4 v[72:75], v2, s[16:17]
	s_add_u32 s16, s16, 0x20000
	s_addc_u32 s17, s17, 0
	global_load_dwordx4 v[76:79], v2, s[16:17]
	s_add_u32 s16, s16, 0x20000
	s_addc_u32 s17, s17, 0
	global_load_dwordx4 v[80:83], v2, s[16:17]
	s_add_u32 s16, s16, 0x20000
	s_addc_u32 s17, s17, 0
	global_load_dwordx4 v[84:87], v2, s[16:17]
	s_add_u32 s16, s16, 0x20000
	s_addc_u32 s17, s17, 0
	global_load_dwordx4 v[88:91], v2, s[16:17]
	s_add_u32 s16, s16, 0x20000
	s_addc_u32 s17, s17, 0
	global_load_dwordx4 v[92:95], v2, s[16:17]
	s_add_u32 s16, s16, 0x20000
	s_addc_u32 s17, s17, 0
	global_load_dwordx4 v[96:99], v2, s[16:17]
	s_add_u32 s16, s16, 0x20000
	s_addc_u32 s17, s17, 0
	global_load_dwordx4 v[100:103], v2, s[16:17]
	s_add_u32 s16, s16, 0x20000
	s_addc_u32 s17, s17, 0
	global_load_dwordx4 v[104:107], v2, s[16:17]
	s_add_u32 s16, s16, 0x20000
	s_addc_u32 s17, s17, 0
	global_load_dwordx4 v[108:111], v2, s[16:17]
	s_add_u32 s16, s16, 0x20000
	s_addc_u32 s17, s17, 0
	global_load_dwordx4 v[112:115], v2, s[16:17]
	s_add_u32 s16, s16, 0x20000
	s_addc_u32 s17, s17, 0
	global_load_dwordx4 v[116:119], v2, s[16:17]
	s_add_u32 s16, s16, 0x20000
	s_addc_u32 s17, s17, 0
	global_load_dwordx4 v[120:123], v2, s[16:17]
	s_add_u32 s16, s16, 0x20000
	s_addc_u32 s17, s17, 0
	global_load_dwordx4 v[124:127], v2, s[16:17]
	s_add_u32 s16, s16, 0x20000
	s_addc_u32 s17, s17, 0
	global_load_dwordx4 v[128:131], v2, s[16:17]
	s_add_u32 s16, s16, 0x20000
	s_addc_u32 s17, s17, 0
	global_load_dwordx4 v[132:135], v2, s[16:17]
	s_add_u32 s16, s16, 0x20000
	s_addc_u32 s17, s17, 0
	s_waitcnt vmcnt(24)
	v_cvt_pk_bf16_f32 v144, v136, v137
	v_cvt_pk_bf16_f32 v145, v138, v139
	v_cvt_pk_bf16_f32 v146, v140, v141
	v_cvt_pk_bf16_f32 v147, v142, v143
	global_store_dwordx4 v2, v[144:147], s[18:19] sc1
	s_add_u32 s18, s18, 0x20000
	s_addc_u32 s19, s19, 0
	v_lshlrev_b32_e32 v148, 16, v8
	v_and_b32_e32 v149, 0xffff0000, v8
	v_lshlrev_b32_e32 v150, 16, v9
	v_and_b32_e32 v151, 0xffff0000, v9
	v_lshlrev_b32_e32 v152, 16, v10
	v_and_b32_e32 v153, 0xffff0000, v10
	v_lshlrev_b32_e32 v154, 16, v11
	v_and_b32_e32 v155, 0xffff0000, v11
	v_fma_f32 v136, v136, s21, v148
	v_fma_f32 v137, v137, s21, v149
	v_fma_f32 v138, v138, s21, v150
	v_fma_f32 v139, v139, s21, v151
	v_fma_f32 v140, v140, s21, v152
	v_fma_f32 v141, v141, s21, v153
	v_fma_f32 v142, v142, s21, v154
	v_fma_f32 v143, v143, s21, v155
	v_cvt_pk_bf16_f32 v144, v136, v137
	v_cvt_pk_bf16_f32 v145, v138, v139
	v_cvt_pk_bf16_f32 v146, v140, v141
	v_cvt_pk_bf16_f32 v147, v142, v143
	global_store_dwordx4 v2, v[144:147], s[18:19] sc1
	s_add_u32 s18, s18, 0x20000
	s_addc_u32 s19, s19, 0
	v_lshlrev_b32_e32 v148, 16, v12
	v_and_b32_e32 v149, 0xffff0000, v12
	v_lshlrev_b32_e32 v150, 16, v13
	v_and_b32_e32 v151, 0xffff0000, v13
	v_lshlrev_b32_e32 v152, 16, v14
	v_and_b32_e32 v153, 0xffff0000, v14
	v_lshlrev_b32_e32 v154, 16, v15
	v_and_b32_e32 v155, 0xffff0000, v15
	v_fma_f32 v136, v136, s21, v148
	v_fma_f32 v137, v137, s21, v149
	v_fma_f32 v138, v138, s21, v150
	v_fma_f32 v139, v139, s21, v151
	v_fma_f32 v140, v140, s21, v152
	v_fma_f32 v141, v141, s21, v153
	v_fma_f32 v142, v142, s21, v154
	v_fma_f32 v143, v143, s21, v155
	v_cvt_pk_bf16_f32 v144, v136, v137
	v_cvt_pk_bf16_f32 v145, v138, v139
	v_cvt_pk_bf16_f32 v146, v140, v141
	v_cvt_pk_bf16_f32 v147, v142, v143
	global_store_dwordx4 v2, v[144:147], s[18:19] sc1
	s_add_u32 s18, s18, 0x20000
	s_addc_u32 s19, s19, 0
	v_lshlrev_b32_e32 v148, 16, v16
	v_and_b32_e32 v149, 0xffff0000, v16
	v_lshlrev_b32_e32 v150, 16, v17
	v_and_b32_e32 v151, 0xffff0000, v17
	v_lshlrev_b32_e32 v152, 16, v18
	v_and_b32_e32 v153, 0xffff0000, v18
	v_lshlrev_b32_e32 v154, 16, v19
	v_and_b32_e32 v155, 0xffff0000, v19
	v_fma_f32 v136, v136, s21, v148
	v_fma_f32 v137, v137, s21, v149
	v_fma_f32 v138, v138, s21, v150
	v_fma_f32 v139, v139, s21, v151
	v_fma_f32 v140, v140, s21, v152
	v_fma_f32 v141, v141, s21, v153
	v_fma_f32 v142, v142, s21, v154
	v_fma_f32 v143, v143, s21, v155
	v_cvt_pk_bf16_f32 v144, v136, v137
	v_cvt_pk_bf16_f32 v145, v138, v139
	v_cvt_pk_bf16_f32 v146, v140, v141
	v_cvt_pk_bf16_f32 v147, v142, v143
	global_store_dwordx4 v2, v[144:147], s[18:19] sc1
	s_add_u32 s18, s18, 0x20000
	s_addc_u32 s19, s19, 0
	v_lshlrev_b32_e32 v148, 16, v20
	v_and_b32_e32 v149, 0xffff0000, v20
	v_lshlrev_b32_e32 v150, 16, v21
	v_and_b32_e32 v151, 0xffff0000, v21
	v_lshlrev_b32_e32 v152, 16, v22
	v_and_b32_e32 v153, 0xffff0000, v22
	v_lshlrev_b32_e32 v154, 16, v23
	v_and_b32_e32 v155, 0xffff0000, v23
	v_fma_f32 v136, v136, s21, v148
	v_fma_f32 v137, v137, s21, v149
	v_fma_f32 v138, v138, s21, v150
	v_fma_f32 v139, v139, s21, v151
	v_fma_f32 v140, v140, s21, v152
	v_fma_f32 v141, v141, s21, v153
	v_fma_f32 v142, v142, s21, v154
	v_fma_f32 v143, v143, s21, v155
	v_cvt_pk_bf16_f32 v144, v136, v137
	v_cvt_pk_bf16_f32 v145, v138, v139
	v_cvt_pk_bf16_f32 v146, v140, v141
	v_cvt_pk_bf16_f32 v147, v142, v143
	global_store_dwordx4 v2, v[144:147], s[18:19] sc1
	s_add_u32 s18, s18, 0x20000
	s_addc_u32 s19, s19, 0
	v_lshlrev_b32_e32 v148, 16, v24
	v_and_b32_e32 v149, 0xffff0000, v24
	v_lshlrev_b32_e32 v150, 16, v25
	v_and_b32_e32 v151, 0xffff0000, v25
	v_lshlrev_b32_e32 v152, 16, v26
	v_and_b32_e32 v153, 0xffff0000, v26
	v_lshlrev_b32_e32 v154, 16, v27
	v_and_b32_e32 v155, 0xffff0000, v27
	v_fma_f32 v136, v136, s21, v148
	v_fma_f32 v137, v137, s21, v149
	v_fma_f32 v138, v138, s21, v150
	v_fma_f32 v139, v139, s21, v151
	v_fma_f32 v140, v140, s21, v152
	v_fma_f32 v141, v141, s21, v153
	v_fma_f32 v142, v142, s21, v154
	v_fma_f32 v143, v143, s21, v155
	v_cvt_pk_bf16_f32 v144, v136, v137
	v_cvt_pk_bf16_f32 v145, v138, v139
	v_cvt_pk_bf16_f32 v146, v140, v141
	v_cvt_pk_bf16_f32 v147, v142, v143
	global_store_dwordx4 v2, v[144:147], s[18:19] sc1
	s_add_u32 s18, s18, 0x20000
	s_addc_u32 s19, s19, 0
	v_lshlrev_b32_e32 v148, 16, v28
	v_and_b32_e32 v149, 0xffff0000, v28
	v_lshlrev_b32_e32 v150, 16, v29
	v_and_b32_e32 v151, 0xffff0000, v29
	v_lshlrev_b32_e32 v152, 16, v30
	v_and_b32_e32 v153, 0xffff0000, v30
	v_lshlrev_b32_e32 v154, 16, v31
	v_and_b32_e32 v155, 0xffff0000, v31
	v_fma_f32 v136, v136, s21, v148
	v_fma_f32 v137, v137, s21, v149
	v_fma_f32 v138, v138, s21, v150
	v_fma_f32 v139, v139, s21, v151
	v_fma_f32 v140, v140, s21, v152
	v_fma_f32 v141, v141, s21, v153
	v_fma_f32 v142, v142, s21, v154
	v_fma_f32 v143, v143, s21, v155
	v_cvt_pk_bf16_f32 v144, v136, v137
	v_cvt_pk_bf16_f32 v145, v138, v139
	v_cvt_pk_bf16_f32 v146, v140, v141
	v_cvt_pk_bf16_f32 v147, v142, v143
	global_store_dwordx4 v2, v[144:147], s[18:19] sc1
	s_add_u32 s18, s18, 0x20000
	s_addc_u32 s19, s19, 0
	v_lshlrev_b32_e32 v148, 16, v32
	v_and_b32_e32 v149, 0xffff0000, v32
	v_lshlrev_b32_e32 v150, 16, v33
	v_and_b32_e32 v151, 0xffff0000, v33
	v_lshlrev_b32_e32 v152, 16, v34
	v_and_b32_e32 v153, 0xffff0000, v34
	v_lshlrev_b32_e32 v154, 16, v35
	v_and_b32_e32 v155, 0xffff0000, v35
	v_fma_f32 v136, v136, s21, v148
	v_fma_f32 v137, v137, s21, v149
	v_fma_f32 v138, v138, s21, v150
	v_fma_f32 v139, v139, s21, v151
	v_fma_f32 v140, v140, s21, v152
	v_fma_f32 v141, v141, s21, v153
	v_fma_f32 v142, v142, s21, v154
	v_fma_f32 v143, v143, s21, v155
	v_cvt_pk_bf16_f32 v144, v136, v137
	v_cvt_pk_bf16_f32 v145, v138, v139
	v_cvt_pk_bf16_f32 v146, v140, v141
	v_cvt_pk_bf16_f32 v147, v142, v143
	global_store_dwordx4 v2, v[144:147], s[18:19] sc1
	s_add_u32 s18, s18, 0x20000
	s_addc_u32 s19, s19, 0
	v_lshlrev_b32_e32 v148, 16, v36
	v_and_b32_e32 v149, 0xffff0000, v36
	v_lshlrev_b32_e32 v150, 16, v37
	v_and_b32_e32 v151, 0xffff0000, v37
	v_lshlrev_b32_e32 v152, 16, v38
	v_and_b32_e32 v153, 0xffff0000, v38
	v_lshlrev_b32_e32 v154, 16, v39
	v_and_b32_e32 v155, 0xffff0000, v39
	v_fma_f32 v136, v136, s21, v148
	v_fma_f32 v137, v137, s21, v149
	v_fma_f32 v138, v138, s21, v150
	v_fma_f32 v139, v139, s21, v151
	v_fma_f32 v140, v140, s21, v152
	v_fma_f32 v141, v141, s21, v153
	v_fma_f32 v142, v142, s21, v154
	v_fma_f32 v143, v143, s21, v155
	global_load_dwordx4 v[8:11], v2, s[16:17]
	s_add_u32 s16, s16, 0x20000
	s_addc_u32 s17, s17, 0
	global_load_dwordx4 v[12:15], v2, s[16:17]
	s_add_u32 s16, s16, 0x20000
	s_addc_u32 s17, s17, 0
	global_load_dwordx4 v[16:19], v2, s[16:17]
	s_add_u32 s16, s16, 0x20000
	s_addc_u32 s17, s17, 0
	global_load_dwordx4 v[20:23], v2, s[16:17]
	s_add_u32 s16, s16, 0x20000
	s_addc_u32 s17, s17, 0
	global_load_dwordx4 v[24:27], v2, s[16:17]
	s_add_u32 s16, s16, 0x20000
	s_addc_u32 s17, s17, 0
	global_load_dwordx4 v[28:31], v2, s[16:17]
	s_add_u32 s16, s16, 0x20000
	s_addc_u32 s17, s17, 0
	global_load_dwordx4 v[32:35], v2, s[16:17]
	s_add_u32 s16, s16, 0x20000
	s_addc_u32 s17, s17, 0
	global_load_dwordx4 v[36:39], v2, s[16:17]
	s_add_u32 s16, s16, 0x20000
	s_addc_u32 s17, s17, 0
	s_waitcnt vmcnt(32)
	v_cvt_pk_bf16_f32 v144, v136, v137
	v_cvt_pk_bf16_f32 v145, v138, v139
	v_cvt_pk_bf16_f32 v146, v140, v141
	v_cvt_pk_bf16_f32 v147, v142, v143
	global_store_dwordx4 v2, v[144:147], s[18:19] sc1
	s_add_u32 s18, s18, 0x20000
	s_addc_u32 s19, s19, 0
	v_lshlrev_b32_e32 v148, 16, v40
	v_and_b32_e32 v149, 0xffff0000, v40
	v_lshlrev_b32_e32 v150, 16, v41
	v_and_b32_e32 v151, 0xffff0000, v41
	v_lshlrev_b32_e32 v152, 16, v42
	v_and_b32_e32 v153, 0xffff0000, v42
	v_lshlrev_b32_e32 v154, 16, v43
	v_and_b32_e32 v155, 0xffff0000, v43
	v_fma_f32 v136, v136, s21, v148
	v_fma_f32 v137, v137, s21, v149
	v_fma_f32 v138, v138, s21, v150
	v_fma_f32 v139, v139, s21, v151
	v_fma_f32 v140, v140, s21, v152
	v_fma_f32 v141, v141, s21, v153
	v_fma_f32 v142, v142, s21, v154
	v_fma_f32 v143, v143, s21, v155
	v_cvt_pk_bf16_f32 v144, v136, v137
	v_cvt_pk_bf16_f32 v145, v138, v139
	v_cvt_pk_bf16_f32 v146, v140, v141
	v_cvt_pk_bf16_f32 v147, v142, v143
	global_store_dwordx4 v2, v[144:147], s[18:19] sc1
	s_add_u32 s18, s18, 0x20000
	s_addc_u32 s19, s19, 0
	v_lshlrev_b32_e32 v148, 16, v44
	v_and_b32_e32 v149, 0xffff0000, v44
	v_lshlrev_b32_e32 v150, 16, v45
	v_and_b32_e32 v151, 0xffff0000, v45
	v_lshlrev_b32_e32 v152, 16, v46
	v_and_b32_e32 v153, 0xffff0000, v46
	v_lshlrev_b32_e32 v154, 16, v47
	v_and_b32_e32 v155, 0xffff0000, v47
	v_fma_f32 v136, v136, s21, v148
	v_fma_f32 v137, v137, s21, v149
	v_fma_f32 v138, v138, s21, v150
	v_fma_f32 v139, v139, s21, v151
	v_fma_f32 v140, v140, s21, v152
	v_fma_f32 v141, v141, s21, v153
	v_fma_f32 v142, v142, s21, v154
	v_fma_f32 v143, v143, s21, v155
	v_cvt_pk_bf16_f32 v144, v136, v137
	v_cvt_pk_bf16_f32 v145, v138, v139
	v_cvt_pk_bf16_f32 v146, v140, v141
	v_cvt_pk_bf16_f32 v147, v142, v143
	global_store_dwordx4 v2, v[144:147], s[18:19] sc1
	s_add_u32 s18, s18, 0x20000
	s_addc_u32 s19, s19, 0
	v_lshlrev_b32_e32 v148, 16, v48
	v_and_b32_e32 v149, 0xffff0000, v48
	v_lshlrev_b32_e32 v150, 16, v49
	v_and_b32_e32 v151, 0xffff0000, v49
	v_lshlrev_b32_e32 v152, 16, v50
	v_and_b32_e32 v153, 0xffff0000, v50
	v_lshlrev_b32_e32 v154, 16, v51
	v_and_b32_e32 v155, 0xffff0000, v51
	v_fma_f32 v136, v136, s21, v148
	v_fma_f32 v137, v137, s21, v149
	v_fma_f32 v138, v138, s21, v150
	v_fma_f32 v139, v139, s21, v151
	v_fma_f32 v140, v140, s21, v152
	v_fma_f32 v141, v141, s21, v153
	v_fma_f32 v142, v142, s21, v154
	v_fma_f32 v143, v143, s21, v155
	v_cvt_pk_bf16_f32 v144, v136, v137
	v_cvt_pk_bf16_f32 v145, v138, v139
	v_cvt_pk_bf16_f32 v146, v140, v141
	v_cvt_pk_bf16_f32 v147, v142, v143
	global_store_dwordx4 v2, v[144:147], s[18:19] sc1
	s_add_u32 s18, s18, 0x20000
	s_addc_u32 s19, s19, 0
	v_lshlrev_b32_e32 v148, 16, v52
	v_and_b32_e32 v149, 0xffff0000, v52
	v_lshlrev_b32_e32 v150, 16, v53
	v_and_b32_e32 v151, 0xffff0000, v53
	v_lshlrev_b32_e32 v152, 16, v54
	v_and_b32_e32 v153, 0xffff0000, v54
	v_lshlrev_b32_e32 v154, 16, v55
	v_and_b32_e32 v155, 0xffff0000, v55
	v_fma_f32 v136, v136, s21, v148
	v_fma_f32 v137, v137, s21, v149
	v_fma_f32 v138, v138, s21, v150
	v_fma_f32 v139, v139, s21, v151
	v_fma_f32 v140, v140, s21, v152
	v_fma_f32 v141, v141, s21, v153
	v_fma_f32 v142, v142, s21, v154
	v_fma_f32 v143, v143, s21, v155
	v_cvt_pk_bf16_f32 v144, v136, v137
	v_cvt_pk_bf16_f32 v145, v138, v139
	v_cvt_pk_bf16_f32 v146, v140, v141
	v_cvt_pk_bf16_f32 v147, v142, v143
	global_store_dwordx4 v2, v[144:147], s[18:19] sc1
	s_add_u32 s18, s18, 0x20000
	s_addc_u32 s19, s19, 0
	v_lshlrev_b32_e32 v148, 16, v56
	v_and_b32_e32 v149, 0xffff0000, v56
	v_lshlrev_b32_e32 v150, 16, v57
	v_and_b32_e32 v151, 0xffff0000, v57
	v_lshlrev_b32_e32 v152, 16, v58
	v_and_b32_e32 v153, 0xffff0000, v58
	v_lshlrev_b32_e32 v154, 16, v59
	v_and_b32_e32 v155, 0xffff0000, v59
	v_fma_f32 v136, v136, s21, v148
	v_fma_f32 v137, v137, s21, v149
	v_fma_f32 v138, v138, s21, v150
	v_fma_f32 v139, v139, s21, v151
	v_fma_f32 v140, v140, s21, v152
	v_fma_f32 v141, v141, s21, v153
	v_fma_f32 v142, v142, s21, v154
	v_fma_f32 v143, v143, s21, v155
	v_cvt_pk_bf16_f32 v144, v136, v137
	v_cvt_pk_bf16_f32 v145, v138, v139
	v_cvt_pk_bf16_f32 v146, v140, v141
	v_cvt_pk_bf16_f32 v147, v142, v143
	global_store_dwordx4 v2, v[144:147], s[18:19] sc1
	s_add_u32 s18, s18, 0x20000
	s_addc_u32 s19, s19, 0
	v_lshlrev_b32_e32 v148, 16, v60
	v_and_b32_e32 v149, 0xffff0000, v60
	v_lshlrev_b32_e32 v150, 16, v61
	v_and_b32_e32 v151, 0xffff0000, v61
	v_lshlrev_b32_e32 v152, 16, v62
	v_and_b32_e32 v153, 0xffff0000, v62
	v_lshlrev_b32_e32 v154, 16, v63
	v_and_b32_e32 v155, 0xffff0000, v63
	v_fma_f32 v136, v136, s21, v148
	v_fma_f32 v137, v137, s21, v149
	v_fma_f32 v138, v138, s21, v150
	v_fma_f32 v139, v139, s21, v151
	v_fma_f32 v140, v140, s21, v152
	v_fma_f32 v141, v141, s21, v153
	v_fma_f32 v142, v142, s21, v154
	v_fma_f32 v143, v143, s21, v155
	v_cvt_pk_bf16_f32 v144, v136, v137
	v_cvt_pk_bf16_f32 v145, v138, v139
	v_cvt_pk_bf16_f32 v146, v140, v141
	v_cvt_pk_bf16_f32 v147, v142, v143
	global_store_dwordx4 v2, v[144:147], s[18:19] sc1
	s_add_u32 s18, s18, 0x20000
	s_addc_u32 s19, s19, 0
	v_lshlrev_b32_e32 v148, 16, v64
	v_and_b32_e32 v149, 0xffff0000, v64
	v_lshlrev_b32_e32 v150, 16, v65
	v_and_b32_e32 v151, 0xffff0000, v65
	v_lshlrev_b32_e32 v152, 16, v66
	v_and_b32_e32 v153, 0xffff0000, v66
	v_lshlrev_b32_e32 v154, 16, v67
	v_and_b32_e32 v155, 0xffff0000, v67
	v_fma_f32 v136, v136, s21, v148
	v_fma_f32 v137, v137, s21, v149
	v_fma_f32 v138, v138, s21, v150
	v_fma_f32 v139, v139, s21, v151
	v_fma_f32 v140, v140, s21, v152
	v_fma_f32 v141, v141, s21, v153
	v_fma_f32 v142, v142, s21, v154
	v_fma_f32 v143, v143, s21, v155
	v_cvt_pk_bf16_f32 v144, v136, v137
	v_cvt_pk_bf16_f32 v145, v138, v139
	v_cvt_pk_bf16_f32 v146, v140, v141
	v_cvt_pk_bf16_f32 v147, v142, v143
	global_store_dwordx4 v2, v[144:147], s[18:19] sc1
	s_add_u32 s18, s18, 0x20000
	s_addc_u32 s19, s19, 0
	v_lshlrev_b32_e32 v148, 16, v68
	v_and_b32_e32 v149, 0xffff0000, v68
	v_lshlrev_b32_e32 v150, 16, v69
	v_and_b32_e32 v151, 0xffff0000, v69
	v_lshlrev_b32_e32 v152, 16, v70
	v_and_b32_e32 v153, 0xffff0000, v70
	v_lshlrev_b32_e32 v154, 16, v71
	v_and_b32_e32 v155, 0xffff0000, v71
	v_fma_f32 v136, v136, s21, v148
	v_fma_f32 v137, v137, s21, v149
	v_fma_f32 v138, v138, s21, v150
	v_fma_f32 v139, v139, s21, v151
	v_fma_f32 v140, v140, s21, v152
	v_fma_f32 v141, v141, s21, v153
	v_fma_f32 v142, v142, s21, v154
	v_fma_f32 v143, v143, s21, v155
	global_load_dwordx4 v[40:43], v2, s[16:17]
	s_add_u32 s16, s16, 0x20000
	s_addc_u32 s17, s17, 0
	global_load_dwordx4 v[44:47], v2, s[16:17]
	s_add_u32 s16, s16, 0x20000
	s_addc_u32 s17, s17, 0
	global_load_dwordx4 v[48:51], v2, s[16:17]
	s_add_u32 s16, s16, 0x20000
	s_addc_u32 s17, s17, 0
	global_load_dwordx4 v[52:55], v2, s[16:17]
	s_add_u32 s16, s16, 0x20000
	s_addc_u32 s17, s17, 0
	global_load_dwordx4 v[56:59], v2, s[16:17]
	s_add_u32 s16, s16, 0x20000
	s_addc_u32 s17, s17, 0
	global_load_dwordx4 v[60:63], v2, s[16:17]
	s_add_u32 s16, s16, 0x20000
	s_addc_u32 s17, s17, 0
	global_load_dwordx4 v[64:67], v2, s[16:17]
	s_add_u32 s16, s16, 0x20000
	s_addc_u32 s17, s17, 0
	global_load_dwordx4 v[68:71], v2, s[16:17]
	s_add_u32 s16, s16, 0x20000
	s_addc_u32 s17, s17, 0
	s_waitcnt vmcnt(40)
	v_cvt_pk_bf16_f32 v144, v136, v137
	v_cvt_pk_bf16_f32 v145, v138, v139
	v_cvt_pk_bf16_f32 v146, v140, v141
	v_cvt_pk_bf16_f32 v147, v142, v143
	global_store_dwordx4 v2, v[144:147], s[18:19] sc1
	s_add_u32 s18, s18, 0x20000
	s_addc_u32 s19, s19, 0
	v_lshlrev_b32_e32 v148, 16, v72
	v_and_b32_e32 v149, 0xffff0000, v72
	v_lshlrev_b32_e32 v150, 16, v73
	v_and_b32_e32 v151, 0xffff0000, v73
	v_lshlrev_b32_e32 v152, 16, v74
	v_and_b32_e32 v153, 0xffff0000, v74
	v_lshlrev_b32_e32 v154, 16, v75
	v_and_b32_e32 v155, 0xffff0000, v75
	v_fma_f32 v136, v136, s21, v148
	v_fma_f32 v137, v137, s21, v149
	v_fma_f32 v138, v138, s21, v150
	v_fma_f32 v139, v139, s21, v151
	v_fma_f32 v140, v140, s21, v152
	v_fma_f32 v141, v141, s21, v153
	v_fma_f32 v142, v142, s21, v154
	v_fma_f32 v143, v143, s21, v155
	v_cvt_pk_bf16_f32 v144, v136, v137
	v_cvt_pk_bf16_f32 v145, v138, v139
	v_cvt_pk_bf16_f32 v146, v140, v141
	v_cvt_pk_bf16_f32 v147, v142, v143
	global_store_dwordx4 v2, v[144:147], s[18:19] sc1
	s_add_u32 s18, s18, 0x20000
	s_addc_u32 s19, s19, 0
	v_lshlrev_b32_e32 v148, 16, v76
	v_and_b32_e32 v149, 0xffff0000, v76
	v_lshlrev_b32_e32 v150, 16, v77
	v_and_b32_e32 v151, 0xffff0000, v77
	v_lshlrev_b32_e32 v152, 16, v78
	v_and_b32_e32 v153, 0xffff0000, v78
	v_lshlrev_b32_e32 v154, 16, v79
	v_and_b32_e32 v155, 0xffff0000, v79
	v_fma_f32 v136, v136, s21, v148
	v_fma_f32 v137, v137, s21, v149
	v_fma_f32 v138, v138, s21, v150
	v_fma_f32 v139, v139, s21, v151
	v_fma_f32 v140, v140, s21, v152
	v_fma_f32 v141, v141, s21, v153
	v_fma_f32 v142, v142, s21, v154
	v_fma_f32 v143, v143, s21, v155
	v_cvt_pk_bf16_f32 v144, v136, v137
	v_cvt_pk_bf16_f32 v145, v138, v139
	v_cvt_pk_bf16_f32 v146, v140, v141
	v_cvt_pk_bf16_f32 v147, v142, v143
	global_store_dwordx4 v2, v[144:147], s[18:19] sc1
	s_add_u32 s18, s18, 0x20000
	s_addc_u32 s19, s19, 0
	v_lshlrev_b32_e32 v148, 16, v80
	v_and_b32_e32 v149, 0xffff0000, v80
	v_lshlrev_b32_e32 v150, 16, v81
	v_and_b32_e32 v151, 0xffff0000, v81
	v_lshlrev_b32_e32 v152, 16, v82
	v_and_b32_e32 v153, 0xffff0000, v82
	v_lshlrev_b32_e32 v154, 16, v83
	v_and_b32_e32 v155, 0xffff0000, v83
	v_fma_f32 v136, v136, s21, v148
	v_fma_f32 v137, v137, s21, v149
	v_fma_f32 v138, v138, s21, v150
	v_fma_f32 v139, v139, s21, v151
	v_fma_f32 v140, v140, s21, v152
	v_fma_f32 v141, v141, s21, v153
	v_fma_f32 v142, v142, s21, v154
	v_fma_f32 v143, v143, s21, v155
	v_cvt_pk_bf16_f32 v144, v136, v137
	v_cvt_pk_bf16_f32 v145, v138, v139
	v_cvt_pk_bf16_f32 v146, v140, v141
	v_cvt_pk_bf16_f32 v147, v142, v143
	global_store_dwordx4 v2, v[144:147], s[18:19] sc1
	s_add_u32 s18, s18, 0x20000
	s_addc_u32 s19, s19, 0
	v_lshlrev_b32_e32 v148, 16, v84
	v_and_b32_e32 v149, 0xffff0000, v84
	v_lshlrev_b32_e32 v150, 16, v85
	v_and_b32_e32 v151, 0xffff0000, v85
	v_lshlrev_b32_e32 v152, 16, v86
	v_and_b32_e32 v153, 0xffff0000, v86
	v_lshlrev_b32_e32 v154, 16, v87
	v_and_b32_e32 v155, 0xffff0000, v87
	v_fma_f32 v136, v136, s21, v148
	v_fma_f32 v137, v137, s21, v149
	v_fma_f32 v138, v138, s21, v150
	v_fma_f32 v139, v139, s21, v151
	v_fma_f32 v140, v140, s21, v152
	v_fma_f32 v141, v141, s21, v153
	v_fma_f32 v142, v142, s21, v154
	v_fma_f32 v143, v143, s21, v155
	v_cvt_pk_bf16_f32 v144, v136, v137
	v_cvt_pk_bf16_f32 v145, v138, v139
	v_cvt_pk_bf16_f32 v146, v140, v141
	v_cvt_pk_bf16_f32 v147, v142, v143
	global_store_dwordx4 v2, v[144:147], s[18:19] sc1
	s_add_u32 s18, s18, 0x20000
	s_addc_u32 s19, s19, 0
	v_lshlrev_b32_e32 v148, 16, v88
	v_and_b32_e32 v149, 0xffff0000, v88
	v_lshlrev_b32_e32 v150, 16, v89
	v_and_b32_e32 v151, 0xffff0000, v89
	v_lshlrev_b32_e32 v152, 16, v90
	v_and_b32_e32 v153, 0xffff0000, v90
	v_lshlrev_b32_e32 v154, 16, v91
	v_and_b32_e32 v155, 0xffff0000, v91
	v_fma_f32 v136, v136, s21, v148
	v_fma_f32 v137, v137, s21, v149
	v_fma_f32 v138, v138, s21, v150
	v_fma_f32 v139, v139, s21, v151
	v_fma_f32 v140, v140, s21, v152
	v_fma_f32 v141, v141, s21, v153
	v_fma_f32 v142, v142, s21, v154
	v_fma_f32 v143, v143, s21, v155
	v_cvt_pk_bf16_f32 v144, v136, v137
	v_cvt_pk_bf16_f32 v145, v138, v139
	v_cvt_pk_bf16_f32 v146, v140, v141
	v_cvt_pk_bf16_f32 v147, v142, v143
	global_store_dwordx4 v2, v[144:147], s[18:19] sc1
	s_add_u32 s18, s18, 0x20000
	s_addc_u32 s19, s19, 0
	v_lshlrev_b32_e32 v148, 16, v92
	v_and_b32_e32 v149, 0xffff0000, v92
	v_lshlrev_b32_e32 v150, 16, v93
	v_and_b32_e32 v151, 0xffff0000, v93
	v_lshlrev_b32_e32 v152, 16, v94
	v_and_b32_e32 v153, 0xffff0000, v94
	v_lshlrev_b32_e32 v154, 16, v95
	v_and_b32_e32 v155, 0xffff0000, v95
	v_fma_f32 v136, v136, s21, v148
	v_fma_f32 v137, v137, s21, v149
	v_fma_f32 v138, v138, s21, v150
	v_fma_f32 v139, v139, s21, v151
	v_fma_f32 v140, v140, s21, v152
	v_fma_f32 v141, v141, s21, v153
	v_fma_f32 v142, v142, s21, v154
	v_fma_f32 v143, v143, s21, v155
	v_cvt_pk_bf16_f32 v144, v136, v137
	v_cvt_pk_bf16_f32 v145, v138, v139
	v_cvt_pk_bf16_f32 v146, v140, v141
	v_cvt_pk_bf16_f32 v147, v142, v143
	global_store_dwordx4 v2, v[144:147], s[18:19] sc1
	s_add_u32 s18, s18, 0x20000
	s_addc_u32 s19, s19, 0
	v_lshlrev_b32_e32 v148, 16, v96
	v_and_b32_e32 v149, 0xffff0000, v96
	v_lshlrev_b32_e32 v150, 16, v97
	v_and_b32_e32 v151, 0xffff0000, v97
	v_lshlrev_b32_e32 v152, 16, v98
	v_and_b32_e32 v153, 0xffff0000, v98
	v_lshlrev_b32_e32 v154, 16, v99
	v_and_b32_e32 v155, 0xffff0000, v99
	v_fma_f32 v136, v136, s21, v148
	v_fma_f32 v137, v137, s21, v149
	v_fma_f32 v138, v138, s21, v150
	v_fma_f32 v139, v139, s21, v151
	v_fma_f32 v140, v140, s21, v152
	v_fma_f32 v141, v141, s21, v153
	v_fma_f32 v142, v142, s21, v154
	v_fma_f32 v143, v143, s21, v155
	v_cvt_pk_bf16_f32 v144, v136, v137
	v_cvt_pk_bf16_f32 v145, v138, v139
	v_cvt_pk_bf16_f32 v146, v140, v141
	v_cvt_pk_bf16_f32 v147, v142, v143
	global_store_dwordx4 v2, v[144:147], s[18:19] sc1
	s_add_u32 s18, s18, 0x20000
	s_addc_u32 s19, s19, 0
	v_lshlrev_b32_e32 v148, 16, v100
	v_and_b32_e32 v149, 0xffff0000, v100
	v_lshlrev_b32_e32 v150, 16, v101
	v_and_b32_e32 v151, 0xffff0000, v101
	v_lshlrev_b32_e32 v152, 16, v102
	v_and_b32_e32 v153, 0xffff0000, v102
	v_lshlrev_b32_e32 v154, 16, v103
	v_and_b32_e32 v155, 0xffff0000, v103
	v_fma_f32 v136, v136, s21, v148
	v_fma_f32 v137, v137, s21, v149
	v_fma_f32 v138, v138, s21, v150
	v_fma_f32 v139, v139, s21, v151
	v_fma_f32 v140, v140, s21, v152
	v_fma_f32 v141, v141, s21, v153
	v_fma_f32 v142, v142, s21, v154
	v_fma_f32 v143, v143, s21, v155
	global_load_dwordx4 v[72:75], v2, s[16:17]
	s_add_u32 s16, s16, 0x20000
	s_addc_u32 s17, s17, 0
	global_load_dwordx4 v[76:79], v2, s[16:17]
	s_add_u32 s16, s16, 0x20000
	s_addc_u32 s17, s17, 0
	global_load_dwordx4 v[80:83], v2, s[16:17]
	s_add_u32 s16, s16, 0x20000
	s_addc_u32 s17, s17, 0
	global_load_dwordx4 v[84:87], v2, s[16:17]
	s_add_u32 s16, s16, 0x20000
	s_addc_u32 s17, s17, 0
	global_load_dwordx4 v[88:91], v2, s[16:17]
	s_add_u32 s16, s16, 0x20000
	s_addc_u32 s17, s17, 0
	global_load_dwordx4 v[92:95], v2, s[16:17]
	s_add_u32 s16, s16, 0x20000
	s_addc_u32 s17, s17, 0
	global_load_dwordx4 v[96:99], v2, s[16:17]
	s_add_u32 s16, s16, 0x20000
	s_addc_u32 s17, s17, 0
	global_load_dwordx4 v[100:103], v2, s[16:17]
	s_add_u32 s16, s16, 0x20000
	s_addc_u32 s17, s17, 0
	s_waitcnt vmcnt(48)
	v_cvt_pk_bf16_f32 v144, v136, v137
	v_cvt_pk_bf16_f32 v145, v138, v139
	v_cvt_pk_bf16_f32 v146, v140, v141
	v_cvt_pk_bf16_f32 v147, v142, v143
	global_store_dwordx4 v2, v[144:147], s[18:19] sc1
	s_add_u32 s18, s18, 0x20000
	s_addc_u32 s19, s19, 0
	v_lshlrev_b32_e32 v148, 16, v104
	v_and_b32_e32 v149, 0xffff0000, v104
	v_lshlrev_b32_e32 v150, 16, v105
	v_and_b32_e32 v151, 0xffff0000, v105
	v_lshlrev_b32_e32 v152, 16, v106
	v_and_b32_e32 v153, 0xffff0000, v106
	v_lshlrev_b32_e32 v154, 16, v107
	v_and_b32_e32 v155, 0xffff0000, v107
	v_fma_f32 v136, v136, s21, v148
	v_fma_f32 v137, v137, s21, v149
	v_fma_f32 v138, v138, s21, v150
	v_fma_f32 v139, v139, s21, v151
	v_fma_f32 v140, v140, s21, v152
	v_fma_f32 v141, v141, s21, v153
	v_fma_f32 v142, v142, s21, v154
	v_fma_f32 v143, v143, s21, v155
	v_cvt_pk_bf16_f32 v144, v136, v137
	v_cvt_pk_bf16_f32 v145, v138, v139
	v_cvt_pk_bf16_f32 v146, v140, v141
	v_cvt_pk_bf16_f32 v147, v142, v143
	global_store_dwordx4 v2, v[144:147], s[18:19] sc1
	s_add_u32 s18, s18, 0x20000
	s_addc_u32 s19, s19, 0
	v_lshlrev_b32_e32 v148, 16, v108
	v_and_b32_e32 v149, 0xffff0000, v108
	v_lshlrev_b32_e32 v150, 16, v109
	v_and_b32_e32 v151, 0xffff0000, v109
	v_lshlrev_b32_e32 v152, 16, v110
	v_and_b32_e32 v153, 0xffff0000, v110
	v_lshlrev_b32_e32 v154, 16, v111
	v_and_b32_e32 v155, 0xffff0000, v111
	v_fma_f32 v136, v136, s21, v148
	v_fma_f32 v137, v137, s21, v149
	v_fma_f32 v138, v138, s21, v150
	v_fma_f32 v139, v139, s21, v151
	v_fma_f32 v140, v140, s21, v152
	v_fma_f32 v141, v141, s21, v153
	v_fma_f32 v142, v142, s21, v154
	v_fma_f32 v143, v143, s21, v155
	v_cvt_pk_bf16_f32 v144, v136, v137
	v_cvt_pk_bf16_f32 v145, v138, v139
	v_cvt_pk_bf16_f32 v146, v140, v141
	v_cvt_pk_bf16_f32 v147, v142, v143
	global_store_dwordx4 v2, v[144:147], s[18:19] sc1
	s_add_u32 s18, s18, 0x20000
	s_addc_u32 s19, s19, 0
	v_lshlrev_b32_e32 v148, 16, v112
	v_and_b32_e32 v149, 0xffff0000, v112
	v_lshlrev_b32_e32 v150, 16, v113
	v_and_b32_e32 v151, 0xffff0000, v113
	v_lshlrev_b32_e32 v152, 16, v114
	v_and_b32_e32 v153, 0xffff0000, v114
	v_lshlrev_b32_e32 v154, 16, v115
	v_and_b32_e32 v155, 0xffff0000, v115
	v_fma_f32 v136, v136, s21, v148
	v_fma_f32 v137, v137, s21, v149
	v_fma_f32 v138, v138, s21, v150
	v_fma_f32 v139, v139, s21, v151
	v_fma_f32 v140, v140, s21, v152
	v_fma_f32 v141, v141, s21, v153
	v_fma_f32 v142, v142, s21, v154
	v_fma_f32 v143, v143, s21, v155
	v_cvt_pk_bf16_f32 v144, v136, v137
	v_cvt_pk_bf16_f32 v145, v138, v139
	v_cvt_pk_bf16_f32 v146, v140, v141
	v_cvt_pk_bf16_f32 v147, v142, v143
	global_store_dwordx4 v2, v[144:147], s[18:19] sc1
	s_add_u32 s18, s18, 0x20000
	s_addc_u32 s19, s19, 0
	v_lshlrev_b32_e32 v148, 16, v116
	v_and_b32_e32 v149, 0xffff0000, v116
	v_lshlrev_b32_e32 v150, 16, v117
	v_and_b32_e32 v151, 0xffff0000, v117
	v_lshlrev_b32_e32 v152, 16, v118
	v_and_b32_e32 v153, 0xffff0000, v118
	v_lshlrev_b32_e32 v154, 16, v119
	v_and_b32_e32 v155, 0xffff0000, v119
	v_fma_f32 v136, v136, s21, v148
	v_fma_f32 v137, v137, s21, v149
	v_fma_f32 v138, v138, s21, v150
	v_fma_f32 v139, v139, s21, v151
	v_fma_f32 v140, v140, s21, v152
	v_fma_f32 v141, v141, s21, v153
	v_fma_f32 v142, v142, s21, v154
	v_fma_f32 v143, v143, s21, v155
	v_cvt_pk_bf16_f32 v144, v136, v137
	v_cvt_pk_bf16_f32 v145, v138, v139
	v_cvt_pk_bf16_f32 v146, v140, v141
	v_cvt_pk_bf16_f32 v147, v142, v143
	global_store_dwordx4 v2, v[144:147], s[18:19] sc1
	s_add_u32 s18, s18, 0x20000
	s_addc_u32 s19, s19, 0
	v_lshlrev_b32_e32 v148, 16, v120
	v_and_b32_e32 v149, 0xffff0000, v120
	v_lshlrev_b32_e32 v150, 16, v121
	v_and_b32_e32 v151, 0xffff0000, v121
	v_lshlrev_b32_e32 v152, 16, v122
	v_and_b32_e32 v153, 0xffff0000, v122
	v_lshlrev_b32_e32 v154, 16, v123
	v_and_b32_e32 v155, 0xffff0000, v123
	v_fma_f32 v136, v136, s21, v148
	v_fma_f32 v137, v137, s21, v149
	v_fma_f32 v138, v138, s21, v150
	v_fma_f32 v139, v139, s21, v151
	v_fma_f32 v140, v140, s21, v152
	v_fma_f32 v141, v141, s21, v153
	v_fma_f32 v142, v142, s21, v154
	v_fma_f32 v143, v143, s21, v155
	v_cvt_pk_bf16_f32 v144, v136, v137
	v_cvt_pk_bf16_f32 v145, v138, v139
	v_cvt_pk_bf16_f32 v146, v140, v141
	v_cvt_pk_bf16_f32 v147, v142, v143
	global_store_dwordx4 v2, v[144:147], s[18:19] sc1
	s_add_u32 s18, s18, 0x20000
	s_addc_u32 s19, s19, 0
	v_lshlrev_b32_e32 v148, 16, v124
	v_and_b32_e32 v149, 0xffff0000, v124
	v_lshlrev_b32_e32 v150, 16, v125
	v_and_b32_e32 v151, 0xffff0000, v125
	v_lshlrev_b32_e32 v152, 16, v126
	v_and_b32_e32 v153, 0xffff0000, v126
	v_lshlrev_b32_e32 v154, 16, v127
	v_and_b32_e32 v155, 0xffff0000, v127
	v_fma_f32 v136, v136, s21, v148
	v_fma_f32 v137, v137, s21, v149
	v_fma_f32 v138, v138, s21, v150
	v_fma_f32 v139, v139, s21, v151
	v_fma_f32 v140, v140, s21, v152
	v_fma_f32 v141, v141, s21, v153
	v_fma_f32 v142, v142, s21, v154
	v_fma_f32 v143, v143, s21, v155
	v_cvt_pk_bf16_f32 v144, v136, v137
	v_cvt_pk_bf16_f32 v145, v138, v139
	v_cvt_pk_bf16_f32 v146, v140, v141
	v_cvt_pk_bf16_f32 v147, v142, v143
	global_store_dwordx4 v2, v[144:147], s[18:19] sc1
	s_add_u32 s18, s18, 0x20000
	s_addc_u32 s19, s19, 0
	v_lshlrev_b32_e32 v148, 16, v128
	v_and_b32_e32 v149, 0xffff0000, v128
	v_lshlrev_b32_e32 v150, 16, v129
	v_and_b32_e32 v151, 0xffff0000, v129
	v_lshlrev_b32_e32 v152, 16, v130
	v_and_b32_e32 v153, 0xffff0000, v130
	v_lshlrev_b32_e32 v154, 16, v131
	v_and_b32_e32 v155, 0xffff0000, v131
	v_fma_f32 v136, v136, s21, v148
	v_fma_f32 v137, v137, s21, v149
	v_fma_f32 v138, v138, s21, v150
	v_fma_f32 v139, v139, s21, v151
	v_fma_f32 v140, v140, s21, v152
	v_fma_f32 v141, v141, s21, v153
	v_fma_f32 v142, v142, s21, v154
	v_fma_f32 v143, v143, s21, v155
	v_cvt_pk_bf16_f32 v144, v136, v137
	v_cvt_pk_bf16_f32 v145, v138, v139
	v_cvt_pk_bf16_f32 v146, v140, v141
	v_cvt_pk_bf16_f32 v147, v142, v143
	global_store_dwordx4 v2, v[144:147], s[18:19] sc1
	s_add_u32 s18, s18, 0x20000
	s_addc_u32 s19, s19, 0
	v_lshlrev_b32_e32 v148, 16, v132
	v_and_b32_e32 v149, 0xffff0000, v132
	v_lshlrev_b32_e32 v150, 16, v133
	v_and_b32_e32 v151, 0xffff0000, v133
	v_lshlrev_b32_e32 v152, 16, v134
	v_and_b32_e32 v153, 0xffff0000, v134
	v_lshlrev_b32_e32 v154, 16, v135
	v_and_b32_e32 v155, 0xffff0000, v135
	v_fma_f32 v136, v136, s21, v148
	v_fma_f32 v137, v137, s21, v149
	v_fma_f32 v138, v138, s21, v150
	v_fma_f32 v139, v139, s21, v151
	v_fma_f32 v140, v140, s21, v152
	v_fma_f32 v141, v141, s21, v153
	v_fma_f32 v142, v142, s21, v154
	v_fma_f32 v143, v143, s21, v155
	global_load_dwordx4 v[104:107], v2, s[16:17]
	s_add_u32 s16, s16, 0x20000
	s_addc_u32 s17, s17, 0
	global_load_dwordx4 v[108:111], v2, s[16:17]
	s_add_u32 s16, s16, 0x20000
	s_addc_u32 s17, s17, 0
	global_load_dwordx4 v[112:115], v2, s[16:17]
	s_add_u32 s16, s16, 0x20000
	s_addc_u32 s17, s17, 0
	global_load_dwordx4 v[116:119], v2, s[16:17]
	s_add_u32 s16, s16, 0x20000
	s_addc_u32 s17, s17, 0
	global_load_dwordx4 v[120:123], v2, s[16:17]
	s_add_u32 s16, s16, 0x20000
	s_addc_u32 s17, s17, 0
	global_load_dwordx4 v[124:127], v2, s[16:17]
	s_add_u32 s16, s16, 0x20000
	s_addc_u32 s17, s17, 0
	global_load_dwordx4 v[128:131], v2, s[16:17]
	s_add_u32 s16, s16, 0x20000
	s_addc_u32 s17, s17, 0
	global_load_dwordx4 v[132:135], v2, s[16:17]
	s_add_u32 s16, s16, 0x20000
	s_addc_u32 s17, s17, 0
	s_mov_b32 s22, 6
.Lp3_ret_loop:
	s_waitcnt vmcnt(48)
	v_cvt_pk_bf16_f32 v144, v136, v137
	v_cvt_pk_bf16_f32 v145, v138, v139
	v_cvt_pk_bf16_f32 v146, v140, v141
	v_cvt_pk_bf16_f32 v147, v142, v143
	global_store_dwordx4 v2, v[144:147], s[18:19] sc1
	s_add_u32 s18, s18, 0x20000
	s_addc_u32 s19, s19, 0
	v_lshlrev_b32_e32 v148, 16, v8
	v_and_b32_e32 v149, 0xffff0000, v8
	v_lshlrev_b32_e32 v150, 16, v9
	v_and_b32_e32 v151, 0xffff0000, v9
	v_lshlrev_b32_e32 v152, 16, v10
	v_and_b32_e32 v153, 0xffff0000, v10
	v_lshlrev_b32_e32 v154, 16, v11
	v_and_b32_e32 v155, 0xffff0000, v11
	v_fma_f32 v136, v136, s21, v148
	v_fma_f32 v137, v137, s21, v149
	v_fma_f32 v138, v138, s21, v150
	v_fma_f32 v139, v139, s21, v151
	v_fma_f32 v140, v140, s21, v152
	v_fma_f32 v141, v141, s21, v153
	v_fma_f32 v142, v142, s21, v154
	v_fma_f32 v143, v143, s21, v155
	v_cvt_pk_bf16_f32 v144, v136, v137
	v_cvt_pk_bf16_f32 v145, v138, v139
	v_cvt_pk_bf16_f32 v146, v140, v141
	v_cvt_pk_bf16_f32 v147, v142, v143
	global_store_dwordx4 v2, v[144:147], s[18:19] sc1
	s_add_u32 s18, s18, 0x20000
	s_addc_u32 s19, s19, 0
	v_lshlrev_b32_e32 v148, 16, v12
	v_and_b32_e32 v149, 0xffff0000, v12
	v_lshlrev_b32_e32 v150, 16, v13
	v_and_b32_e32 v151, 0xffff0000, v13
	v_lshlrev_b32_e32 v152, 16, v14
	v_and_b32_e32 v153, 0xffff0000, v14
	v_lshlrev_b32_e32 v154, 16, v15
	v_and_b32_e32 v155, 0xffff0000, v15
	v_fma_f32 v136, v136, s21, v148
	v_fma_f32 v137, v137, s21, v149
	v_fma_f32 v138, v138, s21, v150
	v_fma_f32 v139, v139, s21, v151
	v_fma_f32 v140, v140, s21, v152
	v_fma_f32 v141, v141, s21, v153
	v_fma_f32 v142, v142, s21, v154
	v_fma_f32 v143, v143, s21, v155
	v_cvt_pk_bf16_f32 v144, v136, v137
	v_cvt_pk_bf16_f32 v145, v138, v139
	v_cvt_pk_bf16_f32 v146, v140, v141
	v_cvt_pk_bf16_f32 v147, v142, v143
	global_store_dwordx4 v2, v[144:147], s[18:19] sc1
	s_add_u32 s18, s18, 0x20000
	s_addc_u32 s19, s19, 0
	v_lshlrev_b32_e32 v148, 16, v16
	v_and_b32_e32 v149, 0xffff0000, v16
	v_lshlrev_b32_e32 v150, 16, v17
	v_and_b32_e32 v151, 0xffff0000, v17
	v_lshlrev_b32_e32 v152, 16, v18
	v_and_b32_e32 v153, 0xffff0000, v18
	v_lshlrev_b32_e32 v154, 16, v19
	v_and_b32_e32 v155, 0xffff0000, v19
	v_fma_f32 v136, v136, s21, v148
	v_fma_f32 v137, v137, s21, v149
	v_fma_f32 v138, v138, s21, v150
	v_fma_f32 v139, v139, s21, v151
	v_fma_f32 v140, v140, s21, v152
	v_fma_f32 v141, v141, s21, v153
	v_fma_f32 v142, v142, s21, v154
	v_fma_f32 v143, v143, s21, v155
	v_cvt_pk_bf16_f32 v144, v136, v137
	v_cvt_pk_bf16_f32 v145, v138, v139
	v_cvt_pk_bf16_f32 v146, v140, v141
	v_cvt_pk_bf16_f32 v147, v142, v143
	global_store_dwordx4 v2, v[144:147], s[18:19] sc1
	s_add_u32 s18, s18, 0x20000
	s_addc_u32 s19, s19, 0
	v_lshlrev_b32_e32 v148, 16, v20
	v_and_b32_e32 v149, 0xffff0000, v20
	v_lshlrev_b32_e32 v150, 16, v21
	v_and_b32_e32 v151, 0xffff0000, v21
	v_lshlrev_b32_e32 v152, 16, v22
	v_and_b32_e32 v153, 0xffff0000, v22
	v_lshlrev_b32_e32 v154, 16, v23
	v_and_b32_e32 v155, 0xffff0000, v23
	v_fma_f32 v136, v136, s21, v148
	v_fma_f32 v137, v137, s21, v149
	v_fma_f32 v138, v138, s21, v150
	v_fma_f32 v139, v139, s21, v151
	v_fma_f32 v140, v140, s21, v152
	v_fma_f32 v141, v141, s21, v153
	v_fma_f32 v142, v142, s21, v154
	v_fma_f32 v143, v143, s21, v155
	v_cvt_pk_bf16_f32 v144, v136, v137
	v_cvt_pk_bf16_f32 v145, v138, v139
	v_cvt_pk_bf16_f32 v146, v140, v141
	v_cvt_pk_bf16_f32 v147, v142, v143
	global_store_dwordx4 v2, v[144:147], s[18:19] sc1
	s_add_u32 s18, s18, 0x20000
	s_addc_u32 s19, s19, 0
	v_lshlrev_b32_e32 v148, 16, v24
	v_and_b32_e32 v149, 0xffff0000, v24
	v_lshlrev_b32_e32 v150, 16, v25
	v_and_b32_e32 v151, 0xffff0000, v25
	v_lshlrev_b32_e32 v152, 16, v26
	v_and_b32_e32 v153, 0xffff0000, v26
	v_lshlrev_b32_e32 v154, 16, v27
	v_and_b32_e32 v155, 0xffff0000, v27
	v_fma_f32 v136, v136, s21, v148
	v_fma_f32 v137, v137, s21, v149
	v_fma_f32 v138, v138, s21, v150
	v_fma_f32 v139, v139, s21, v151
	v_fma_f32 v140, v140, s21, v152
	v_fma_f32 v141, v141, s21, v153
	v_fma_f32 v142, v142, s21, v154
	v_fma_f32 v143, v143, s21, v155
	v_cvt_pk_bf16_f32 v144, v136, v137
	v_cvt_pk_bf16_f32 v145, v138, v139
	v_cvt_pk_bf16_f32 v146, v140, v141
	v_cvt_pk_bf16_f32 v147, v142, v143
	global_store_dwordx4 v2, v[144:147], s[18:19] sc1
	s_add_u32 s18, s18, 0x20000
	s_addc_u32 s19, s19, 0
	v_lshlrev_b32_e32 v148, 16, v28
	v_and_b32_e32 v149, 0xffff0000, v28
	v_lshlrev_b32_e32 v150, 16, v29
	v_and_b32_e32 v151, 0xffff0000, v29
	v_lshlrev_b32_e32 v152, 16, v30
	v_and_b32_e32 v153, 0xffff0000, v30
	v_lshlrev_b32_e32 v154, 16, v31
	v_and_b32_e32 v155, 0xffff0000, v31
	v_fma_f32 v136, v136, s21, v148
	v_fma_f32 v137, v137, s21, v149
	v_fma_f32 v138, v138, s21, v150
	v_fma_f32 v139, v139, s21, v151
	v_fma_f32 v140, v140, s21, v152
	v_fma_f32 v141, v141, s21, v153
	v_fma_f32 v142, v142, s21, v154
	v_fma_f32 v143, v143, s21, v155
	v_cvt_pk_bf16_f32 v144, v136, v137
	v_cvt_pk_bf16_f32 v145, v138, v139
	v_cvt_pk_bf16_f32 v146, v140, v141
	v_cvt_pk_bf16_f32 v147, v142, v143
	global_store_dwordx4 v2, v[144:147], s[18:19] sc1
	s_add_u32 s18, s18, 0x20000
	s_addc_u32 s19, s19, 0
	v_lshlrev_b32_e32 v148, 16, v32
	v_and_b32_e32 v149, 0xffff0000, v32
	v_lshlrev_b32_e32 v150, 16, v33
	v_and_b32_e32 v151, 0xffff0000, v33
	v_lshlrev_b32_e32 v152, 16, v34
	v_and_b32_e32 v153, 0xffff0000, v34
	v_lshlrev_b32_e32 v154, 16, v35
	v_and_b32_e32 v155, 0xffff0000, v35
	v_fma_f32 v136, v136, s21, v148
	v_fma_f32 v137, v137, s21, v149
	v_fma_f32 v138, v138, s21, v150
	v_fma_f32 v139, v139, s21, v151
	v_fma_f32 v140, v140, s21, v152
	v_fma_f32 v141, v141, s21, v153
	v_fma_f32 v142, v142, s21, v154
	v_fma_f32 v143, v143, s21, v155
	v_cvt_pk_bf16_f32 v144, v136, v137
	v_cvt_pk_bf16_f32 v145, v138, v139
	v_cvt_pk_bf16_f32 v146, v140, v141
	v_cvt_pk_bf16_f32 v147, v142, v143
	global_store_dwordx4 v2, v[144:147], s[18:19] sc1
	s_add_u32 s18, s18, 0x20000
	s_addc_u32 s19, s19, 0
	v_lshlrev_b32_e32 v148, 16, v36
	v_and_b32_e32 v149, 0xffff0000, v36
	v_lshlrev_b32_e32 v150, 16, v37
	v_and_b32_e32 v151, 0xffff0000, v37
	v_lshlrev_b32_e32 v152, 16, v38
	v_and_b32_e32 v153, 0xffff0000, v38
	v_lshlrev_b32_e32 v154, 16, v39
	v_and_b32_e32 v155, 0xffff0000, v39
	v_fma_f32 v136, v136, s21, v148
	v_fma_f32 v137, v137, s21, v149
	v_fma_f32 v138, v138, s21, v150
	v_fma_f32 v139, v139, s21, v151
	v_fma_f32 v140, v140, s21, v152
	v_fma_f32 v141, v141, s21, v153
	v_fma_f32 v142, v142, s21, v154
	v_fma_f32 v143, v143, s21, v155
	global_load_dwordx4 v[8:11], v2, s[16:17]
	s_add_u32 s16, s16, 0x20000
	s_addc_u32 s17, s17, 0
	global_load_dwordx4 v[12:15], v2, s[16:17]
	s_add_u32 s16, s16, 0x20000
	s_addc_u32 s17, s17, 0
	global_load_dwordx4 v[16:19], v2, s[16:17]
	s_add_u32 s16, s16, 0x20000
	s_addc_u32 s17, s17, 0
	global_load_dwordx4 v[20:23], v2, s[16:17]
	s_add_u32 s16, s16, 0x20000
	s_addc_u32 s17, s17, 0
	global_load_dwordx4 v[24:27], v2, s[16:17]
	s_add_u32 s16, s16, 0x20000
	s_addc_u32 s17, s17, 0
	global_load_dwordx4 v[28:31], v2, s[16:17]
	s_add_u32 s16, s16, 0x20000
	s_addc_u32 s17, s17, 0
	global_load_dwordx4 v[32:35], v2, s[16:17]
	s_add_u32 s16, s16, 0x20000
	s_addc_u32 s17, s17, 0
	global_load_dwordx4 v[36:39], v2, s[16:17]
	s_add_u32 s16, s16, 0x20000
	s_addc_u32 s17, s17, 0
	s_waitcnt vmcnt(48)
	v_cvt_pk_bf16_f32 v144, v136, v137
	v_cvt_pk_bf16_f32 v145, v138, v139
	v_cvt_pk_bf16_f32 v146, v140, v141
	v_cvt_pk_bf16_f32 v147, v142, v143
	global_store_dwordx4 v2, v[144:147], s[18:19] sc1
	s_add_u32 s18, s18, 0x20000
	s_addc_u32 s19, s19, 0
	v_lshlrev_b32_e32 v148, 16, v40
	v_and_b32_e32 v149, 0xffff0000, v40
	v_lshlrev_b32_e32 v150, 16, v41
	v_and_b32_e32 v151, 0xffff0000, v41
	v_lshlrev_b32_e32 v152, 16, v42
	v_and_b32_e32 v153, 0xffff0000, v42
	v_lshlrev_b32_e32 v154, 16, v43
	v_and_b32_e32 v155, 0xffff0000, v43
	v_fma_f32 v136, v136, s21, v148
	v_fma_f32 v137, v137, s21, v149
	v_fma_f32 v138, v138, s21, v150
	v_fma_f32 v139, v139, s21, v151
	v_fma_f32 v140, v140, s21, v152
	v_fma_f32 v141, v141, s21, v153
	v_fma_f32 v142, v142, s21, v154
	v_fma_f32 v143, v143, s21, v155
	v_cvt_pk_bf16_f32 v144, v136, v137
	v_cvt_pk_bf16_f32 v145, v138, v139
	v_cvt_pk_bf16_f32 v146, v140, v141
	v_cvt_pk_bf16_f32 v147, v142, v143
	global_store_dwordx4 v2, v[144:147], s[18:19] sc1
	s_add_u32 s18, s18, 0x20000
	s_addc_u32 s19, s19, 0
	v_lshlrev_b32_e32 v148, 16, v44
	v_and_b32_e32 v149, 0xffff0000, v44
	v_lshlrev_b32_e32 v150, 16, v45
	v_and_b32_e32 v151, 0xffff0000, v45
	v_lshlrev_b32_e32 v152, 16, v46
	v_and_b32_e32 v153, 0xffff0000, v46
	v_lshlrev_b32_e32 v154, 16, v47
	v_and_b32_e32 v155, 0xffff0000, v47
	v_fma_f32 v136, v136, s21, v148
	v_fma_f32 v137, v137, s21, v149
	v_fma_f32 v138, v138, s21, v150
	v_fma_f32 v139, v139, s21, v151
	v_fma_f32 v140, v140, s21, v152
	v_fma_f32 v141, v141, s21, v153
	v_fma_f32 v142, v142, s21, v154
	v_fma_f32 v143, v143, s21, v155
	v_cvt_pk_bf16_f32 v144, v136, v137
	v_cvt_pk_bf16_f32 v145, v138, v139
	v_cvt_pk_bf16_f32 v146, v140, v141
	v_cvt_pk_bf16_f32 v147, v142, v143
	global_store_dwordx4 v2, v[144:147], s[18:19] sc1
	s_add_u32 s18, s18, 0x20000
	s_addc_u32 s19, s19, 0
	v_lshlrev_b32_e32 v148, 16, v48
	v_and_b32_e32 v149, 0xffff0000, v48
	v_lshlrev_b32_e32 v150, 16, v49
	v_and_b32_e32 v151, 0xffff0000, v49
	v_lshlrev_b32_e32 v152, 16, v50
	v_and_b32_e32 v153, 0xffff0000, v50
	v_lshlrev_b32_e32 v154, 16, v51
	v_and_b32_e32 v155, 0xffff0000, v51
	v_fma_f32 v136, v136, s21, v148
	v_fma_f32 v137, v137, s21, v149
	v_fma_f32 v138, v138, s21, v150
	v_fma_f32 v139, v139, s21, v151
	v_fma_f32 v140, v140, s21, v152
	v_fma_f32 v141, v141, s21, v153
	v_fma_f32 v142, v142, s21, v154
	v_fma_f32 v143, v143, s21, v155
	v_cvt_pk_bf16_f32 v144, v136, v137
	v_cvt_pk_bf16_f32 v145, v138, v139
	v_cvt_pk_bf16_f32 v146, v140, v141
	v_cvt_pk_bf16_f32 v147, v142, v143
	global_store_dwordx4 v2, v[144:147], s[18:19] sc1
	s_add_u32 s18, s18, 0x20000
	s_addc_u32 s19, s19, 0
	v_lshlrev_b32_e32 v148, 16, v52
	v_and_b32_e32 v149, 0xffff0000, v52
	v_lshlrev_b32_e32 v150, 16, v53
	v_and_b32_e32 v151, 0xffff0000, v53
	v_lshlrev_b32_e32 v152, 16, v54
	v_and_b32_e32 v153, 0xffff0000, v54
	v_lshlrev_b32_e32 v154, 16, v55
	v_and_b32_e32 v155, 0xffff0000, v55
	v_fma_f32 v136, v136, s21, v148
	v_fma_f32 v137, v137, s21, v149
	v_fma_f32 v138, v138, s21, v150
	v_fma_f32 v139, v139, s21, v151
	v_fma_f32 v140, v140, s21, v152
	v_fma_f32 v141, v141, s21, v153
	v_fma_f32 v142, v142, s21, v154
	v_fma_f32 v143, v143, s21, v155
	v_cvt_pk_bf16_f32 v144, v136, v137
	v_cvt_pk_bf16_f32 v145, v138, v139
	v_cvt_pk_bf16_f32 v146, v140, v141
	v_cvt_pk_bf16_f32 v147, v142, v143
	global_store_dwordx4 v2, v[144:147], s[18:19] sc1
	s_add_u32 s18, s18, 0x20000
	s_addc_u32 s19, s19, 0
	v_lshlrev_b32_e32 v148, 16, v56
	v_and_b32_e32 v149, 0xffff0000, v56
	v_lshlrev_b32_e32 v150, 16, v57
	v_and_b32_e32 v151, 0xffff0000, v57
	v_lshlrev_b32_e32 v152, 16, v58
	v_and_b32_e32 v153, 0xffff0000, v58
	v_lshlrev_b32_e32 v154, 16, v59
	v_and_b32_e32 v155, 0xffff0000, v59
	v_fma_f32 v136, v136, s21, v148
	v_fma_f32 v137, v137, s21, v149
	v_fma_f32 v138, v138, s21, v150
	v_fma_f32 v139, v139, s21, v151
	v_fma_f32 v140, v140, s21, v152
	v_fma_f32 v141, v141, s21, v153
	v_fma_f32 v142, v142, s21, v154
	v_fma_f32 v143, v143, s21, v155
	v_cvt_pk_bf16_f32 v144, v136, v137
	v_cvt_pk_bf16_f32 v145, v138, v139
	v_cvt_pk_bf16_f32 v146, v140, v141
	v_cvt_pk_bf16_f32 v147, v142, v143
	global_store_dwordx4 v2, v[144:147], s[18:19] sc1
	s_add_u32 s18, s18, 0x20000
	s_addc_u32 s19, s19, 0
	v_lshlrev_b32_e32 v148, 16, v60
	v_and_b32_e32 v149, 0xffff0000, v60
	v_lshlrev_b32_e32 v150, 16, v61
	v_and_b32_e32 v151, 0xffff0000, v61
	v_lshlrev_b32_e32 v152, 16, v62
	v_and_b32_e32 v153, 0xffff0000, v62
	v_lshlrev_b32_e32 v154, 16, v63
	v_and_b32_e32 v155, 0xffff0000, v63
	v_fma_f32 v136, v136, s21, v148
	v_fma_f32 v137, v137, s21, v149
	v_fma_f32 v138, v138, s21, v150
	v_fma_f32 v139, v139, s21, v151
	v_fma_f32 v140, v140, s21, v152
	v_fma_f32 v141, v141, s21, v153
	v_fma_f32 v142, v142, s21, v154
	v_fma_f32 v143, v143, s21, v155
	v_cvt_pk_bf16_f32 v144, v136, v137
	v_cvt_pk_bf16_f32 v145, v138, v139
	v_cvt_pk_bf16_f32 v146, v140, v141
	v_cvt_pk_bf16_f32 v147, v142, v143
	global_store_dwordx4 v2, v[144:147], s[18:19] sc1
	s_add_u32 s18, s18, 0x20000
	s_addc_u32 s19, s19, 0
	v_lshlrev_b32_e32 v148, 16, v64
	v_and_b32_e32 v149, 0xffff0000, v64
	v_lshlrev_b32_e32 v150, 16, v65
	v_and_b32_e32 v151, 0xffff0000, v65
	v_lshlrev_b32_e32 v152, 16, v66
	v_and_b32_e32 v153, 0xffff0000, v66
	v_lshlrev_b32_e32 v154, 16, v67
	v_and_b32_e32 v155, 0xffff0000, v67
	v_fma_f32 v136, v136, s21, v148
	v_fma_f32 v137, v137, s21, v149
	v_fma_f32 v138, v138, s21, v150
	v_fma_f32 v139, v139, s21, v151
	v_fma_f32 v140, v140, s21, v152
	v_fma_f32 v141, v141, s21, v153
	v_fma_f32 v142, v142, s21, v154
	v_fma_f32 v143, v143, s21, v155
	v_cvt_pk_bf16_f32 v144, v136, v137
	v_cvt_pk_bf16_f32 v145, v138, v139
	v_cvt_pk_bf16_f32 v146, v140, v141
	v_cvt_pk_bf16_f32 v147, v142, v143
	global_store_dwordx4 v2, v[144:147], s[18:19] sc1
	s_add_u32 s18, s18, 0x20000
	s_addc_u32 s19, s19, 0
	v_lshlrev_b32_e32 v148, 16, v68
	v_and_b32_e32 v149, 0xffff0000, v68
	v_lshlrev_b32_e32 v150, 16, v69
	v_and_b32_e32 v151, 0xffff0000, v69
	v_lshlrev_b32_e32 v152, 16, v70
	v_and_b32_e32 v153, 0xffff0000, v70
	v_lshlrev_b32_e32 v154, 16, v71
	v_and_b32_e32 v155, 0xffff0000, v71
	v_fma_f32 v136, v136, s21, v148
	v_fma_f32 v137, v137, s21, v149
	v_fma_f32 v138, v138, s21, v150
	v_fma_f32 v139, v139, s21, v151
	v_fma_f32 v140, v140, s21, v152
	v_fma_f32 v141, v141, s21, v153
	v_fma_f32 v142, v142, s21, v154
	v_fma_f32 v143, v143, s21, v155
	global_load_dwordx4 v[40:43], v2, s[16:17]
	s_add_u32 s16, s16, 0x20000
	s_addc_u32 s17, s17, 0
	global_load_dwordx4 v[44:47], v2, s[16:17]
	s_add_u32 s16, s16, 0x20000
	s_addc_u32 s17, s17, 0
	global_load_dwordx4 v[48:51], v2, s[16:17]
	s_add_u32 s16, s16, 0x20000
	s_addc_u32 s17, s17, 0
	global_load_dwordx4 v[52:55], v2, s[16:17]
	s_add_u32 s16, s16, 0x20000
	s_addc_u32 s17, s17, 0
	global_load_dwordx4 v[56:59], v2, s[16:17]
	s_add_u32 s16, s16, 0x20000
	s_addc_u32 s17, s17, 0
	global_load_dwordx4 v[60:63], v2, s[16:17]
	s_add_u32 s16, s16, 0x20000
	s_addc_u32 s17, s17, 0
	global_load_dwordx4 v[64:67], v2, s[16:17]
	s_add_u32 s16, s16, 0x20000
	s_addc_u32 s17, s17, 0
	global_load_dwordx4 v[68:71], v2, s[16:17]
	s_add_u32 s16, s16, 0x20000
	s_addc_u32 s17, s17, 0
	s_waitcnt vmcnt(48)
	v_cvt_pk_bf16_f32 v144, v136, v137
	v_cvt_pk_bf16_f32 v145, v138, v139
	v_cvt_pk_bf16_f32 v146, v140, v141
	v_cvt_pk_bf16_f32 v147, v142, v143
	global_store_dwordx4 v2, v[144:147], s[18:19] sc1
	s_add_u32 s18, s18, 0x20000
	s_addc_u32 s19, s19, 0
	v_lshlrev_b32_e32 v148, 16, v72
	v_and_b32_e32 v149, 0xffff0000, v72
	v_lshlrev_b32_e32 v150, 16, v73
	v_and_b32_e32 v151, 0xffff0000, v73
	v_lshlrev_b32_e32 v152, 16, v74
	v_and_b32_e32 v153, 0xffff0000, v74
	v_lshlrev_b32_e32 v154, 16, v75
	v_and_b32_e32 v155, 0xffff0000, v75
	v_fma_f32 v136, v136, s21, v148
	v_fma_f32 v137, v137, s21, v149
	v_fma_f32 v138, v138, s21, v150
	v_fma_f32 v139, v139, s21, v151
	v_fma_f32 v140, v140, s21, v152
	v_fma_f32 v141, v141, s21, v153
	v_fma_f32 v142, v142, s21, v154
	v_fma_f32 v143, v143, s21, v155
	v_cvt_pk_bf16_f32 v144, v136, v137
	v_cvt_pk_bf16_f32 v145, v138, v139
	v_cvt_pk_bf16_f32 v146, v140, v141
	v_cvt_pk_bf16_f32 v147, v142, v143
	global_store_dwordx4 v2, v[144:147], s[18:19] sc1
	s_add_u32 s18, s18, 0x20000
	s_addc_u32 s19, s19, 0
	v_lshlrev_b32_e32 v148, 16, v76
	v_and_b32_e32 v149, 0xffff0000, v76
	v_lshlrev_b32_e32 v150, 16, v77
	v_and_b32_e32 v151, 0xffff0000, v77
	v_lshlrev_b32_e32 v152, 16, v78
	v_and_b32_e32 v153, 0xffff0000, v78
	v_lshlrev_b32_e32 v154, 16, v79
	v_and_b32_e32 v155, 0xffff0000, v79
	v_fma_f32 v136, v136, s21, v148
	v_fma_f32 v137, v137, s21, v149
	v_fma_f32 v138, v138, s21, v150
	v_fma_f32 v139, v139, s21, v151
	v_fma_f32 v140, v140, s21, v152
	v_fma_f32 v141, v141, s21, v153
	v_fma_f32 v142, v142, s21, v154
	v_fma_f32 v143, v143, s21, v155
	v_cvt_pk_bf16_f32 v144, v136, v137
	v_cvt_pk_bf16_f32 v145, v138, v139
	v_cvt_pk_bf16_f32 v146, v140, v141
	v_cvt_pk_bf16_f32 v147, v142, v143
	global_store_dwordx4 v2, v[144:147], s[18:19] sc1
	s_add_u32 s18, s18, 0x20000
	s_addc_u32 s19, s19, 0
	v_lshlrev_b32_e32 v148, 16, v80
	v_and_b32_e32 v149, 0xffff0000, v80
	v_lshlrev_b32_e32 v150, 16, v81
	v_and_b32_e32 v151, 0xffff0000, v81
	v_lshlrev_b32_e32 v152, 16, v82
	v_and_b32_e32 v153, 0xffff0000, v82
	v_lshlrev_b32_e32 v154, 16, v83
	v_and_b32_e32 v155, 0xffff0000, v83
	v_fma_f32 v136, v136, s21, v148
	v_fma_f32 v137, v137, s21, v149
	v_fma_f32 v138, v138, s21, v150
	v_fma_f32 v139, v139, s21, v151
	v_fma_f32 v140, v140, s21, v152
	v_fma_f32 v141, v141, s21, v153
	v_fma_f32 v142, v142, s21, v154
	v_fma_f32 v143, v143, s21, v155
	v_cvt_pk_bf16_f32 v144, v136, v137
	v_cvt_pk_bf16_f32 v145, v138, v139
	v_cvt_pk_bf16_f32 v146, v140, v141
	v_cvt_pk_bf16_f32 v147, v142, v143
	global_store_dwordx4 v2, v[144:147], s[18:19] sc1
	s_add_u32 s18, s18, 0x20000
	s_addc_u32 s19, s19, 0
	v_lshlrev_b32_e32 v148, 16, v84
	v_and_b32_e32 v149, 0xffff0000, v84
	v_lshlrev_b32_e32 v150, 16, v85
	v_and_b32_e32 v151, 0xffff0000, v85
	v_lshlrev_b32_e32 v152, 16, v86
	v_and_b32_e32 v153, 0xffff0000, v86
	v_lshlrev_b32_e32 v154, 16, v87
	v_and_b32_e32 v155, 0xffff0000, v87
	v_fma_f32 v136, v136, s21, v148
	v_fma_f32 v137, v137, s21, v149
	v_fma_f32 v138, v138, s21, v150
	v_fma_f32 v139, v139, s21, v151
	v_fma_f32 v140, v140, s21, v152
	v_fma_f32 v141, v141, s21, v153
	v_fma_f32 v142, v142, s21, v154
	v_fma_f32 v143, v143, s21, v155
	v_cvt_pk_bf16_f32 v144, v136, v137
	v_cvt_pk_bf16_f32 v145, v138, v139
	v_cvt_pk_bf16_f32 v146, v140, v141
	v_cvt_pk_bf16_f32 v147, v142, v143
	global_store_dwordx4 v2, v[144:147], s[18:19] sc1
	s_add_u32 s18, s18, 0x20000
	s_addc_u32 s19, s19, 0
	v_lshlrev_b32_e32 v148, 16, v88
	v_and_b32_e32 v149, 0xffff0000, v88
	v_lshlrev_b32_e32 v150, 16, v89
	v_and_b32_e32 v151, 0xffff0000, v89
	v_lshlrev_b32_e32 v152, 16, v90
	v_and_b32_e32 v153, 0xffff0000, v90
	v_lshlrev_b32_e32 v154, 16, v91
	v_and_b32_e32 v155, 0xffff0000, v91
	v_fma_f32 v136, v136, s21, v148
	v_fma_f32 v137, v137, s21, v149
	v_fma_f32 v138, v138, s21, v150
	v_fma_f32 v139, v139, s21, v151
	v_fma_f32 v140, v140, s21, v152
	v_fma_f32 v141, v141, s21, v153
	v_fma_f32 v142, v142, s21, v154
	v_fma_f32 v143, v143, s21, v155
	v_cvt_pk_bf16_f32 v144, v136, v137
	v_cvt_pk_bf16_f32 v145, v138, v139
	v_cvt_pk_bf16_f32 v146, v140, v141
	v_cvt_pk_bf16_f32 v147, v142, v143
	global_store_dwordx4 v2, v[144:147], s[18:19] sc1
	s_add_u32 s18, s18, 0x20000
	s_addc_u32 s19, s19, 0
	v_lshlrev_b32_e32 v148, 16, v92
	v_and_b32_e32 v149, 0xffff0000, v92
	v_lshlrev_b32_e32 v150, 16, v93
	v_and_b32_e32 v151, 0xffff0000, v93
	v_lshlrev_b32_e32 v152, 16, v94
	v_and_b32_e32 v153, 0xffff0000, v94
	v_lshlrev_b32_e32 v154, 16, v95
	v_and_b32_e32 v155, 0xffff0000, v95
	v_fma_f32 v136, v136, s21, v148
	v_fma_f32 v137, v137, s21, v149
	v_fma_f32 v138, v138, s21, v150
	v_fma_f32 v139, v139, s21, v151
	v_fma_f32 v140, v140, s21, v152
	v_fma_f32 v141, v141, s21, v153
	v_fma_f32 v142, v142, s21, v154
	v_fma_f32 v143, v143, s21, v155
	v_cvt_pk_bf16_f32 v144, v136, v137
	v_cvt_pk_bf16_f32 v145, v138, v139
	v_cvt_pk_bf16_f32 v146, v140, v141
	v_cvt_pk_bf16_f32 v147, v142, v143
	global_store_dwordx4 v2, v[144:147], s[18:19] sc1
	s_add_u32 s18, s18, 0x20000
	s_addc_u32 s19, s19, 0
	v_lshlrev_b32_e32 v148, 16, v96
	v_and_b32_e32 v149, 0xffff0000, v96
	v_lshlrev_b32_e32 v150, 16, v97
	v_and_b32_e32 v151, 0xffff0000, v97
	v_lshlrev_b32_e32 v152, 16, v98
	v_and_b32_e32 v153, 0xffff0000, v98
	v_lshlrev_b32_e32 v154, 16, v99
	v_and_b32_e32 v155, 0xffff0000, v99
	v_fma_f32 v136, v136, s21, v148
	v_fma_f32 v137, v137, s21, v149
	v_fma_f32 v138, v138, s21, v150
	v_fma_f32 v139, v139, s21, v151
	v_fma_f32 v140, v140, s21, v152
	v_fma_f32 v141, v141, s21, v153
	v_fma_f32 v142, v142, s21, v154
	v_fma_f32 v143, v143, s21, v155
	v_cvt_pk_bf16_f32 v144, v136, v137
	v_cvt_pk_bf16_f32 v145, v138, v139
	v_cvt_pk_bf16_f32 v146, v140, v141
	v_cvt_pk_bf16_f32 v147, v142, v143
	global_store_dwordx4 v2, v[144:147], s[18:19] sc1
	s_add_u32 s18, s18, 0x20000
	s_addc_u32 s19, s19, 0
	v_lshlrev_b32_e32 v148, 16, v100
	v_and_b32_e32 v149, 0xffff0000, v100
	v_lshlrev_b32_e32 v150, 16, v101
	v_and_b32_e32 v151, 0xffff0000, v101
	v_lshlrev_b32_e32 v152, 16, v102
	v_and_b32_e32 v153, 0xffff0000, v102
	v_lshlrev_b32_e32 v154, 16, v103
	v_and_b32_e32 v155, 0xffff0000, v103
	v_fma_f32 v136, v136, s21, v148
	v_fma_f32 v137, v137, s21, v149
	v_fma_f32 v138, v138, s21, v150
	v_fma_f32 v139, v139, s21, v151
	v_fma_f32 v140, v140, s21, v152
	v_fma_f32 v141, v141, s21, v153
	v_fma_f32 v142, v142, s21, v154
	v_fma_f32 v143, v143, s21, v155
	global_load_dwordx4 v[72:75], v2, s[16:17]
	s_add_u32 s16, s16, 0x20000
	s_addc_u32 s17, s17, 0
	global_load_dwordx4 v[76:79], v2, s[16:17]
	s_add_u32 s16, s16, 0x20000
	s_addc_u32 s17, s17, 0
	global_load_dwordx4 v[80:83], v2, s[16:17]
	s_add_u32 s16, s16, 0x20000
	s_addc_u32 s17, s17, 0
	global_load_dwordx4 v[84:87], v2, s[16:17]
	s_add_u32 s16, s16, 0x20000
	s_addc_u32 s17, s17, 0
	global_load_dwordx4 v[88:91], v2, s[16:17]
	s_add_u32 s16, s16, 0x20000
	s_addc_u32 s17, s17, 0
	global_load_dwordx4 v[92:95], v2, s[16:17]
	s_add_u32 s16, s16, 0x20000
	s_addc_u32 s17, s17, 0
	global_load_dwordx4 v[96:99], v2, s[16:17]
	s_add_u32 s16, s16, 0x20000
	s_addc_u32 s17, s17, 0
	global_load_dwordx4 v[100:103], v2, s[16:17]
	s_add_u32 s16, s16, 0x20000
	s_addc_u32 s17, s17, 0
	s_waitcnt vmcnt(48)
	v_cvt_pk_bf16_f32 v144, v136, v137
	v_cvt_pk_bf16_f32 v145, v138, v139
	v_cvt_pk_bf16_f32 v146, v140, v141
	v_cvt_pk_bf16_f32 v147, v142, v143
	global_store_dwordx4 v2, v[144:147], s[18:19] sc1
	s_add_u32 s18, s18, 0x20000
	s_addc_u32 s19, s19, 0
	v_lshlrev_b32_e32 v148, 16, v104
	v_and_b32_e32 v149, 0xffff0000, v104
	v_lshlrev_b32_e32 v150, 16, v105
	v_and_b32_e32 v151, 0xffff0000, v105
	v_lshlrev_b32_e32 v152, 16, v106
	v_and_b32_e32 v153, 0xffff0000, v106
	v_lshlrev_b32_e32 v154, 16, v107
	v_and_b32_e32 v155, 0xffff0000, v107
	v_fma_f32 v136, v136, s21, v148
	v_fma_f32 v137, v137, s21, v149
	v_fma_f32 v138, v138, s21, v150
	v_fma_f32 v139, v139, s21, v151
	v_fma_f32 v140, v140, s21, v152
	v_fma_f32 v141, v141, s21, v153
	v_fma_f32 v142, v142, s21, v154
	v_fma_f32 v143, v143, s21, v155
	v_cvt_pk_bf16_f32 v144, v136, v137
	v_cvt_pk_bf16_f32 v145, v138, v139
	v_cvt_pk_bf16_f32 v146, v140, v141
	v_cvt_pk_bf16_f32 v147, v142, v143
	global_store_dwordx4 v2, v[144:147], s[18:19] sc1
	s_add_u32 s18, s18, 0x20000
	s_addc_u32 s19, s19, 0
	v_lshlrev_b32_e32 v148, 16, v108
	v_and_b32_e32 v149, 0xffff0000, v108
	v_lshlrev_b32_e32 v150, 16, v109
	v_and_b32_e32 v151, 0xffff0000, v109
	v_lshlrev_b32_e32 v152, 16, v110
	v_and_b32_e32 v153, 0xffff0000, v110
	v_lshlrev_b32_e32 v154, 16, v111
	v_and_b32_e32 v155, 0xffff0000, v111
	v_fma_f32 v136, v136, s21, v148
	v_fma_f32 v137, v137, s21, v149
	v_fma_f32 v138, v138, s21, v150
	v_fma_f32 v139, v139, s21, v151
	v_fma_f32 v140, v140, s21, v152
	v_fma_f32 v141, v141, s21, v153
	v_fma_f32 v142, v142, s21, v154
	v_fma_f32 v143, v143, s21, v155
	v_cvt_pk_bf16_f32 v144, v136, v137
	v_cvt_pk_bf16_f32 v145, v138, v139
	v_cvt_pk_bf16_f32 v146, v140, v141
	v_cvt_pk_bf16_f32 v147, v142, v143
	global_store_dwordx4 v2, v[144:147], s[18:19] sc1
	s_add_u32 s18, s18, 0x20000
	s_addc_u32 s19, s19, 0
	v_lshlrev_b32_e32 v148, 16, v112
	v_and_b32_e32 v149, 0xffff0000, v112
	v_lshlrev_b32_e32 v150, 16, v113
	v_and_b32_e32 v151, 0xffff0000, v113
	v_lshlrev_b32_e32 v152, 16, v114
	v_and_b32_e32 v153, 0xffff0000, v114
	v_lshlrev_b32_e32 v154, 16, v115
	v_and_b32_e32 v155, 0xffff0000, v115
	v_fma_f32 v136, v136, s21, v148
	v_fma_f32 v137, v137, s21, v149
	v_fma_f32 v138, v138, s21, v150
	v_fma_f32 v139, v139, s21, v151
	v_fma_f32 v140, v140, s21, v152
	v_fma_f32 v141, v141, s21, v153
	v_fma_f32 v142, v142, s21, v154
	v_fma_f32 v143, v143, s21, v155
	v_cvt_pk_bf16_f32 v144, v136, v137
	v_cvt_pk_bf16_f32 v145, v138, v139
	v_cvt_pk_bf16_f32 v146, v140, v141
	v_cvt_pk_bf16_f32 v147, v142, v143
	global_store_dwordx4 v2, v[144:147], s[18:19] sc1
	s_add_u32 s18, s18, 0x20000
	s_addc_u32 s19, s19, 0
	v_lshlrev_b32_e32 v148, 16, v116
	v_and_b32_e32 v149, 0xffff0000, v116
	v_lshlrev_b32_e32 v150, 16, v117
	v_and_b32_e32 v151, 0xffff0000, v117
	v_lshlrev_b32_e32 v152, 16, v118
	v_and_b32_e32 v153, 0xffff0000, v118
	v_lshlrev_b32_e32 v154, 16, v119
	v_and_b32_e32 v155, 0xffff0000, v119
	v_fma_f32 v136, v136, s21, v148
	v_fma_f32 v137, v137, s21, v149
	v_fma_f32 v138, v138, s21, v150
	v_fma_f32 v139, v139, s21, v151
	v_fma_f32 v140, v140, s21, v152
	v_fma_f32 v141, v141, s21, v153
	v_fma_f32 v142, v142, s21, v154
	v_fma_f32 v143, v143, s21, v155
	v_cvt_pk_bf16_f32 v144, v136, v137
	v_cvt_pk_bf16_f32 v145, v138, v139
	v_cvt_pk_bf16_f32 v146, v140, v141
	v_cvt_pk_bf16_f32 v147, v142, v143
	global_store_dwordx4 v2, v[144:147], s[18:19] sc1
	s_add_u32 s18, s18, 0x20000
	s_addc_u32 s19, s19, 0
	v_lshlrev_b32_e32 v148, 16, v120
	v_and_b32_e32 v149, 0xffff0000, v120
	v_lshlrev_b32_e32 v150, 16, v121
	v_and_b32_e32 v151, 0xffff0000, v121
	v_lshlrev_b32_e32 v152, 16, v122
	v_and_b32_e32 v153, 0xffff0000, v122
	v_lshlrev_b32_e32 v154, 16, v123
	v_and_b32_e32 v155, 0xffff0000, v123
	v_fma_f32 v136, v136, s21, v148
	v_fma_f32 v137, v137, s21, v149
	v_fma_f32 v138, v138, s21, v150
	v_fma_f32 v139, v139, s21, v151
	v_fma_f32 v140, v140, s21, v152
	v_fma_f32 v141, v141, s21, v153
	v_fma_f32 v142, v142, s21, v154
	v_fma_f32 v143, v143, s21, v155
	v_cvt_pk_bf16_f32 v144, v136, v137
	v_cvt_pk_bf16_f32 v145, v138, v139
	v_cvt_pk_bf16_f32 v146, v140, v141
	v_cvt_pk_bf16_f32 v147, v142, v143
	global_store_dwordx4 v2, v[144:147], s[18:19] sc1
	s_add_u32 s18, s18, 0x20000
	s_addc_u32 s19, s19, 0
	v_lshlrev_b32_e32 v148, 16, v124
	v_and_b32_e32 v149, 0xffff0000, v124
	v_lshlrev_b32_e32 v150, 16, v125
	v_and_b32_e32 v151, 0xffff0000, v125
	v_lshlrev_b32_e32 v152, 16, v126
	v_and_b32_e32 v153, 0xffff0000, v126
	v_lshlrev_b32_e32 v154, 16, v127
	v_and_b32_e32 v155, 0xffff0000, v127
	v_fma_f32 v136, v136, s21, v148
	v_fma_f32 v137, v137, s21, v149
	v_fma_f32 v138, v138, s21, v150
	v_fma_f32 v139, v139, s21, v151
	v_fma_f32 v140, v140, s21, v152
	v_fma_f32 v141, v141, s21, v153
	v_fma_f32 v142, v142, s21, v154
	v_fma_f32 v143, v143, s21, v155
	v_cvt_pk_bf16_f32 v144, v136, v137
	v_cvt_pk_bf16_f32 v145, v138, v139
	v_cvt_pk_bf16_f32 v146, v140, v141
	v_cvt_pk_bf16_f32 v147, v142, v143
	global_store_dwordx4 v2, v[144:147], s[18:19] sc1
	s_add_u32 s18, s18, 0x20000
	s_addc_u32 s19, s19, 0
	v_lshlrev_b32_e32 v148, 16, v128
	v_and_b32_e32 v149, 0xffff0000, v128
	v_lshlrev_b32_e32 v150, 16, v129
	v_and_b32_e32 v151, 0xffff0000, v129
	v_lshlrev_b32_e32 v152, 16, v130
	v_and_b32_e32 v153, 0xffff0000, v130
	v_lshlrev_b32_e32 v154, 16, v131
	v_and_b32_e32 v155, 0xffff0000, v131
	v_fma_f32 v136, v136, s21, v148
	v_fma_f32 v137, v137, s21, v149
	v_fma_f32 v138, v138, s21, v150
	v_fma_f32 v139, v139, s21, v151
	v_fma_f32 v140, v140, s21, v152
	v_fma_f32 v141, v141, s21, v153
	v_fma_f32 v142, v142, s21, v154
	v_fma_f32 v143, v143, s21, v155
	v_cvt_pk_bf16_f32 v144, v136, v137
	v_cvt_pk_bf16_f32 v145, v138, v139
	v_cvt_pk_bf16_f32 v146, v140, v141
	v_cvt_pk_bf16_f32 v147, v142, v143
	global_store_dwordx4 v2, v[144:147], s[18:19] sc1
	s_add_u32 s18, s18, 0x20000
	s_addc_u32 s19, s19, 0
	v_lshlrev_b32_e32 v148, 16, v132
	v_and_b32_e32 v149, 0xffff0000, v132
	v_lshlrev_b32_e32 v150, 16, v133
	v_and_b32_e32 v151, 0xffff0000, v133
	v_lshlrev_b32_e32 v152, 16, v134
	v_and_b32_e32 v153, 0xffff0000, v134
	v_lshlrev_b32_e32 v154, 16, v135
	v_and_b32_e32 v155, 0xffff0000, v135
	v_fma_f32 v136, v136, s21, v148
	v_fma_f32 v137, v137, s21, v149
	v_fma_f32 v138, v138, s21, v150
	v_fma_f32 v139, v139, s21, v151
	v_fma_f32 v140, v140, s21, v152
	v_fma_f32 v141, v141, s21, v153
	v_fma_f32 v142, v142, s21, v154
	v_fma_f32 v143, v143, s21, v155
	global_load_dwordx4 v[104:107], v2, s[16:17]
	s_add_u32 s16, s16, 0x20000
	s_addc_u32 s17, s17, 0
	global_load_dwordx4 v[108:111], v2, s[16:17]
	s_add_u32 s16, s16, 0x20000
	s_addc_u32 s17, s17, 0
	global_load_dwordx4 v[112:115], v2, s[16:17]
	s_add_u32 s16, s16, 0x20000
	s_addc_u32 s17, s17, 0
	global_load_dwordx4 v[116:119], v2, s[16:17]
	s_add_u32 s16, s16, 0x20000
	s_addc_u32 s17, s17, 0
	global_load_dwordx4 v[120:123], v2, s[16:17]
	s_add_u32 s16, s16, 0x20000
	s_addc_u32 s17, s17, 0
	global_load_dwordx4 v[124:127], v2, s[16:17]
	s_add_u32 s16, s16, 0x20000
	s_addc_u32 s17, s17, 0
	global_load_dwordx4 v[128:131], v2, s[16:17]
	s_add_u32 s16, s16, 0x20000
	s_addc_u32 s17, s17, 0
	global_load_dwordx4 v[132:135], v2, s[16:17]
	s_add_u32 s16, s16, 0x20000
	s_addc_u32 s17, s17, 0
	s_sub_u32 s22, s22, 1
	s_cmp_lg_u32 s22, 0
	s_cbranch_scc1 .Lp3_ret_loop
	s_waitcnt vmcnt(48)
	v_cvt_pk_bf16_f32 v144, v136, v137
	v_cvt_pk_bf16_f32 v145, v138, v139
	v_cvt_pk_bf16_f32 v146, v140, v141
	v_cvt_pk_bf16_f32 v147, v142, v143
	global_store_dwordx4 v2, v[144:147], s[18:19] sc1
	s_add_u32 s18, s18, 0x20000
	s_addc_u32 s19, s19, 0
	v_lshlrev_b32_e32 v148, 16, v8
	v_and_b32_e32 v149, 0xffff0000, v8
	v_lshlrev_b32_e32 v150, 16, v9
	v_and_b32_e32 v151, 0xffff0000, v9
	v_lshlrev_b32_e32 v152, 16, v10
	v_and_b32_e32 v153, 0xffff0000, v10
	v_lshlrev_b32_e32 v154, 16, v11
	v_and_b32_e32 v155, 0xffff0000, v11
	v_fma_f32 v136, v136, s21, v148
	v_fma_f32 v137, v137, s21, v149
	v_fma_f32 v138, v138, s21, v150
	v_fma_f32 v139, v139, s21, v151
	v_fma_f32 v140, v140, s21, v152
	v_fma_f32 v141, v141, s21, v153
	v_fma_f32 v142, v142, s21, v154
	v_fma_f32 v143, v143, s21, v155
	v_cvt_pk_bf16_f32 v144, v136, v137
	v_cvt_pk_bf16_f32 v145, v138, v139
	v_cvt_pk_bf16_f32 v146, v140, v141
	v_cvt_pk_bf16_f32 v147, v142, v143
	global_store_dwordx4 v2, v[144:147], s[18:19] sc1
	s_add_u32 s18, s18, 0x20000
	s_addc_u32 s19, s19, 0
	v_lshlrev_b32_e32 v148, 16, v12
	v_and_b32_e32 v149, 0xffff0000, v12
	v_lshlrev_b32_e32 v150, 16, v13
	v_and_b32_e32 v151, 0xffff0000, v13
	v_lshlrev_b32_e32 v152, 16, v14
	v_and_b32_e32 v153, 0xffff0000, v14
	v_lshlrev_b32_e32 v154, 16, v15
	v_and_b32_e32 v155, 0xffff0000, v15
	v_fma_f32 v136, v136, s21, v148
	v_fma_f32 v137, v137, s21, v149
	v_fma_f32 v138, v138, s21, v150
	v_fma_f32 v139, v139, s21, v151
	v_fma_f32 v140, v140, s21, v152
	v_fma_f32 v141, v141, s21, v153
	v_fma_f32 v142, v142, s21, v154
	v_fma_f32 v143, v143, s21, v155
	v_cvt_pk_bf16_f32 v144, v136, v137
	v_cvt_pk_bf16_f32 v145, v138, v139
	v_cvt_pk_bf16_f32 v146, v140, v141
	v_cvt_pk_bf16_f32 v147, v142, v143
	global_store_dwordx4 v2, v[144:147], s[18:19] sc1
	s_add_u32 s18, s18, 0x20000
	s_addc_u32 s19, s19, 0
	v_lshlrev_b32_e32 v148, 16, v16
	v_and_b32_e32 v149, 0xffff0000, v16
	v_lshlrev_b32_e32 v150, 16, v17
	v_and_b32_e32 v151, 0xffff0000, v17
	v_lshlrev_b32_e32 v152, 16, v18
	v_and_b32_e32 v153, 0xffff0000, v18
	v_lshlrev_b32_e32 v154, 16, v19
	v_and_b32_e32 v155, 0xffff0000, v19
	v_fma_f32 v136, v136, s21, v148
	v_fma_f32 v137, v137, s21, v149
	v_fma_f32 v138, v138, s21, v150
	v_fma_f32 v139, v139, s21, v151
	v_fma_f32 v140, v140, s21, v152
	v_fma_f32 v141, v141, s21, v153
	v_fma_f32 v142, v142, s21, v154
	v_fma_f32 v143, v143, s21, v155
	v_cvt_pk_bf16_f32 v144, v136, v137
	v_cvt_pk_bf16_f32 v145, v138, v139
	v_cvt_pk_bf16_f32 v146, v140, v141
	v_cvt_pk_bf16_f32 v147, v142, v143
	global_store_dwordx4 v2, v[144:147], s[18:19] sc1
	s_add_u32 s18, s18, 0x20000
	s_addc_u32 s19, s19, 0
	v_lshlrev_b32_e32 v148, 16, v20
	v_and_b32_e32 v149, 0xffff0000, v20
	v_lshlrev_b32_e32 v150, 16, v21
	v_and_b32_e32 v151, 0xffff0000, v21
	v_lshlrev_b32_e32 v152, 16, v22
	v_and_b32_e32 v153, 0xffff0000, v22
	v_lshlrev_b32_e32 v154, 16, v23
	v_and_b32_e32 v155, 0xffff0000, v23
	v_fma_f32 v136, v136, s21, v148
	v_fma_f32 v137, v137, s21, v149
	v_fma_f32 v138, v138, s21, v150
	v_fma_f32 v139, v139, s21, v151
	v_fma_f32 v140, v140, s21, v152
	v_fma_f32 v141, v141, s21, v153
	v_fma_f32 v142, v142, s21, v154
	v_fma_f32 v143, v143, s21, v155
	v_cvt_pk_bf16_f32 v144, v136, v137
	v_cvt_pk_bf16_f32 v145, v138, v139
	v_cvt_pk_bf16_f32 v146, v140, v141
	v_cvt_pk_bf16_f32 v147, v142, v143
	global_store_dwordx4 v2, v[144:147], s[18:19] sc1
	s_add_u32 s18, s18, 0x20000
	s_addc_u32 s19, s19, 0
	v_lshlrev_b32_e32 v148, 16, v24
	v_and_b32_e32 v149, 0xffff0000, v24
	v_lshlrev_b32_e32 v150, 16, v25
	v_and_b32_e32 v151, 0xffff0000, v25
	v_lshlrev_b32_e32 v152, 16, v26
	v_and_b32_e32 v153, 0xffff0000, v26
	v_lshlrev_b32_e32 v154, 16, v27
	v_and_b32_e32 v155, 0xffff0000, v27
	v_fma_f32 v136, v136, s21, v148
	v_fma_f32 v137, v137, s21, v149
	v_fma_f32 v138, v138, s21, v150
	v_fma_f32 v139, v139, s21, v151
	v_fma_f32 v140, v140, s21, v152
	v_fma_f32 v141, v141, s21, v153
	v_fma_f32 v142, v142, s21, v154
	v_fma_f32 v143, v143, s21, v155
	v_cvt_pk_bf16_f32 v144, v136, v137
	v_cvt_pk_bf16_f32 v145, v138, v139
	v_cvt_pk_bf16_f32 v146, v140, v141
	v_cvt_pk_bf16_f32 v147, v142, v143
	global_store_dwordx4 v2, v[144:147], s[18:19] sc1
	s_add_u32 s18, s18, 0x20000
	s_addc_u32 s19, s19, 0
	v_lshlrev_b32_e32 v148, 16, v28
	v_and_b32_e32 v149, 0xffff0000, v28
	v_lshlrev_b32_e32 v150, 16, v29
	v_and_b32_e32 v151, 0xffff0000, v29
	v_lshlrev_b32_e32 v152, 16, v30
	v_and_b32_e32 v153, 0xffff0000, v30
	v_lshlrev_b32_e32 v154, 16, v31
	v_and_b32_e32 v155, 0xffff0000, v31
	v_fma_f32 v136, v136, s21, v148
	v_fma_f32 v137, v137, s21, v149
	v_fma_f32 v138, v138, s21, v150
	v_fma_f32 v139, v139, s21, v151
	v_fma_f32 v140, v140, s21, v152
	v_fma_f32 v141, v141, s21, v153
	v_fma_f32 v142, v142, s21, v154
	v_fma_f32 v143, v143, s21, v155
	v_cvt_pk_bf16_f32 v144, v136, v137
	v_cvt_pk_bf16_f32 v145, v138, v139
	v_cvt_pk_bf16_f32 v146, v140, v141
	v_cvt_pk_bf16_f32 v147, v142, v143
	global_store_dwordx4 v2, v[144:147], s[18:19] sc1
	s_add_u32 s18, s18, 0x20000
	s_addc_u32 s19, s19, 0
	v_lshlrev_b32_e32 v148, 16, v32
	v_and_b32_e32 v149, 0xffff0000, v32
	v_lshlrev_b32_e32 v150, 16, v33
	v_and_b32_e32 v151, 0xffff0000, v33
	v_lshlrev_b32_e32 v152, 16, v34
	v_and_b32_e32 v153, 0xffff0000, v34
	v_lshlrev_b32_e32 v154, 16, v35
	v_and_b32_e32 v155, 0xffff0000, v35
	v_fma_f32 v136, v136, s21, v148
	v_fma_f32 v137, v137, s21, v149
	v_fma_f32 v138, v138, s21, v150
	v_fma_f32 v139, v139, s21, v151
	v_fma_f32 v140, v140, s21, v152
	v_fma_f32 v141, v141, s21, v153
	v_fma_f32 v142, v142, s21, v154
	v_fma_f32 v143, v143, s21, v155
	v_cvt_pk_bf16_f32 v144, v136, v137
	v_cvt_pk_bf16_f32 v145, v138, v139
	v_cvt_pk_bf16_f32 v146, v140, v141
	v_cvt_pk_bf16_f32 v147, v142, v143
	global_store_dwordx4 v2, v[144:147], s[18:19] sc1
	s_add_u32 s18, s18, 0x20000
	s_addc_u32 s19, s19, 0
	v_lshlrev_b32_e32 v148, 16, v36
	v_and_b32_e32 v149, 0xffff0000, v36
	v_lshlrev_b32_e32 v150, 16, v37
	v_and_b32_e32 v151, 0xffff0000, v37
	v_lshlrev_b32_e32 v152, 16, v38
	v_and_b32_e32 v153, 0xffff0000, v38
	v_lshlrev_b32_e32 v154, 16, v39
	v_and_b32_e32 v155, 0xffff0000, v39
	v_fma_f32 v136, v136, s21, v148
	v_fma_f32 v137, v137, s21, v149
	v_fma_f32 v138, v138, s21, v150
	v_fma_f32 v139, v139, s21, v151
	v_fma_f32 v140, v140, s21, v152
	v_fma_f32 v141, v141, s21, v153
	v_fma_f32 v142, v142, s21, v154
	v_fma_f32 v143, v143, s21, v155
	s_waitcnt vmcnt(40)
	v_cvt_pk_bf16_f32 v144, v136, v137
	v_cvt_pk_bf16_f32 v145, v138, v139
	v_cvt_pk_bf16_f32 v146, v140, v141
	v_cvt_pk_bf16_f32 v147, v142, v143
	global_store_dwordx4 v2, v[144:147], s[18:19] sc1
	s_add_u32 s18, s18, 0x20000
	s_addc_u32 s19, s19, 0
	v_lshlrev_b32_e32 v148, 16, v40
	v_and_b32_e32 v149, 0xffff0000, v40
	v_lshlrev_b32_e32 v150, 16, v41
	v_and_b32_e32 v151, 0xffff0000, v41
	v_lshlrev_b32_e32 v152, 16, v42
	v_and_b32_e32 v153, 0xffff0000, v42
	v_lshlrev_b32_e32 v154, 16, v43
	v_and_b32_e32 v155, 0xffff0000, v43
	v_fma_f32 v136, v136, s21, v148
	v_fma_f32 v137, v137, s21, v149
	v_fma_f32 v138, v138, s21, v150
	v_fma_f32 v139, v139, s21, v151
	v_fma_f32 v140, v140, s21, v152
	v_fma_f32 v141, v141, s21, v153
	v_fma_f32 v142, v142, s21, v154
	v_fma_f32 v143, v143, s21, v155
	v_cvt_pk_bf16_f32 v144, v136, v137
	v_cvt_pk_bf16_f32 v145, v138, v139
	v_cvt_pk_bf16_f32 v146, v140, v141
	v_cvt_pk_bf16_f32 v147, v142, v143
	global_store_dwordx4 v2, v[144:147], s[18:19] sc1
	s_add_u32 s18, s18, 0x20000
	s_addc_u32 s19, s19, 0
	v_lshlrev_b32_e32 v148, 16, v44
	v_and_b32_e32 v149, 0xffff0000, v44
	v_lshlrev_b32_e32 v150, 16, v45
	v_and_b32_e32 v151, 0xffff0000, v45
	v_lshlrev_b32_e32 v152, 16, v46
	v_and_b32_e32 v153, 0xffff0000, v46
	v_lshlrev_b32_e32 v154, 16, v47
	v_and_b32_e32 v155, 0xffff0000, v47
	v_fma_f32 v136, v136, s21, v148
	v_fma_f32 v137, v137, s21, v149
	v_fma_f32 v138, v138, s21, v150
	v_fma_f32 v139, v139, s21, v151
	v_fma_f32 v140, v140, s21, v152
	v_fma_f32 v141, v141, s21, v153
	v_fma_f32 v142, v142, s21, v154
	v_fma_f32 v143, v143, s21, v155
	v_cvt_pk_bf16_f32 v144, v136, v137
	v_cvt_pk_bf16_f32 v145, v138, v139
	v_cvt_pk_bf16_f32 v146, v140, v141
	v_cvt_pk_bf16_f32 v147, v142, v143
	global_store_dwordx4 v2, v[144:147], s[18:19] sc1
	s_add_u32 s18, s18, 0x20000
	s_addc_u32 s19, s19, 0
	v_lshlrev_b32_e32 v148, 16, v48
	v_and_b32_e32 v149, 0xffff0000, v48
	v_lshlrev_b32_e32 v150, 16, v49
	v_and_b32_e32 v151, 0xffff0000, v49
	v_lshlrev_b32_e32 v152, 16, v50
	v_and_b32_e32 v153, 0xffff0000, v50
	v_lshlrev_b32_e32 v154, 16, v51
	v_and_b32_e32 v155, 0xffff0000, v51
	v_fma_f32 v136, v136, s21, v148
	v_fma_f32 v137, v137, s21, v149
	v_fma_f32 v138, v138, s21, v150
	v_fma_f32 v139, v139, s21, v151
	v_fma_f32 v140, v140, s21, v152
	v_fma_f32 v141, v141, s21, v153
	v_fma_f32 v142, v142, s21, v154
	v_fma_f32 v143, v143, s21, v155
	v_cvt_pk_bf16_f32 v144, v136, v137
	v_cvt_pk_bf16_f32 v145, v138, v139
	v_cvt_pk_bf16_f32 v146, v140, v141
	v_cvt_pk_bf16_f32 v147, v142, v143
	global_store_dwordx4 v2, v[144:147], s[18:19] sc1
	s_add_u32 s18, s18, 0x20000
	s_addc_u32 s19, s19, 0
	v_lshlrev_b32_e32 v148, 16, v52
	v_and_b32_e32 v149, 0xffff0000, v52
	v_lshlrev_b32_e32 v150, 16, v53
	v_and_b32_e32 v151, 0xffff0000, v53
	v_lshlrev_b32_e32 v152, 16, v54
	v_and_b32_e32 v153, 0xffff0000, v54
	v_lshlrev_b32_e32 v154, 16, v55
	v_and_b32_e32 v155, 0xffff0000, v55
	v_fma_f32 v136, v136, s21, v148
	v_fma_f32 v137, v137, s21, v149
	v_fma_f32 v138, v138, s21, v150
	v_fma_f32 v139, v139, s21, v151
	v_fma_f32 v140, v140, s21, v152
	v_fma_f32 v141, v141, s21, v153
	v_fma_f32 v142, v142, s21, v154
	v_fma_f32 v143, v143, s21, v155
	v_cvt_pk_bf16_f32 v144, v136, v137
	v_cvt_pk_bf16_f32 v145, v138, v139
	v_cvt_pk_bf16_f32 v146, v140, v141
	v_cvt_pk_bf16_f32 v147, v142, v143
	global_store_dwordx4 v2, v[144:147], s[18:19] sc1
	s_add_u32 s18, s18, 0x20000
	s_addc_u32 s19, s19, 0
	v_lshlrev_b32_e32 v148, 16, v56
	v_and_b32_e32 v149, 0xffff0000, v56
	v_lshlrev_b32_e32 v150, 16, v57
	v_and_b32_e32 v151, 0xffff0000, v57
	v_lshlrev_b32_e32 v152, 16, v58
	v_and_b32_e32 v153, 0xffff0000, v58
	v_lshlrev_b32_e32 v154, 16, v59
	v_and_b32_e32 v155, 0xffff0000, v59
	v_fma_f32 v136, v136, s21, v148
	v_fma_f32 v137, v137, s21, v149
	v_fma_f32 v138, v138, s21, v150
	v_fma_f32 v139, v139, s21, v151
	v_fma_f32 v140, v140, s21, v152
	v_fma_f32 v141, v141, s21, v153
	v_fma_f32 v142, v142, s21, v154
	v_fma_f32 v143, v143, s21, v155
	v_cvt_pk_bf16_f32 v144, v136, v137
	v_cvt_pk_bf16_f32 v145, v138, v139
	v_cvt_pk_bf16_f32 v146, v140, v141
	v_cvt_pk_bf16_f32 v147, v142, v143
	global_store_dwordx4 v2, v[144:147], s[18:19] sc1
	s_add_u32 s18, s18, 0x20000
	s_addc_u32 s19, s19, 0
	v_lshlrev_b32_e32 v148, 16, v60
	v_and_b32_e32 v149, 0xffff0000, v60
	v_lshlrev_b32_e32 v150, 16, v61
	v_and_b32_e32 v151, 0xffff0000, v61
	v_lshlrev_b32_e32 v152, 16, v62
	v_and_b32_e32 v153, 0xffff0000, v62
	v_lshlrev_b32_e32 v154, 16, v63
	v_and_b32_e32 v155, 0xffff0000, v63
	v_fma_f32 v136, v136, s21, v148
	v_fma_f32 v137, v137, s21, v149
	v_fma_f32 v138, v138, s21, v150
	v_fma_f32 v139, v139, s21, v151
	v_fma_f32 v140, v140, s21, v152
	v_fma_f32 v141, v141, s21, v153
	v_fma_f32 v142, v142, s21, v154
	v_fma_f32 v143, v143, s21, v155
	v_cvt_pk_bf16_f32 v144, v136, v137
	v_cvt_pk_bf16_f32 v145, v138, v139
	v_cvt_pk_bf16_f32 v146, v140, v141
	v_cvt_pk_bf16_f32 v147, v142, v143
	global_store_dwordx4 v2, v[144:147], s[18:19] sc1
	s_add_u32 s18, s18, 0x20000
	s_addc_u32 s19, s19, 0
	v_lshlrev_b32_e32 v148, 16, v64
	v_and_b32_e32 v149, 0xffff0000, v64
	v_lshlrev_b32_e32 v150, 16, v65
	v_and_b32_e32 v151, 0xffff0000, v65
	v_lshlrev_b32_e32 v152, 16, v66
	v_and_b32_e32 v153, 0xffff0000, v66
	v_lshlrev_b32_e32 v154, 16, v67
	v_and_b32_e32 v155, 0xffff0000, v67
	v_fma_f32 v136, v136, s21, v148
	v_fma_f32 v137, v137, s21, v149
	v_fma_f32 v138, v138, s21, v150
	v_fma_f32 v139, v139, s21, v151
	v_fma_f32 v140, v140, s21, v152
	v_fma_f32 v141, v141, s21, v153
	v_fma_f32 v142, v142, s21, v154
	v_fma_f32 v143, v143, s21, v155
	v_cvt_pk_bf16_f32 v144, v136, v137
	v_cvt_pk_bf16_f32 v145, v138, v139
	v_cvt_pk_bf16_f32 v146, v140, v141
	v_cvt_pk_bf16_f32 v147, v142, v143
	global_store_dwordx4 v2, v[144:147], s[18:19] sc1
	s_add_u32 s18, s18, 0x20000
	s_addc_u32 s19, s19, 0
	v_lshlrev_b32_e32 v148, 16, v68
	v_and_b32_e32 v149, 0xffff0000, v68
	v_lshlrev_b32_e32 v150, 16, v69
	v_and_b32_e32 v151, 0xffff0000, v69
	v_lshlrev_b32_e32 v152, 16, v70
	v_and_b32_e32 v153, 0xffff0000, v70
	v_lshlrev_b32_e32 v154, 16, v71
	v_and_b32_e32 v155, 0xffff0000, v71
	v_fma_f32 v136, v136, s21, v148
	v_fma_f32 v137, v137, s21, v149
	v_fma_f32 v138, v138, s21, v150
	v_fma_f32 v139, v139, s21, v151
	v_fma_f32 v140, v140, s21, v152
	v_fma_f32 v141, v141, s21, v153
	v_fma_f32 v142, v142, s21, v154
	v_fma_f32 v143, v143, s21, v155
	s_waitcnt vmcnt(32)
	v_cvt_pk_bf16_f32 v144, v136, v137
	v_cvt_pk_bf16_f32 v145, v138, v139
	v_cvt_pk_bf16_f32 v146, v140, v141
	v_cvt_pk_bf16_f32 v147, v142, v143
	global_store_dwordx4 v2, v[144:147], s[18:19] sc1
	s_add_u32 s18, s18, 0x20000
	s_addc_u32 s19, s19, 0
	v_lshlrev_b32_e32 v148, 16, v72
	v_and_b32_e32 v149, 0xffff0000, v72
	v_lshlrev_b32_e32 v150, 16, v73
	v_and_b32_e32 v151, 0xffff0000, v73
	v_lshlrev_b32_e32 v152, 16, v74
	v_and_b32_e32 v153, 0xffff0000, v74
	v_lshlrev_b32_e32 v154, 16, v75
	v_and_b32_e32 v155, 0xffff0000, v75
	v_fma_f32 v136, v136, s21, v148
	v_fma_f32 v137, v137, s21, v149
	v_fma_f32 v138, v138, s21, v150
	v_fma_f32 v139, v139, s21, v151
	v_fma_f32 v140, v140, s21, v152
	v_fma_f32 v141, v141, s21, v153
	v_fma_f32 v142, v142, s21, v154
	v_fma_f32 v143, v143, s21, v155
	v_cvt_pk_bf16_f32 v144, v136, v137
	v_cvt_pk_bf16_f32 v145, v138, v139
	v_cvt_pk_bf16_f32 v146, v140, v141
	v_cvt_pk_bf16_f32 v147, v142, v143
	global_store_dwordx4 v2, v[144:147], s[18:19] sc1
	s_add_u32 s18, s18, 0x20000
	s_addc_u32 s19, s19, 0
	v_lshlrev_b32_e32 v148, 16, v76
	v_and_b32_e32 v149, 0xffff0000, v76
	v_lshlrev_b32_e32 v150, 16, v77
	v_and_b32_e32 v151, 0xffff0000, v77
	v_lshlrev_b32_e32 v152, 16, v78
	v_and_b32_e32 v153, 0xffff0000, v78
	v_lshlrev_b32_e32 v154, 16, v79
	v_and_b32_e32 v155, 0xffff0000, v79
	v_fma_f32 v136, v136, s21, v148
	v_fma_f32 v137, v137, s21, v149
	v_fma_f32 v138, v138, s21, v150
	v_fma_f32 v139, v139, s21, v151
	v_fma_f32 v140, v140, s21, v152
	v_fma_f32 v141, v141, s21, v153
	v_fma_f32 v142, v142, s21, v154
	v_fma_f32 v143, v143, s21, v155
	v_cvt_pk_bf16_f32 v144, v136, v137
	v_cvt_pk_bf16_f32 v145, v138, v139
	v_cvt_pk_bf16_f32 v146, v140, v141
	v_cvt_pk_bf16_f32 v147, v142, v143
	global_store_dwordx4 v2, v[144:147], s[18:19] sc1
	s_add_u32 s18, s18, 0x20000
	s_addc_u32 s19, s19, 0
	v_lshlrev_b32_e32 v148, 16, v80
	v_and_b32_e32 v149, 0xffff0000, v80
	v_lshlrev_b32_e32 v150, 16, v81
	v_and_b32_e32 v151, 0xffff0000, v81
	v_lshlrev_b32_e32 v152, 16, v82
	v_and_b32_e32 v153, 0xffff0000, v82
	v_lshlrev_b32_e32 v154, 16, v83
	v_and_b32_e32 v155, 0xffff0000, v83
	v_fma_f32 v136, v136, s21, v148
	v_fma_f32 v137, v137, s21, v149
	v_fma_f32 v138, v138, s21, v150
	v_fma_f32 v139, v139, s21, v151
	v_fma_f32 v140, v140, s21, v152
	v_fma_f32 v141, v141, s21, v153
	v_fma_f32 v142, v142, s21, v154
	v_fma_f32 v143, v143, s21, v155
	v_cvt_pk_bf16_f32 v144, v136, v137
	v_cvt_pk_bf16_f32 v145, v138, v139
	v_cvt_pk_bf16_f32 v146, v140, v141
	v_cvt_pk_bf16_f32 v147, v142, v143
	global_store_dwordx4 v2, v[144:147], s[18:19] sc1
	s_add_u32 s18, s18, 0x20000
	s_addc_u32 s19, s19, 0
	v_lshlrev_b32_e32 v148, 16, v84
	v_and_b32_e32 v149, 0xffff0000, v84
	v_lshlrev_b32_e32 v150, 16, v85
	v_and_b32_e32 v151, 0xffff0000, v85
	v_lshlrev_b32_e32 v152, 16, v86
	v_and_b32_e32 v153, 0xffff0000, v86
	v_lshlrev_b32_e32 v154, 16, v87
	v_and_b32_e32 v155, 0xffff0000, v87
	v_fma_f32 v136, v136, s21, v148
	v_fma_f32 v137, v137, s21, v149
	v_fma_f32 v138, v138, s21, v150
	v_fma_f32 v139, v139, s21, v151
	v_fma_f32 v140, v140, s21, v152
	v_fma_f32 v141, v141, s21, v153
	v_fma_f32 v142, v142, s21, v154
	v_fma_f32 v143, v143, s21, v155
	v_cvt_pk_bf16_f32 v144, v136, v137
	v_cvt_pk_bf16_f32 v145, v138, v139
	v_cvt_pk_bf16_f32 v146, v140, v141
	v_cvt_pk_bf16_f32 v147, v142, v143
	global_store_dwordx4 v2, v[144:147], s[18:19] sc1
	s_add_u32 s18, s18, 0x20000
	s_addc_u32 s19, s19, 0
	v_lshlrev_b32_e32 v148, 16, v88
	v_and_b32_e32 v149, 0xffff0000, v88
	v_lshlrev_b32_e32 v150, 16, v89
	v_and_b32_e32 v151, 0xffff0000, v89
	v_lshlrev_b32_e32 v152, 16, v90
	v_and_b32_e32 v153, 0xffff0000, v90
	v_lshlrev_b32_e32 v154, 16, v91
	v_and_b32_e32 v155, 0xffff0000, v91
	v_fma_f32 v136, v136, s21, v148
	v_fma_f32 v137, v137, s21, v149
	v_fma_f32 v138, v138, s21, v150
	v_fma_f32 v139, v139, s21, v151
	v_fma_f32 v140, v140, s21, v152
	v_fma_f32 v141, v141, s21, v153
	v_fma_f32 v142, v142, s21, v154
	v_fma_f32 v143, v143, s21, v155
	v_cvt_pk_bf16_f32 v144, v136, v137
	v_cvt_pk_bf16_f32 v145, v138, v139
	v_cvt_pk_bf16_f32 v146, v140, v141
	v_cvt_pk_bf16_f32 v147, v142, v143
	global_store_dwordx4 v2, v[144:147], s[18:19] sc1
	s_add_u32 s18, s18, 0x20000
	s_addc_u32 s19, s19, 0
	v_lshlrev_b32_e32 v148, 16, v92
	v_and_b32_e32 v149, 0xffff0000, v92
	v_lshlrev_b32_e32 v150, 16, v93
	v_and_b32_e32 v151, 0xffff0000, v93
	v_lshlrev_b32_e32 v152, 16, v94
	v_and_b32_e32 v153, 0xffff0000, v94
	v_lshlrev_b32_e32 v154, 16, v95
	v_and_b32_e32 v155, 0xffff0000, v95
	v_fma_f32 v136, v136, s21, v148
	v_fma_f32 v137, v137, s21, v149
	v_fma_f32 v138, v138, s21, v150
	v_fma_f32 v139, v139, s21, v151
	v_fma_f32 v140, v140, s21, v152
	v_fma_f32 v141, v141, s21, v153
	v_fma_f32 v142, v142, s21, v154
	v_fma_f32 v143, v143, s21, v155
	v_cvt_pk_bf16_f32 v144, v136, v137
	v_cvt_pk_bf16_f32 v145, v138, v139
	v_cvt_pk_bf16_f32 v146, v140, v141
	v_cvt_pk_bf16_f32 v147, v142, v143
	global_store_dwordx4 v2, v[144:147], s[18:19] sc1
	s_add_u32 s18, s18, 0x20000
	s_addc_u32 s19, s19, 0
	v_lshlrev_b32_e32 v148, 16, v96
	v_and_b32_e32 v149, 0xffff0000, v96
	v_lshlrev_b32_e32 v150, 16, v97
	v_and_b32_e32 v151, 0xffff0000, v97
	v_lshlrev_b32_e32 v152, 16, v98
	v_and_b32_e32 v153, 0xffff0000, v98
	v_lshlrev_b32_e32 v154, 16, v99
	v_and_b32_e32 v155, 0xffff0000, v99
	v_fma_f32 v136, v136, s21, v148
	v_fma_f32 v137, v137, s21, v149
	v_fma_f32 v138, v138, s21, v150
	v_fma_f32 v139, v139, s21, v151
	v_fma_f32 v140, v140, s21, v152
	v_fma_f32 v141, v141, s21, v153
	v_fma_f32 v142, v142, s21, v154
	v_fma_f32 v143, v143, s21, v155
	v_cvt_pk_bf16_f32 v144, v136, v137
	v_cvt_pk_bf16_f32 v145, v138, v139
	v_cvt_pk_bf16_f32 v146, v140, v141
	v_cvt_pk_bf16_f32 v147, v142, v143
	global_store_dwordx4 v2, v[144:147], s[18:19] sc1
	s_add_u32 s18, s18, 0x20000
	s_addc_u32 s19, s19, 0
	v_lshlrev_b32_e32 v148, 16, v100
	v_and_b32_e32 v149, 0xffff0000, v100
	v_lshlrev_b32_e32 v150, 16, v101
	v_and_b32_e32 v151, 0xffff0000, v101
	v_lshlrev_b32_e32 v152, 16, v102
	v_and_b32_e32 v153, 0xffff0000, v102
	v_lshlrev_b32_e32 v154, 16, v103
	v_and_b32_e32 v155, 0xffff0000, v103
	v_fma_f32 v136, v136, s21, v148
	v_fma_f32 v137, v137, s21, v149
	v_fma_f32 v138, v138, s21, v150
	v_fma_f32 v139, v139, s21, v151
	v_fma_f32 v140, v140, s21, v152
	v_fma_f32 v141, v141, s21, v153
	v_fma_f32 v142, v142, s21, v154
	v_fma_f32 v143, v143, s21, v155
	s_waitcnt vmcnt(24)
	v_cvt_pk_bf16_f32 v144, v136, v137
	v_cvt_pk_bf16_f32 v145, v138, v139
	v_cvt_pk_bf16_f32 v146, v140, v141
	v_cvt_pk_bf16_f32 v147, v142, v143
	global_store_dwordx4 v2, v[144:147], s[18:19] sc1
	s_add_u32 s18, s18, 0x20000
	s_addc_u32 s19, s19, 0
	v_lshlrev_b32_e32 v148, 16, v104
	v_and_b32_e32 v149, 0xffff0000, v104
	v_lshlrev_b32_e32 v150, 16, v105
	v_and_b32_e32 v151, 0xffff0000, v105
	v_lshlrev_b32_e32 v152, 16, v106
	v_and_b32_e32 v153, 0xffff0000, v106
	v_lshlrev_b32_e32 v154, 16, v107
	v_and_b32_e32 v155, 0xffff0000, v107
	v_fma_f32 v136, v136, s21, v148
	v_fma_f32 v137, v137, s21, v149
	v_fma_f32 v138, v138, s21, v150
	v_fma_f32 v139, v139, s21, v151
	v_fma_f32 v140, v140, s21, v152
	v_fma_f32 v141, v141, s21, v153
	v_fma_f32 v142, v142, s21, v154
	v_fma_f32 v143, v143, s21, v155
	v_cvt_pk_bf16_f32 v144, v136, v137
	v_cvt_pk_bf16_f32 v145, v138, v139
	v_cvt_pk_bf16_f32 v146, v140, v141
	v_cvt_pk_bf16_f32 v147, v142, v143
	global_store_dwordx4 v2, v[144:147], s[18:19] sc1
	s_add_u32 s18, s18, 0x20000
	s_addc_u32 s19, s19, 0
	v_lshlrev_b32_e32 v148, 16, v108
	v_and_b32_e32 v149, 0xffff0000, v108
	v_lshlrev_b32_e32 v150, 16, v109
	v_and_b32_e32 v151, 0xffff0000, v109
	v_lshlrev_b32_e32 v152, 16, v110
	v_and_b32_e32 v153, 0xffff0000, v110
	v_lshlrev_b32_e32 v154, 16, v111
	v_and_b32_e32 v155, 0xffff0000, v111
	v_fma_f32 v136, v136, s21, v148
	v_fma_f32 v137, v137, s21, v149
	v_fma_f32 v138, v138, s21, v150
	v_fma_f32 v139, v139, s21, v151
	v_fma_f32 v140, v140, s21, v152
	v_fma_f32 v141, v141, s21, v153
	v_fma_f32 v142, v142, s21, v154
	v_fma_f32 v143, v143, s21, v155
	v_cvt_pk_bf16_f32 v144, v136, v137
	v_cvt_pk_bf16_f32 v145, v138, v139
	v_cvt_pk_bf16_f32 v146, v140, v141
	v_cvt_pk_bf16_f32 v147, v142, v143
	global_store_dwordx4 v2, v[144:147], s[18:19] sc1
	s_add_u32 s18, s18, 0x20000
	s_addc_u32 s19, s19, 0
	v_lshlrev_b32_e32 v148, 16, v112
	v_and_b32_e32 v149, 0xffff0000, v112
	v_lshlrev_b32_e32 v150, 16, v113
	v_and_b32_e32 v151, 0xffff0000, v113
	v_lshlrev_b32_e32 v152, 16, v114
	v_and_b32_e32 v153, 0xffff0000, v114
	v_lshlrev_b32_e32 v154, 16, v115
	v_and_b32_e32 v155, 0xffff0000, v115
	v_fma_f32 v136, v136, s21, v148
	v_fma_f32 v137, v137, s21, v149
	v_fma_f32 v138, v138, s21, v150
	v_fma_f32 v139, v139, s21, v151
	v_fma_f32 v140, v140, s21, v152
	v_fma_f32 v141, v141, s21, v153
	v_fma_f32 v142, v142, s21, v154
	v_fma_f32 v143, v143, s21, v155
	v_cvt_pk_bf16_f32 v144, v136, v137
	v_cvt_pk_bf16_f32 v145, v138, v139
	v_cvt_pk_bf16_f32 v146, v140, v141
	v_cvt_pk_bf16_f32 v147, v142, v143
	global_store_dwordx4 v2, v[144:147], s[18:19] sc1
	s_add_u32 s18, s18, 0x20000
	s_addc_u32 s19, s19, 0
	v_lshlrev_b32_e32 v148, 16, v116
	v_and_b32_e32 v149, 0xffff0000, v116
	v_lshlrev_b32_e32 v150, 16, v117
	v_and_b32_e32 v151, 0xffff0000, v117
	v_lshlrev_b32_e32 v152, 16, v118
	v_and_b32_e32 v153, 0xffff0000, v118
	v_lshlrev_b32_e32 v154, 16, v119
	v_and_b32_e32 v155, 0xffff0000, v119
	v_fma_f32 v136, v136, s21, v148
	v_fma_f32 v137, v137, s21, v149
	v_fma_f32 v138, v138, s21, v150
	v_fma_f32 v139, v139, s21, v151
	v_fma_f32 v140, v140, s21, v152
	v_fma_f32 v141, v141, s21, v153
	v_fma_f32 v142, v142, s21, v154
	v_fma_f32 v143, v143, s21, v155
	v_cvt_pk_bf16_f32 v144, v136, v137
	v_cvt_pk_bf16_f32 v145, v138, v139
	v_cvt_pk_bf16_f32 v146, v140, v141
	v_cvt_pk_bf16_f32 v147, v142, v143
	global_store_dwordx4 v2, v[144:147], s[18:19] sc1
	s_add_u32 s18, s18, 0x20000
	s_addc_u32 s19, s19, 0
	v_lshlrev_b32_e32 v148, 16, v120
	v_and_b32_e32 v149, 0xffff0000, v120
	v_lshlrev_b32_e32 v150, 16, v121
	v_and_b32_e32 v151, 0xffff0000, v121
	v_lshlrev_b32_e32 v152, 16, v122
	v_and_b32_e32 v153, 0xffff0000, v122
	v_lshlrev_b32_e32 v154, 16, v123
	v_and_b32_e32 v155, 0xffff0000, v123
	v_fma_f32 v136, v136, s21, v148
	v_fma_f32 v137, v137, s21, v149
	v_fma_f32 v138, v138, s21, v150
	v_fma_f32 v139, v139, s21, v151
	v_fma_f32 v140, v140, s21, v152
	v_fma_f32 v141, v141, s21, v153
	v_fma_f32 v142, v142, s21, v154
	v_fma_f32 v143, v143, s21, v155
	v_cvt_pk_bf16_f32 v144, v136, v137
	v_cvt_pk_bf16_f32 v145, v138, v139
	v_cvt_pk_bf16_f32 v146, v140, v141
	v_cvt_pk_bf16_f32 v147, v142, v143
	global_store_dwordx4 v2, v[144:147], s[18:19] sc1
	s_add_u32 s18, s18, 0x20000
	s_addc_u32 s19, s19, 0
	v_lshlrev_b32_e32 v148, 16, v124
	v_and_b32_e32 v149, 0xffff0000, v124
	v_lshlrev_b32_e32 v150, 16, v125
	v_and_b32_e32 v151, 0xffff0000, v125
	v_lshlrev_b32_e32 v152, 16, v126
	v_and_b32_e32 v153, 0xffff0000, v126
	v_lshlrev_b32_e32 v154, 16, v127
	v_and_b32_e32 v155, 0xffff0000, v127
	v_fma_f32 v136, v136, s21, v148
	v_fma_f32 v137, v137, s21, v149
	v_fma_f32 v138, v138, s21, v150
	v_fma_f32 v139, v139, s21, v151
	v_fma_f32 v140, v140, s21, v152
	v_fma_f32 v141, v141, s21, v153
	v_fma_f32 v142, v142, s21, v154
	v_fma_f32 v143, v143, s21, v155
	v_cvt_pk_bf16_f32 v144, v136, v137
	v_cvt_pk_bf16_f32 v145, v138, v139
	v_cvt_pk_bf16_f32 v146, v140, v141
	v_cvt_pk_bf16_f32 v147, v142, v143
	global_store_dwordx4 v2, v[144:147], s[18:19] sc1
	s_add_u32 s18, s18, 0x20000
	s_addc_u32 s19, s19, 0
	v_lshlrev_b32_e32 v148, 16, v128
	v_and_b32_e32 v149, 0xffff0000, v128
	v_lshlrev_b32_e32 v150, 16, v129
	v_and_b32_e32 v151, 0xffff0000, v129
	v_lshlrev_b32_e32 v152, 16, v130
	v_and_b32_e32 v153, 0xffff0000, v130
	v_lshlrev_b32_e32 v154, 16, v131
	v_and_b32_e32 v155, 0xffff0000, v131
	v_fma_f32 v136, v136, s21, v148
	v_fma_f32 v137, v137, s21, v149
	v_fma_f32 v138, v138, s21, v150
	v_fma_f32 v139, v139, s21, v151
	v_fma_f32 v140, v140, s21, v152
	v_fma_f32 v141, v141, s21, v153
	v_fma_f32 v142, v142, s21, v154
	v_fma_f32 v143, v143, s21, v155
	v_cvt_pk_bf16_f32 v144, v136, v137
	v_cvt_pk_bf16_f32 v145, v138, v139
	v_cvt_pk_bf16_f32 v146, v140, v141
	v_cvt_pk_bf16_f32 v147, v142, v143
	global_store_dwordx4 v2, v[144:147], s[18:19] sc1
	s_add_u32 s18, s18, 0x20000
	s_addc_u32 s19, s19, 0
	v_lshlrev_b32_e32 v148, 16, v132
	v_and_b32_e32 v149, 0xffff0000, v132
	v_lshlrev_b32_e32 v150, 16, v133
	v_and_b32_e32 v151, 0xffff0000, v133
	v_lshlrev_b32_e32 v152, 16, v134
	v_and_b32_e32 v153, 0xffff0000, v134
	v_lshlrev_b32_e32 v154, 16, v135
	v_and_b32_e32 v155, 0xffff0000, v135
	v_fma_f32 v136, v136, s21, v148
	v_fma_f32 v137, v137, s21, v149
	v_fma_f32 v138, v138, s21, v150
	v_fma_f32 v139, v139, s21, v151
	v_fma_f32 v140, v140, s21, v152
	v_fma_f32 v141, v141, s21, v153
	v_fma_f32 v142, v142, s21, v154
	v_fma_f32 v143, v143, s21, v155
	s_branch .Lp3_done
.Lp3_ssd:
	s_add_u32 s16, s8, s15
	s_addc_u32 s17, s9, 0
	s_add_u32 s16, s16, 0x4000000
	s_addc_u32 s17, s17, 0
	s_mov_b64 s[18:19], s[16:17]
	v_add_u32_e32 v1, 0xffff8000, v1
	v_lshlrev_b32_e32 v2, 2, v1
	s_sub_u32 s20, s14, 0x8000
	s_lshr_b32 s20, s20, 12
	s_lshl_b32 s23, s13, 11
	s_add_u32 s20, s20, s23
	s_lshl_b32 s20, s20, 2
	s_add_u32 s24, s10, 0x3f2a000
	s_addc_u32 s25, s11, 0
	s_add_u32 s24, s24, s20
	s_addc_u32 s25, s25, 0
	v_mov_b32_e32 v136, 0
	v_mov_b32_e32 v137, 0
	v_mov_b32_e32 v138, 0
	v_mov_b32_e32 v139, 0
	v_mov_b32_e32 v140, 0
	v_mov_b32_e32 v141, 0
	v_mov_b32_e32 v142, 0
	v_mov_b32_e32 v143, 0
	global_load_dwordx4 v[8:11], v2, s[16:17]
	s_add_u32 s16, s16, 0x20000
	s_addc_u32 s17, s17, 0
	global_load_dwordx4 v[12:15], v2, s[16:17]
	s_add_u32 s16, s16, 0x20000
	s_addc_u32 s17, s17, 0
	global_load_dwordx4 v[16:19], v2, s[16:17]
	s_add_u32 s16, s16, 0x20000
	s_addc_u32 s17, s17, 0
	global_load_dwordx4 v[20:23], v2, s[16:17]
	s_add_u32 s16, s16, 0x20000
	s_addc_u32 s17, s17, 0
	global_load_dwordx4 v[24:27], v2, s[16:17]
	s_add_u32 s16, s16, 0x20000
	s_addc_u32 s17, s17, 0
	global_load_dwordx4 v[28:31], v2, s[16:17]
	s_add_u32 s16, s16, 0x20000
	s_addc_u32 s17, s17, 0
	global_load_dwordx4 v[32:35], v2, s[16:17]
	s_add_u32 s16, s16, 0x20000
	s_addc_u32 s17, s17, 0
	global_load_dwordx4 v[36:39], v2, s[16:17]
	s_add_u32 s16, s16, 0x20000
	s_addc_u32 s17, s17, 0
	s_load_dword s32, s[24:25], 0x0
	s_load_dword s33, s[24:25], 0x20
	s_load_dword s34, s[24:25], 0x40
	s_load_dword s35, s[24:25], 0x60
	s_load_dword s36, s[24:25], 0x80
	s_load_dword s37, s[24:25], 0xa0
	s_load_dword s38, s[24:25], 0xc0
	s_load_dword s39, s[24:25], 0xe0
	s_add_u32 s24, s24, 0x100
	s_addc_u32 s25, s25, 0
	global_load_dwordx4 v[40:43], v2, s[16:17]
	s_add_u32 s16, s16, 0x20000
	s_addc_u32 s17, s17, 0
	global_load_dwordx4 v[44:47], v2, s[16:17]
	s_add_u32 s16, s16, 0x20000
	s_addc_u32 s17, s17, 0
	global_load_dwordx4 v[48:51], v2, s[16:17]
	s_add_u32 s16, s16, 0x20000
	s_addc_u32 s17, s17, 0
	global_load_dwordx4 v[52:55], v2, s[16:17]
	s_add_u32 s16, s16, 0x20000
	s_addc_u32 s17, s17, 0
	global_load_dwordx4 v[56:59], v2, s[16:17]
	s_add_u32 s16, s16, 0x20000
	s_addc_u32 s17, s17, 0
	global_load_dwordx4 v[60:63], v2, s[16:17]
	s_add_u32 s16, s16, 0x20000
	s_addc_u32 s17, s17, 0
	global_load_dwordx4 v[64:67], v2, s[16:17]
	s_add_u32 s16, s16, 0x20000
	s_addc_u32 s17, s17, 0
	global_load_dwordx4 v[68:71], v2, s[16:17]
	s_add_u32 s16, s16, 0x20000
	s_addc_u32 s17, s17, 0
	s_load_dword s40, s[24:25], 0x0
	s_load_dword s41, s[24:25], 0x20
	s_load_dword s42, s[24:25], 0x40
	s_load_dword s43, s[24:25], 0x60
	s_load_dword s44, s[24:25], 0x80
	s_load_dword s45, s[24:25], 0xa0
	s_load_dword s46, s[24:25], 0xc0
	s_load_dword s47, s[24:25], 0xe0
	s_add_u32 s24, s24, 0x100
	s_addc_u32 s25, s25, 0
	global_load_dwordx4 v[72:75], v2, s[16:17]
	s_add_u32 s16, s16, 0x20000
	s_addc_u32 s17, s17, 0
	global_load_dwordx4 v[76:79], v2, s[16:17]
	s_add_u32 s16, s16, 0x20000
	s_addc_u32 s17, s17, 0
	global_load_dwordx4 v[80:83], v2, s[16:17]
	s_add_u32 s16, s16, 0x20000
	s_addc_u32 s17, s17, 0
	global_load_dwordx4 v[84:87], v2, s[16:17]
	s_add_u32 s16, s16, 0x20000
	s_addc_u32 s17, s17, 0
	global_load_dwordx4 v[88:91], v2, s[16:17]
	s_add_u32 s16, s16, 0x20000
	s_addc_u32 s17, s17, 0
	global_load_dwordx4 v[92:95], v2, s[16:17]
	s_add_u32 s16, s16, 0x20000
	s_addc_u32 s17, s17, 0
	global_load_dwordx4 v[96:99], v2, s[16:17]
	s_add_u32 s16, s16, 0x20000
	s_addc_u32 s17, s17, 0
	global_load_dwordx4 v[100:103], v2, s[16:17]
	s_add_u32 s16, s16, 0x20000
	s_addc_u32 s17, s17, 0
	s_load_dword s48, s[24:25], 0x0
	s_load_dword s49, s[24:25], 0x20
	s_load_dword s50, s[24:25], 0x40
	s_load_dword s51, s[24:25], 0x60
	s_load_dword s52, s[24:25], 0x80
	s_load_dword s53, s[24:25], 0xa0
	s_load_dword s54, s[24:25], 0xc0
	s_load_dword s55, s[24:25], 0xe0
	s_add_u32 s24, s24, 0x100
	s_addc_u32 s25, s25, 0
	global_load_dwordx4 v[104:107], v2, s[16:17]
	s_add_u32 s16, s16, 0x20000
	s_addc_u32 s17, s17, 0
	global_load_dwordx4 v[108:111], v2, s[16:17]
	s_add_u32 s16, s16, 0x20000
	s_addc_u32 s17, s17, 0
	global_load_dwordx4 v[112:115], v2, s[16:17]
	s_add_u32 s16, s16, 0x20000
	s_addc_u32 s17, s17, 0
	global_load_dwordx4 v[116:119], v2, s[16:17]
	s_add_u32 s16, s16, 0x20000
	s_addc_u32 s17, s17, 0
	global_load_dwordx4 v[120:123], v2, s[16:17]
	s_add_u32 s16, s16, 0x20000
	s_addc_u32 s17, s17, 0
	global_load_dwordx4 v[124:127], v2, s[16:17]
	s_add_u32 s16, s16, 0x20000
	s_addc_u32 s17, s17, 0
	global_load_dwordx4 v[128:131], v2, s[16:17]
	s_add_u32 s16, s16, 0x20000
	s_addc_u32 s17, s17, 0
	global_load_dwordx4 v[132:135], v2, s[16:17]
	s_add_u32 s16, s16, 0x20000
	s_addc_u32 s17, s17, 0
	s_load_dword s56, s[24:25], 0x0
	s_load_dword s57, s[24:25], 0x20
	s_load_dword s58, s[24:25], 0x40
	s_load_dword s59, s[24:25], 0x60
	s_load_dword s60, s[24:25], 0x80
	s_load_dword s61, s[24:25], 0xa0
	s_load_dword s62, s[24:25], 0xc0
	s_load_dword s63, s[24:25], 0xe0
	s_add_u32 s24, s24, 0x100
	s_addc_u32 s25, s25, 0
	s_waitcnt vmcnt(24) lgkmcnt(0)
	v_cvt_pk_bf16_f32 v144, v136, v137
	v_cvt_pk_bf16_f32 v145, v138, v139
	v_cvt_pk_bf16_f32 v146, v140, v141
	v_cvt_pk_bf16_f32 v147, v142, v143
	global_store_dwordx4 v2, v[144:147], s[18:19] sc1
	s_add_u32 s18, s18, 0x20000
	s_addc_u32 s19, s19, 0
	v_lshlrev_b32_e32 v148, 16, v8
	v_and_b32_e32 v149, 0xffff0000, v8
	v_lshlrev_b32_e32 v150, 16, v9
	v_and_b32_e32 v151, 0xffff0000, v9
	v_lshlrev_b32_e32 v152, 16, v10
	v_and_b32_e32 v153, 0xffff0000, v10
	v_lshlrev_b32_e32 v154, 16, v11
	v_and_b32_e32 v155, 0xffff0000, v11
	v_fma_f32 v136, v136, s32, v148
	v_fma_f32 v137, v137, s32, v149
	v_fma_f32 v138, v138, s32, v150
	v_fma_f32 v139, v139, s32, v151
	v_fma_f32 v140, v140, s32, v152
	v_fma_f32 v141, v141, s32, v153
	v_fma_f32 v142, v142, s32, v154
	v_fma_f32 v143, v143, s32, v155
	v_cvt_pk_bf16_f32 v144, v136, v137
	v_cvt_pk_bf16_f32 v145, v138, v139
	v_cvt_pk_bf16_f32 v146, v140, v141
	v_cvt_pk_bf16_f32 v147, v142, v143
	global_store_dwordx4 v2, v[144:147], s[18:19] sc1
	s_add_u32 s18, s18, 0x20000
	s_addc_u32 s19, s19, 0
	v_lshlrev_b32_e32 v148, 16, v12
	v_and_b32_e32 v149, 0xffff0000, v12
	v_lshlrev_b32_e32 v150, 16, v13
	v_and_b32_e32 v151, 0xffff0000, v13
	v_lshlrev_b32_e32 v152, 16, v14
	v_and_b32_e32 v153, 0xffff0000, v14
	v_lshlrev_b32_e32 v154, 16, v15
	v_and_b32_e32 v155, 0xffff0000, v15
	v_fma_f32 v136, v136, s33, v148
	v_fma_f32 v137, v137, s33, v149
	v_fma_f32 v138, v138, s33, v150
	v_fma_f32 v139, v139, s33, v151
	v_fma_f32 v140, v140, s33, v152
	v_fma_f32 v141, v141, s33, v153
	v_fma_f32 v142, v142, s33, v154
	v_fma_f32 v143, v143, s33, v155
	v_cvt_pk_bf16_f32 v144, v136, v137
	v_cvt_pk_bf16_f32 v145, v138, v139
	v_cvt_pk_bf16_f32 v146, v140, v141
	v_cvt_pk_bf16_f32 v147, v142, v143
	global_store_dwordx4 v2, v[144:147], s[18:19] sc1
	s_add_u32 s18, s18, 0x20000
	s_addc_u32 s19, s19, 0
	v_lshlrev_b32_e32 v148, 16, v16
	v_and_b32_e32 v149, 0xffff0000, v16
	v_lshlrev_b32_e32 v150, 16, v17
	v_and_b32_e32 v151, 0xffff0000, v17
	v_lshlrev_b32_e32 v152, 16, v18
	v_and_b32_e32 v153, 0xffff0000, v18
	v_lshlrev_b32_e32 v154, 16, v19
	v_and_b32_e32 v155, 0xffff0000, v19
	v_fma_f32 v136, v136, s34, v148
	v_fma_f32 v137, v137, s34, v149
	v_fma_f32 v138, v138, s34, v150
	v_fma_f32 v139, v139, s34, v151
	v_fma_f32 v140, v140, s34, v152
	v_fma_f32 v141, v141, s34, v153
	v_fma_f32 v142, v142, s34, v154
	v_fma_f32 v143, v143, s34, v155
	v_cvt_pk_bf16_f32 v144, v136, v137
	v_cvt_pk_bf16_f32 v145, v138, v139
	v_cvt_pk_bf16_f32 v146, v140, v141
	v_cvt_pk_bf16_f32 v147, v142, v143
	global_store_dwordx4 v2, v[144:147], s[18:19] sc1
	s_add_u32 s18, s18, 0x20000
	s_addc_u32 s19, s19, 0
	v_lshlrev_b32_e32 v148, 16, v20
	v_and_b32_e32 v149, 0xffff0000, v20
	v_lshlrev_b32_e32 v150, 16, v21
	v_and_b32_e32 v151, 0xffff0000, v21
	v_lshlrev_b32_e32 v152, 16, v22
	v_and_b32_e32 v153, 0xffff0000, v22
	v_lshlrev_b32_e32 v154, 16, v23
	v_and_b32_e32 v155, 0xffff0000, v23
	v_fma_f32 v136, v136, s35, v148
	v_fma_f32 v137, v137, s35, v149
	v_fma_f32 v138, v138, s35, v150
	v_fma_f32 v139, v139, s35, v151
	v_fma_f32 v140, v140, s35, v152
	v_fma_f32 v141, v141, s35, v153
	v_fma_f32 v142, v142, s35, v154
	v_fma_f32 v143, v143, s35, v155
	v_cvt_pk_bf16_f32 v144, v136, v137
	v_cvt_pk_bf16_f32 v145, v138, v139
	v_cvt_pk_bf16_f32 v146, v140, v141
	v_cvt_pk_bf16_f32 v147, v142, v143
	global_store_dwordx4 v2, v[144:147], s[18:19] sc1
	s_add_u32 s18, s18, 0x20000
	s_addc_u32 s19, s19, 0
	v_lshlrev_b32_e32 v148, 16, v24
	v_and_b32_e32 v149, 0xffff0000, v24
	v_lshlrev_b32_e32 v150, 16, v25
	v_and_b32_e32 v151, 0xffff0000, v25
	v_lshlrev_b32_e32 v152, 16, v26
	v_and_b32_e32 v153, 0xffff0000, v26
	v_lshlrev_b32_e32 v154, 16, v27
	v_and_b32_e32 v155, 0xffff0000, v27
	v_fma_f32 v136, v136, s36, v148
	v_fma_f32 v137, v137, s36, v149
	v_fma_f32 v138, v138, s36, v150
	v_fma_f32 v139, v139, s36, v151
	v_fma_f32 v140, v140, s36, v152
	v_fma_f32 v141, v141, s36, v153
	v_fma_f32 v142, v142, s36, v154
	v_fma_f32 v143, v143, s36, v155
	v_cvt_pk_bf16_f32 v144, v136, v137
	v_cvt_pk_bf16_f32 v145, v138, v139
	v_cvt_pk_bf16_f32 v146, v140, v141
	v_cvt_pk_bf16_f32 v147, v142, v143
	global_store_dwordx4 v2, v[144:147], s[18:19] sc1
	s_add_u32 s18, s18, 0x20000
	s_addc_u32 s19, s19, 0
	v_lshlrev_b32_e32 v148, 16, v28
	v_and_b32_e32 v149, 0xffff0000, v28
	v_lshlrev_b32_e32 v150, 16, v29
	v_and_b32_e32 v151, 0xffff0000, v29
	v_lshlrev_b32_e32 v152, 16, v30
	v_and_b32_e32 v153, 0xffff0000, v30
	v_lshlrev_b32_e32 v154, 16, v31
	v_and_b32_e32 v155, 0xffff0000, v31
	v_fma_f32 v136, v136, s37, v148
	v_fma_f32 v137, v137, s37, v149
	v_fma_f32 v138, v138, s37, v150
	v_fma_f32 v139, v139, s37, v151
	v_fma_f32 v140, v140, s37, v152
	v_fma_f32 v141, v141, s37, v153
	v_fma_f32 v142, v142, s37, v154
	v_fma_f32 v143, v143, s37, v155
	v_cvt_pk_bf16_f32 v144, v136, v137
	v_cvt_pk_bf16_f32 v145, v138, v139
	v_cvt_pk_bf16_f32 v146, v140, v141
	v_cvt_pk_bf16_f32 v147, v142, v143
	global_store_dwordx4 v2, v[144:147], s[18:19] sc1
	s_add_u32 s18, s18, 0x20000
	s_addc_u32 s19, s19, 0
	v_lshlrev_b32_e32 v148, 16, v32
	v_and_b32_e32 v149, 0xffff0000, v32
	v_lshlrev_b32_e32 v150, 16, v33
	v_and_b32_e32 v151, 0xffff0000, v33
	v_lshlrev_b32_e32 v152, 16, v34
	v_and_b32_e32 v153, 0xffff0000, v34
	v_lshlrev_b32_e32 v154, 16, v35
	v_and_b32_e32 v155, 0xffff0000, v35
	v_fma_f32 v136, v136, s38, v148
	v_fma_f32 v137, v137, s38, v149
	v_fma_f32 v138, v138, s38, v150
	v_fma_f32 v139, v139, s38, v151
	v_fma_f32 v140, v140, s38, v152
	v_fma_f32 v141, v141, s38, v153
	v_fma_f32 v142, v142, s38, v154
	v_fma_f32 v143, v143, s38, v155
	v_cvt_pk_bf16_f32 v144, v136, v137
	v_cvt_pk_bf16_f32 v145, v138, v139
	v_cvt_pk_bf16_f32 v146, v140, v141
	v_cvt_pk_bf16_f32 v147, v142, v143
	global_store_dwordx4 v2, v[144:147], s[18:19] sc1
	s_add_u32 s18, s18, 0x20000
	s_addc_u32 s19, s19, 0
	v_lshlrev_b32_e32 v148, 16, v36
	v_and_b32_e32 v149, 0xffff0000, v36
	v_lshlrev_b32_e32 v150, 16, v37
	v_and_b32_e32 v151, 0xffff0000, v37
	v_lshlrev_b32_e32 v152, 16, v38
	v_and_b32_e32 v153, 0xffff0000, v38
	v_lshlrev_b32_e32 v154, 16, v39
	v_and_b32_e32 v155, 0xffff0000, v39
	v_fma_f32 v136, v136, s39, v148
	v_fma_f32 v137, v137, s39, v149
	v_fma_f32 v138, v138, s39, v150
	v_fma_f32 v139, v139, s39, v151
	v_fma_f32 v140, v140, s39, v152
	v_fma_f32 v141, v141, s39, v153
	v_fma_f32 v142, v142, s39, v154
	v_fma_f32 v143, v143, s39, v155
	global_load_dwordx4 v[8:11], v2, s[16:17]
	s_add_u32 s16, s16, 0x20000
	s_addc_u32 s17, s17, 0
	global_load_dwordx4 v[12:15], v2, s[16:17]
	s_add_u32 s16, s16, 0x20000
	s_addc_u32 s17, s17, 0
	global_load_dwordx4 v[16:19], v2, s[16:17]
	s_add_u32 s16, s16, 0x20000
	s_addc_u32 s17, s17, 0
	global_load_dwordx4 v[20:23], v2, s[16:17]
	s_add_u32 s16, s16, 0x20000
	s_addc_u32 s17, s17, 0
	global_load_dwordx4 v[24:27], v2, s[16:17]
	s_add_u32 s16, s16, 0x20000
	s_addc_u32 s17, s17, 0
	global_load_dwordx4 v[28:31], v2, s[16:17]
	s_add_u32 s16, s16, 0x20000
	s_addc_u32 s17, s17, 0
	global_load_dwordx4 v[32:35], v2, s[16:17]
	s_add_u32 s16, s16, 0x20000
	s_addc_u32 s17, s17, 0
	global_load_dwordx4 v[36:39], v2, s[16:17]
	s_add_u32 s16, s16, 0x20000
	s_addc_u32 s17, s17, 0
	s_load_dword s32, s[24:25], 0x0
	s_load_dword s33, s[24:25], 0x20
	s_load_dword s34, s[24:25], 0x40
	s_load_dword s35, s[24:25], 0x60
	s_load_dword s36, s[24:25], 0x80
	s_load_dword s37, s[24:25], 0xa0
	s_load_dword s38, s[24:25], 0xc0
	s_load_dword s39, s[24:25], 0xe0
	s_add_u32 s24, s24, 0x100
	s_addc_u32 s25, s25, 0
	s_waitcnt vmcnt(32) lgkmcnt(0)
	v_cvt_pk_bf16_f32 v144, v136, v137
	v_cvt_pk_bf16_f32 v145, v138, v139
	v_cvt_pk_bf16_f32 v146, v140, v141
	v_cvt_pk_bf16_f32 v147, v142, v143
	global_store_dwordx4 v2, v[144:147], s[18:19] sc1
	s_add_u32 s18, s18, 0x20000
	s_addc_u32 s19, s19, 0
	v_lshlrev_b32_e32 v148, 16, v40
	v_and_b32_e32 v149, 0xffff0000, v40
	v_lshlrev_b32_e32 v150, 16, v41
	v_and_b32_e32 v151, 0xffff0000, v41
	v_lshlrev_b32_e32 v152, 16, v42
	v_and_b32_e32 v153, 0xffff0000, v42
	v_lshlrev_b32_e32 v154, 16, v43
	v_and_b32_e32 v155, 0xffff0000, v43
	v_fma_f32 v136, v136, s40, v148
	v_fma_f32 v137, v137, s40, v149
	v_fma_f32 v138, v138, s40, v150
	v_fma_f32 v139, v139, s40, v151
	v_fma_f32 v140, v140, s40, v152
	v_fma_f32 v141, v141, s40, v153
	v_fma_f32 v142, v142, s40, v154
	v_fma_f32 v143, v143, s40, v155
	v_cvt_pk_bf16_f32 v144, v136, v137
	v_cvt_pk_bf16_f32 v145, v138, v139
	v_cvt_pk_bf16_f32 v146, v140, v141
	v_cvt_pk_bf16_f32 v147, v142, v143
	global_store_dwordx4 v2, v[144:147], s[18:19] sc1
	s_add_u32 s18, s18, 0x20000
	s_addc_u32 s19, s19, 0
	v_lshlrev_b32_e32 v148, 16, v44
	v_and_b32_e32 v149, 0xffff0000, v44
	v_lshlrev_b32_e32 v150, 16, v45
	v_and_b32_e32 v151, 0xffff0000, v45
	v_lshlrev_b32_e32 v152, 16, v46
	v_and_b32_e32 v153, 0xffff0000, v46
	v_lshlrev_b32_e32 v154, 16, v47
	v_and_b32_e32 v155, 0xffff0000, v47
	v_fma_f32 v136, v136, s41, v148
	v_fma_f32 v137, v137, s41, v149
	v_fma_f32 v138, v138, s41, v150
	v_fma_f32 v139, v139, s41, v151
	v_fma_f32 v140, v140, s41, v152
	v_fma_f32 v141, v141, s41, v153
	v_fma_f32 v142, v142, s41, v154
	v_fma_f32 v143, v143, s41, v155
	v_cvt_pk_bf16_f32 v144, v136, v137
	v_cvt_pk_bf16_f32 v145, v138, v139
	v_cvt_pk_bf16_f32 v146, v140, v141
	v_cvt_pk_bf16_f32 v147, v142, v143
	global_store_dwordx4 v2, v[144:147], s[18:19] sc1
	s_add_u32 s18, s18, 0x20000
	s_addc_u32 s19, s19, 0
	v_lshlrev_b32_e32 v148, 16, v48
	v_and_b32_e32 v149, 0xffff0000, v48
	v_lshlrev_b32_e32 v150, 16, v49
	v_and_b32_e32 v151, 0xffff0000, v49
	v_lshlrev_b32_e32 v152, 16, v50
	v_and_b32_e32 v153, 0xffff0000, v50
	v_lshlrev_b32_e32 v154, 16, v51
	v_and_b32_e32 v155, 0xffff0000, v51
	v_fma_f32 v136, v136, s42, v148
	v_fma_f32 v137, v137, s42, v149
	v_fma_f32 v138, v138, s42, v150
	v_fma_f32 v139, v139, s42, v151
	v_fma_f32 v140, v140, s42, v152
	v_fma_f32 v141, v141, s42, v153
	v_fma_f32 v142, v142, s42, v154
	v_fma_f32 v143, v143, s42, v155
	v_cvt_pk_bf16_f32 v144, v136, v137
	v_cvt_pk_bf16_f32 v145, v138, v139
	v_cvt_pk_bf16_f32 v146, v140, v141
	v_cvt_pk_bf16_f32 v147, v142, v143
	global_store_dwordx4 v2, v[144:147], s[18:19] sc1
	s_add_u32 s18, s18, 0x20000
	s_addc_u32 s19, s19, 0
	v_lshlrev_b32_e32 v148, 16, v52
	v_and_b32_e32 v149, 0xffff0000, v52
	v_lshlrev_b32_e32 v150, 16, v53
	v_and_b32_e32 v151, 0xffff0000, v53
	v_lshlrev_b32_e32 v152, 16, v54
	v_and_b32_e32 v153, 0xffff0000, v54
	v_lshlrev_b32_e32 v154, 16, v55
	v_and_b32_e32 v155, 0xffff0000, v55
	v_fma_f32 v136, v136, s43, v148
	v_fma_f32 v137, v137, s43, v149
	v_fma_f32 v138, v138, s43, v150
	v_fma_f32 v139, v139, s43, v151
	v_fma_f32 v140, v140, s43, v152
	v_fma_f32 v141, v141, s43, v153
	v_fma_f32 v142, v142, s43, v154
	v_fma_f32 v143, v143, s43, v155
	v_cvt_pk_bf16_f32 v144, v136, v137
	v_cvt_pk_bf16_f32 v145, v138, v139
	v_cvt_pk_bf16_f32 v146, v140, v141
	v_cvt_pk_bf16_f32 v147, v142, v143
	global_store_dwordx4 v2, v[144:147], s[18:19] sc1
	s_add_u32 s18, s18, 0x20000
	s_addc_u32 s19, s19, 0
	v_lshlrev_b32_e32 v148, 16, v56
	v_and_b32_e32 v149, 0xffff0000, v56
	v_lshlrev_b32_e32 v150, 16, v57
	v_and_b32_e32 v151, 0xffff0000, v57
	v_lshlrev_b32_e32 v152, 16, v58
	v_and_b32_e32 v153, 0xffff0000, v58
	v_lshlrev_b32_e32 v154, 16, v59
	v_and_b32_e32 v155, 0xffff0000, v59
	v_fma_f32 v136, v136, s44, v148
	v_fma_f32 v137, v137, s44, v149
	v_fma_f32 v138, v138, s44, v150
	v_fma_f32 v139, v139, s44, v151
	v_fma_f32 v140, v140, s44, v152
	v_fma_f32 v141, v141, s44, v153
	v_fma_f32 v142, v142, s44, v154
	v_fma_f32 v143, v143, s44, v155
	v_cvt_pk_bf16_f32 v144, v136, v137
	v_cvt_pk_bf16_f32 v145, v138, v139
	v_cvt_pk_bf16_f32 v146, v140, v141
	v_cvt_pk_bf16_f32 v147, v142, v143
	global_store_dwordx4 v2, v[144:147], s[18:19] sc1
	s_add_u32 s18, s18, 0x20000
	s_addc_u32 s19, s19, 0
	v_lshlrev_b32_e32 v148, 16, v60
	v_and_b32_e32 v149, 0xffff0000, v60
	v_lshlrev_b32_e32 v150, 16, v61
	v_and_b32_e32 v151, 0xffff0000, v61
	v_lshlrev_b32_e32 v152, 16, v62
	v_and_b32_e32 v153, 0xffff0000, v62
	v_lshlrev_b32_e32 v154, 16, v63
	v_and_b32_e32 v155, 0xffff0000, v63
	v_fma_f32 v136, v136, s45, v148
	v_fma_f32 v137, v137, s45, v149
	v_fma_f32 v138, v138, s45, v150
	v_fma_f32 v139, v139, s45, v151
	v_fma_f32 v140, v140, s45, v152
	v_fma_f32 v141, v141, s45, v153
	v_fma_f32 v142, v142, s45, v154
	v_fma_f32 v143, v143, s45, v155
	v_cvt_pk_bf16_f32 v144, v136, v137
	v_cvt_pk_bf16_f32 v145, v138, v139
	v_cvt_pk_bf16_f32 v146, v140, v141
	v_cvt_pk_bf16_f32 v147, v142, v143
	global_store_dwordx4 v2, v[144:147], s[18:19] sc1
	s_add_u32 s18, s18, 0x20000
	s_addc_u32 s19, s19, 0
	v_lshlrev_b32_e32 v148, 16, v64
	v_and_b32_e32 v149, 0xffff0000, v64
	v_lshlrev_b32_e32 v150, 16, v65
	v_and_b32_e32 v151, 0xffff0000, v65
	v_lshlrev_b32_e32 v152, 16, v66
	v_and_b32_e32 v153, 0xffff0000, v66
	v_lshlrev_b32_e32 v154, 16, v67
	v_and_b32_e32 v155, 0xffff0000, v67
	v_fma_f32 v136, v136, s46, v148
	v_fma_f32 v137, v137, s46, v149
	v_fma_f32 v138, v138, s46, v150
	v_fma_f32 v139, v139, s46, v151
	v_fma_f32 v140, v140, s46, v152
	v_fma_f32 v141, v141, s46, v153
	v_fma_f32 v142, v142, s46, v154
	v_fma_f32 v143, v143, s46, v155
	v_cvt_pk_bf16_f32 v144, v136, v137
	v_cvt_pk_bf16_f32 v145, v138, v139
	v_cvt_pk_bf16_f32 v146, v140, v141
	v_cvt_pk_bf16_f32 v147, v142, v143
	global_store_dwordx4 v2, v[144:147], s[18:19] sc1
	s_add_u32 s18, s18, 0x20000
	s_addc_u32 s19, s19, 0
	v_lshlrev_b32_e32 v148, 16, v68
	v_and_b32_e32 v149, 0xffff0000, v68
	v_lshlrev_b32_e32 v150, 16, v69
	v_and_b32_e32 v151, 0xffff0000, v69
	v_lshlrev_b32_e32 v152, 16, v70
	v_and_b32_e32 v153, 0xffff0000, v70
	v_lshlrev_b32_e32 v154, 16, v71
	v_and_b32_e32 v155, 0xffff0000, v71
	v_fma_f32 v136, v136, s47, v148
	v_fma_f32 v137, v137, s47, v149
	v_fma_f32 v138, v138, s47, v150
	v_fma_f32 v139, v139, s47, v151
	v_fma_f32 v140, v140, s47, v152
	v_fma_f32 v141, v141, s47, v153
	v_fma_f32 v142, v142, s47, v154
	v_fma_f32 v143, v143, s47, v155
	global_load_dwordx4 v[40:43], v2, s[16:17]
	s_add_u32 s16, s16, 0x20000
	s_addc_u32 s17, s17, 0
	global_load_dwordx4 v[44:47], v2, s[16:17]
	s_add_u32 s16, s16, 0x20000
	s_addc_u32 s17, s17, 0
	global_load_dwordx4 v[48:51], v2, s[16:17]
	s_add_u32 s16, s16, 0x20000
	s_addc_u32 s17, s17, 0
	global_load_dwordx4 v[52:55], v2, s[16:17]
	s_add_u32 s16, s16, 0x20000
	s_addc_u32 s17, s17, 0
	global_load_dwordx4 v[56:59], v2, s[16:17]
	s_add_u32 s16, s16, 0x20000
	s_addc_u32 s17, s17, 0
	global_load_dwordx4 v[60:63], v2, s[16:17]
	s_add_u32 s16, s16, 0x20000
	s_addc_u32 s17, s17, 0
	global_load_dwordx4 v[64:67], v2, s[16:17]
	s_add_u32 s16, s16, 0x20000
	s_addc_u32 s17, s17, 0
	global_load_dwordx4 v[68:71], v2, s[16:17]
	s_add_u32 s16, s16, 0x20000
	s_addc_u32 s17, s17, 0
	s_load_dword s40, s[24:25], 0x0
	s_load_dword s41, s[24:25], 0x20
	s_load_dword s42, s[24:25], 0x40
	s_load_dword s43, s[24:25], 0x60
	s_load_dword s44, s[24:25], 0x80
	s_load_dword s45, s[24:25], 0xa0
	s_load_dword s46, s[24:25], 0xc0
	s_load_dword s47, s[24:25], 0xe0
	s_add_u32 s24, s24, 0x100
	s_addc_u32 s25, s25, 0
	s_waitcnt vmcnt(40) lgkmcnt(0)
	v_cvt_pk_bf16_f32 v144, v136, v137
	v_cvt_pk_bf16_f32 v145, v138, v139
	v_cvt_pk_bf16_f32 v146, v140, v141
	v_cvt_pk_bf16_f32 v147, v142, v143
	global_store_dwordx4 v2, v[144:147], s[18:19] sc1
	s_add_u32 s18, s18, 0x20000
	s_addc_u32 s19, s19, 0
	v_lshlrev_b32_e32 v148, 16, v72
	v_and_b32_e32 v149, 0xffff0000, v72
	v_lshlrev_b32_e32 v150, 16, v73
	v_and_b32_e32 v151, 0xffff0000, v73
	v_lshlrev_b32_e32 v152, 16, v74
	v_and_b32_e32 v153, 0xffff0000, v74
	v_lshlrev_b32_e32 v154, 16, v75
	v_and_b32_e32 v155, 0xffff0000, v75
	v_fma_f32 v136, v136, s48, v148
	v_fma_f32 v137, v137, s48, v149
	v_fma_f32 v138, v138, s48, v150
	v_fma_f32 v139, v139, s48, v151
	v_fma_f32 v140, v140, s48, v152
	v_fma_f32 v141, v141, s48, v153
	v_fma_f32 v142, v142, s48, v154
	v_fma_f32 v143, v143, s48, v155
	v_cvt_pk_bf16_f32 v144, v136, v137
	v_cvt_pk_bf16_f32 v145, v138, v139
	v_cvt_pk_bf16_f32 v146, v140, v141
	v_cvt_pk_bf16_f32 v147, v142, v143
	global_store_dwordx4 v2, v[144:147], s[18:19] sc1
	s_add_u32 s18, s18, 0x20000
	s_addc_u32 s19, s19, 0
	v_lshlrev_b32_e32 v148, 16, v76
	v_and_b32_e32 v149, 0xffff0000, v76
	v_lshlrev_b32_e32 v150, 16, v77
	v_and_b32_e32 v151, 0xffff0000, v77
	v_lshlrev_b32_e32 v152, 16, v78
	v_and_b32_e32 v153, 0xffff0000, v78
	v_lshlrev_b32_e32 v154, 16, v79
	v_and_b32_e32 v155, 0xffff0000, v79
	v_fma_f32 v136, v136, s49, v148
	v_fma_f32 v137, v137, s49, v149
	v_fma_f32 v138, v138, s49, v150
	v_fma_f32 v139, v139, s49, v151
	v_fma_f32 v140, v140, s49, v152
	v_fma_f32 v141, v141, s49, v153
	v_fma_f32 v142, v142, s49, v154
	v_fma_f32 v143, v143, s49, v155
	v_cvt_pk_bf16_f32 v144, v136, v137
	v_cvt_pk_bf16_f32 v145, v138, v139
	v_cvt_pk_bf16_f32 v146, v140, v141
	v_cvt_pk_bf16_f32 v147, v142, v143
	global_store_dwordx4 v2, v[144:147], s[18:19] sc1
	s_add_u32 s18, s18, 0x20000
	s_addc_u32 s19, s19, 0
	v_lshlrev_b32_e32 v148, 16, v80
	v_and_b32_e32 v149, 0xffff0000, v80
	v_lshlrev_b32_e32 v150, 16, v81
	v_and_b32_e32 v151, 0xffff0000, v81
	v_lshlrev_b32_e32 v152, 16, v82
	v_and_b32_e32 v153, 0xffff0000, v82
	v_lshlrev_b32_e32 v154, 16, v83
	v_and_b32_e32 v155, 0xffff0000, v83
	v_fma_f32 v136, v136, s50, v148
	v_fma_f32 v137, v137, s50, v149
	v_fma_f32 v138, v138, s50, v150
	v_fma_f32 v139, v139, s50, v151
	v_fma_f32 v140, v140, s50, v152
	v_fma_f32 v141, v141, s50, v153
	v_fma_f32 v142, v142, s50, v154
	v_fma_f32 v143, v143, s50, v155
	v_cvt_pk_bf16_f32 v144, v136, v137
	v_cvt_pk_bf16_f32 v145, v138, v139
	v_cvt_pk_bf16_f32 v146, v140, v141
	v_cvt_pk_bf16_f32 v147, v142, v143
	global_store_dwordx4 v2, v[144:147], s[18:19] sc1
	s_add_u32 s18, s18, 0x20000
	s_addc_u32 s19, s19, 0
	v_lshlrev_b32_e32 v148, 16, v84
	v_and_b32_e32 v149, 0xffff0000, v84
	v_lshlrev_b32_e32 v150, 16, v85
	v_and_b32_e32 v151, 0xffff0000, v85
	v_lshlrev_b32_e32 v152, 16, v86
	v_and_b32_e32 v153, 0xffff0000, v86
	v_lshlrev_b32_e32 v154, 16, v87
	v_and_b32_e32 v155, 0xffff0000, v87
	v_fma_f32 v136, v136, s51, v148
	v_fma_f32 v137, v137, s51, v149
	v_fma_f32 v138, v138, s51, v150
	v_fma_f32 v139, v139, s51, v151
	v_fma_f32 v140, v140, s51, v152
	v_fma_f32 v141, v141, s51, v153
	v_fma_f32 v142, v142, s51, v154
	v_fma_f32 v143, v143, s51, v155
	v_cvt_pk_bf16_f32 v144, v136, v137
	v_cvt_pk_bf16_f32 v145, v138, v139
	v_cvt_pk_bf16_f32 v146, v140, v141
	v_cvt_pk_bf16_f32 v147, v142, v143
	global_store_dwordx4 v2, v[144:147], s[18:19] sc1
	s_add_u32 s18, s18, 0x20000
	s_addc_u32 s19, s19, 0
	v_lshlrev_b32_e32 v148, 16, v88
	v_and_b32_e32 v149, 0xffff0000, v88
	v_lshlrev_b32_e32 v150, 16, v89
	v_and_b32_e32 v151, 0xffff0000, v89
	v_lshlrev_b32_e32 v152, 16, v90
	v_and_b32_e32 v153, 0xffff0000, v90
	v_lshlrev_b32_e32 v154, 16, v91
	v_and_b32_e32 v155, 0xffff0000, v91
	v_fma_f32 v136, v136, s52, v148
	v_fma_f32 v137, v137, s52, v149
	v_fma_f32 v138, v138, s52, v150
	v_fma_f32 v139, v139, s52, v151
	v_fma_f32 v140, v140, s52, v152
	v_fma_f32 v141, v141, s52, v153
	v_fma_f32 v142, v142, s52, v154
	v_fma_f32 v143, v143, s52, v155
	v_cvt_pk_bf16_f32 v144, v136, v137
	v_cvt_pk_bf16_f32 v145, v138, v139
	v_cvt_pk_bf16_f32 v146, v140, v141
	v_cvt_pk_bf16_f32 v147, v142, v143
	global_store_dwordx4 v2, v[144:147], s[18:19] sc1
	s_add_u32 s18, s18, 0x20000
	s_addc_u32 s19, s19, 0
	v_lshlrev_b32_e32 v148, 16, v92
	v_and_b32_e32 v149, 0xffff0000, v92
	v_lshlrev_b32_e32 v150, 16, v93
	v_and_b32_e32 v151, 0xffff0000, v93
	v_lshlrev_b32_e32 v152, 16, v94
	v_and_b32_e32 v153, 0xffff0000, v94
	v_lshlrev_b32_e32 v154, 16, v95
	v_and_b32_e32 v155, 0xffff0000, v95
	v_fma_f32 v136, v136, s53, v148
	v_fma_f32 v137, v137, s53, v149
	v_fma_f32 v138, v138, s53, v150
	v_fma_f32 v139, v139, s53, v151
	v_fma_f32 v140, v140, s53, v152
	v_fma_f32 v141, v141, s53, v153
	v_fma_f32 v142, v142, s53, v154
	v_fma_f32 v143, v143, s53, v155
	v_cvt_pk_bf16_f32 v144, v136, v137
	v_cvt_pk_bf16_f32 v145, v138, v139
	v_cvt_pk_bf16_f32 v146, v140, v141
	v_cvt_pk_bf16_f32 v147, v142, v143
	global_store_dwordx4 v2, v[144:147], s[18:19] sc1
	s_add_u32 s18, s18, 0x20000
	s_addc_u32 s19, s19, 0
	v_lshlrev_b32_e32 v148, 16, v96
	v_and_b32_e32 v149, 0xffff0000, v96
	v_lshlrev_b32_e32 v150, 16, v97
	v_and_b32_e32 v151, 0xffff0000, v97
	v_lshlrev_b32_e32 v152, 16, v98
	v_and_b32_e32 v153, 0xffff0000, v98
	v_lshlrev_b32_e32 v154, 16, v99
	v_and_b32_e32 v155, 0xffff0000, v99
	v_fma_f32 v136, v136, s54, v148
	v_fma_f32 v137, v137, s54, v149
	v_fma_f32 v138, v138, s54, v150
	v_fma_f32 v139, v139, s54, v151
	v_fma_f32 v140, v140, s54, v152
	v_fma_f32 v141, v141, s54, v153
	v_fma_f32 v142, v142, s54, v154
	v_fma_f32 v143, v143, s54, v155
	v_cvt_pk_bf16_f32 v144, v136, v137
	v_cvt_pk_bf16_f32 v145, v138, v139
	v_cvt_pk_bf16_f32 v146, v140, v141
	v_cvt_pk_bf16_f32 v147, v142, v143
	global_store_dwordx4 v2, v[144:147], s[18:19] sc1
	s_add_u32 s18, s18, 0x20000
	s_addc_u32 s19, s19, 0
	v_lshlrev_b32_e32 v148, 16, v100
	v_and_b32_e32 v149, 0xffff0000, v100
	v_lshlrev_b32_e32 v150, 16, v101
	v_and_b32_e32 v151, 0xffff0000, v101
	v_lshlrev_b32_e32 v152, 16, v102
	v_and_b32_e32 v153, 0xffff0000, v102
	v_lshlrev_b32_e32 v154, 16, v103
	v_and_b32_e32 v155, 0xffff0000, v103
	v_fma_f32 v136, v136, s55, v148
	v_fma_f32 v137, v137, s55, v149
	v_fma_f32 v138, v138, s55, v150
	v_fma_f32 v139, v139, s55, v151
	v_fma_f32 v140, v140, s55, v152
	v_fma_f32 v141, v141, s55, v153
	v_fma_f32 v142, v142, s55, v154
	v_fma_f32 v143, v143, s55, v155
	global_load_dwordx4 v[72:75], v2, s[16:17]
	s_add_u32 s16, s16, 0x20000
	s_addc_u32 s17, s17, 0
	global_load_dwordx4 v[76:79], v2, s[16:17]
	s_add_u32 s16, s16, 0x20000
	s_addc_u32 s17, s17, 0
	global_load_dwordx4 v[80:83], v2, s[16:17]
	s_add_u32 s16, s16, 0x20000
	s_addc_u32 s17, s17, 0
	global_load_dwordx4 v[84:87], v2, s[16:17]
	s_add_u32 s16, s16, 0x20000
	s_addc_u32 s17, s17, 0
	global_load_dwordx4 v[88:91], v2, s[16:17]
	s_add_u32 s16, s16, 0x20000
	s_addc_u32 s17, s17, 0
	global_load_dwordx4 v[92:95], v2, s[16:17]
	s_add_u32 s16, s16, 0x20000
	s_addc_u32 s17, s17, 0
	global_load_dwordx4 v[96:99], v2, s[16:17]
	s_add_u32 s16, s16, 0x20000
	s_addc_u32 s17, s17, 0
	global_load_dwordx4 v[100:103], v2, s[16:17]
	s_add_u32 s16, s16, 0x20000
	s_addc_u32 s17, s17, 0
	s_load_dword s48, s[24:25], 0x0
	s_load_dword s49, s[24:25], 0x20
	s_load_dword s50, s[24:25], 0x40
	s_load_dword s51, s[24:25], 0x60
	s_load_dword s52, s[24:25], 0x80
	s_load_dword s53, s[24:25], 0xa0
	s_load_dword s54, s[24:25], 0xc0
	s_load_dword s55, s[24:25], 0xe0
	s_add_u32 s24, s24, 0x100
	s_addc_u32 s25, s25, 0
	s_waitcnt vmcnt(48) lgkmcnt(0)
	v_cvt_pk_bf16_f32 v144, v136, v137
	v_cvt_pk_bf16_f32 v145, v138, v139
	v_cvt_pk_bf16_f32 v146, v140, v141
	v_cvt_pk_bf16_f32 v147, v142, v143
	global_store_dwordx4 v2, v[144:147], s[18:19] sc1
	s_add_u32 s18, s18, 0x20000
	s_addc_u32 s19, s19, 0
	v_lshlrev_b32_e32 v148, 16, v104
	v_and_b32_e32 v149, 0xffff0000, v104
	v_lshlrev_b32_e32 v150, 16, v105
	v_and_b32_e32 v151, 0xffff0000, v105
	v_lshlrev_b32_e32 v152, 16, v106
	v_and_b32_e32 v153, 0xffff0000, v106
	v_lshlrev_b32_e32 v154, 16, v107
	v_and_b32_e32 v155, 0xffff0000, v107
	v_fma_f32 v136, v136, s56, v148
	v_fma_f32 v137, v137, s56, v149
	v_fma_f32 v138, v138, s56, v150
	v_fma_f32 v139, v139, s56, v151
	v_fma_f32 v140, v140, s56, v152
	v_fma_f32 v141, v141, s56, v153
	v_fma_f32 v142, v142, s56, v154
	v_fma_f32 v143, v143, s56, v155
	v_cvt_pk_bf16_f32 v144, v136, v137
	v_cvt_pk_bf16_f32 v145, v138, v139
	v_cvt_pk_bf16_f32 v146, v140, v141
	v_cvt_pk_bf16_f32 v147, v142, v143
	global_store_dwordx4 v2, v[144:147], s[18:19] sc1
	s_add_u32 s18, s18, 0x20000
	s_addc_u32 s19, s19, 0
	v_lshlrev_b32_e32 v148, 16, v108
	v_and_b32_e32 v149, 0xffff0000, v108
	v_lshlrev_b32_e32 v150, 16, v109
	v_and_b32_e32 v151, 0xffff0000, v109
	v_lshlrev_b32_e32 v152, 16, v110
	v_and_b32_e32 v153, 0xffff0000, v110
	v_lshlrev_b32_e32 v154, 16, v111
	v_and_b32_e32 v155, 0xffff0000, v111
	v_fma_f32 v136, v136, s57, v148
	v_fma_f32 v137, v137, s57, v149
	v_fma_f32 v138, v138, s57, v150
	v_fma_f32 v139, v139, s57, v151
	v_fma_f32 v140, v140, s57, v152
	v_fma_f32 v141, v141, s57, v153
	v_fma_f32 v142, v142, s57, v154
	v_fma_f32 v143, v143, s57, v155
	v_cvt_pk_bf16_f32 v144, v136, v137
	v_cvt_pk_bf16_f32 v145, v138, v139
	v_cvt_pk_bf16_f32 v146, v140, v141
	v_cvt_pk_bf16_f32 v147, v142, v143
	global_store_dwordx4 v2, v[144:147], s[18:19] sc1
	s_add_u32 s18, s18, 0x20000
	s_addc_u32 s19, s19, 0
	v_lshlrev_b32_e32 v148, 16, v112
	v_and_b32_e32 v149, 0xffff0000, v112
	v_lshlrev_b32_e32 v150, 16, v113
	v_and_b32_e32 v151, 0xffff0000, v113
	v_lshlrev_b32_e32 v152, 16, v114
	v_and_b32_e32 v153, 0xffff0000, v114
	v_lshlrev_b32_e32 v154, 16, v115
	v_and_b32_e32 v155, 0xffff0000, v115
	v_fma_f32 v136, v136, s58, v148
	v_fma_f32 v137, v137, s58, v149
	v_fma_f32 v138, v138, s58, v150
	v_fma_f32 v139, v139, s58, v151
	v_fma_f32 v140, v140, s58, v152
	v_fma_f32 v141, v141, s58, v153
	v_fma_f32 v142, v142, s58, v154
	v_fma_f32 v143, v143, s58, v155
	v_cvt_pk_bf16_f32 v144, v136, v137
	v_cvt_pk_bf16_f32 v145, v138, v139
	v_cvt_pk_bf16_f32 v146, v140, v141
	v_cvt_pk_bf16_f32 v147, v142, v143
	global_store_dwordx4 v2, v[144:147], s[18:19] sc1
	s_add_u32 s18, s18, 0x20000
	s_addc_u32 s19, s19, 0
	v_lshlrev_b32_e32 v148, 16, v116
	v_and_b32_e32 v149, 0xffff0000, v116
	v_lshlrev_b32_e32 v150, 16, v117
	v_and_b32_e32 v151, 0xffff0000, v117
	v_lshlrev_b32_e32 v152, 16, v118
	v_and_b32_e32 v153, 0xffff0000, v118
	v_lshlrev_b32_e32 v154, 16, v119
	v_and_b32_e32 v155, 0xffff0000, v119
	v_fma_f32 v136, v136, s59, v148
	v_fma_f32 v137, v137, s59, v149
	v_fma_f32 v138, v138, s59, v150
	v_fma_f32 v139, v139, s59, v151
	v_fma_f32 v140, v140, s59, v152
	v_fma_f32 v141, v141, s59, v153
	v_fma_f32 v142, v142, s59, v154
	v_fma_f32 v143, v143, s59, v155
	v_cvt_pk_bf16_f32 v144, v136, v137
	v_cvt_pk_bf16_f32 v145, v138, v139
	v_cvt_pk_bf16_f32 v146, v140, v141
	v_cvt_pk_bf16_f32 v147, v142, v143
	global_store_dwordx4 v2, v[144:147], s[18:19] sc1
	s_add_u32 s18, s18, 0x20000
	s_addc_u32 s19, s19, 0
	v_lshlrev_b32_e32 v148, 16, v120
	v_and_b32_e32 v149, 0xffff0000, v120
	v_lshlrev_b32_e32 v150, 16, v121
	v_and_b32_e32 v151, 0xffff0000, v121
	v_lshlrev_b32_e32 v152, 16, v122
	v_and_b32_e32 v153, 0xffff0000, v122
	v_lshlrev_b32_e32 v154, 16, v123
	v_and_b32_e32 v155, 0xffff0000, v123
	v_fma_f32 v136, v136, s60, v148
	v_fma_f32 v137, v137, s60, v149
	v_fma_f32 v138, v138, s60, v150
	v_fma_f32 v139, v139, s60, v151
	v_fma_f32 v140, v140, s60, v152
	v_fma_f32 v141, v141, s60, v153
	v_fma_f32 v142, v142, s60, v154
	v_fma_f32 v143, v143, s60, v155
	v_cvt_pk_bf16_f32 v144, v136, v137
	v_cvt_pk_bf16_f32 v145, v138, v139
	v_cvt_pk_bf16_f32 v146, v140, v141
	v_cvt_pk_bf16_f32 v147, v142, v143
	global_store_dwordx4 v2, v[144:147], s[18:19] sc1
	s_add_u32 s18, s18, 0x20000
	s_addc_u32 s19, s19, 0
	v_lshlrev_b32_e32 v148, 16, v124
	v_and_b32_e32 v149, 0xffff0000, v124
	v_lshlrev_b32_e32 v150, 16, v125
	v_and_b32_e32 v151, 0xffff0000, v125
	v_lshlrev_b32_e32 v152, 16, v126
	v_and_b32_e32 v153, 0xffff0000, v126
	v_lshlrev_b32_e32 v154, 16, v127
	v_and_b32_e32 v155, 0xffff0000, v127
	v_fma_f32 v136, v136, s61, v148
	v_fma_f32 v137, v137, s61, v149
	v_fma_f32 v138, v138, s61, v150
	v_fma_f32 v139, v139, s61, v151
	v_fma_f32 v140, v140, s61, v152
	v_fma_f32 v141, v141, s61, v153
	v_fma_f32 v142, v142, s61, v154
	v_fma_f32 v143, v143, s61, v155
	v_cvt_pk_bf16_f32 v144, v136, v137
	v_cvt_pk_bf16_f32 v145, v138, v139
	v_cvt_pk_bf16_f32 v146, v140, v141
	v_cvt_pk_bf16_f32 v147, v142, v143
	global_store_dwordx4 v2, v[144:147], s[18:19] sc1
	s_add_u32 s18, s18, 0x20000
	s_addc_u32 s19, s19, 0
	v_lshlrev_b32_e32 v148, 16, v128
	v_and_b32_e32 v149, 0xffff0000, v128
	v_lshlrev_b32_e32 v150, 16, v129
	v_and_b32_e32 v151, 0xffff0000, v129
	v_lshlrev_b32_e32 v152, 16, v130
	v_and_b32_e32 v153, 0xffff0000, v130
	v_lshlrev_b32_e32 v154, 16, v131
	v_and_b32_e32 v155, 0xffff0000, v131
	v_fma_f32 v136, v136, s62, v148
	v_fma_f32 v137, v137, s62, v149
	v_fma_f32 v138, v138, s62, v150
	v_fma_f32 v139, v139, s62, v151
	v_fma_f32 v140, v140, s62, v152
	v_fma_f32 v141, v141, s62, v153
	v_fma_f32 v142, v142, s62, v154
	v_fma_f32 v143, v143, s62, v155
	v_cvt_pk_bf16_f32 v144, v136, v137
	v_cvt_pk_bf16_f32 v145, v138, v139
	v_cvt_pk_bf16_f32 v146, v140, v141
	v_cvt_pk_bf16_f32 v147, v142, v143
	global_store_dwordx4 v2, v[144:147], s[18:19] sc1
	s_add_u32 s18, s18, 0x20000
	s_addc_u32 s19, s19, 0
	v_lshlrev_b32_e32 v148, 16, v132
	v_and_b32_e32 v149, 0xffff0000, v132
	v_lshlrev_b32_e32 v150, 16, v133
	v_and_b32_e32 v151, 0xffff0000, v133
	v_lshlrev_b32_e32 v152, 16, v134
	v_and_b32_e32 v153, 0xffff0000, v134
	v_lshlrev_b32_e32 v154, 16, v135
	v_and_b32_e32 v155, 0xffff0000, v135
	v_fma_f32 v136, v136, s63, v148
	v_fma_f32 v137, v137, s63, v149
	v_fma_f32 v138, v138, s63, v150
	v_fma_f32 v139, v139, s63, v151
	v_fma_f32 v140, v140, s63, v152
	v_fma_f32 v141, v141, s63, v153
	v_fma_f32 v142, v142, s63, v154
	v_fma_f32 v143, v143, s63, v155
	global_load_dwordx4 v[104:107], v2, s[16:17]
	s_add_u32 s16, s16, 0x20000
	s_addc_u32 s17, s17, 0
	global_load_dwordx4 v[108:111], v2, s[16:17]
	s_add_u32 s16, s16, 0x20000
	s_addc_u32 s17, s17, 0
	global_load_dwordx4 v[112:115], v2, s[16:17]
	s_add_u32 s16, s16, 0x20000
	s_addc_u32 s17, s17, 0
	global_load_dwordx4 v[116:119], v2, s[16:17]
	s_add_u32 s16, s16, 0x20000
	s_addc_u32 s17, s17, 0
	global_load_dwordx4 v[120:123], v2, s[16:17]
	s_add_u32 s16, s16, 0x20000
	s_addc_u32 s17, s17, 0
	global_load_dwordx4 v[124:127], v2, s[16:17]
	s_add_u32 s16, s16, 0x20000
	s_addc_u32 s17, s17, 0
	global_load_dwordx4 v[128:131], v2, s[16:17]
	s_add_u32 s16, s16, 0x20000
	s_addc_u32 s17, s17, 0
	global_load_dwordx4 v[132:135], v2, s[16:17]
	s_add_u32 s16, s16, 0x20000
	s_addc_u32 s17, s17, 0
	s_load_dword s56, s[24:25], 0x0
	s_load_dword s57, s[24:25], 0x20
	s_load_dword s58, s[24:25], 0x40
	s_load_dword s59, s[24:25], 0x60
	s_load_dword s60, s[24:25], 0x80
	s_load_dword s61, s[24:25], 0xa0
	s_load_dword s62, s[24:25], 0xc0
	s_load_dword s63, s[24:25], 0xe0
	s_add_u32 s24, s24, 0x100
	s_addc_u32 s25, s25, 0
	s_mov_b32 s22, 6
.Lp3_ssd_loop:
	s_waitcnt vmcnt(48) lgkmcnt(0)
	v_cvt_pk_bf16_f32 v144, v136, v137
	v_cvt_pk_bf16_f32 v145, v138, v139
	v_cvt_pk_bf16_f32 v146, v140, v141
	v_cvt_pk_bf16_f32 v147, v142, v143
	global_store_dwordx4 v2, v[144:147], s[18:19] sc1
	s_add_u32 s18, s18, 0x20000
	s_addc_u32 s19, s19, 0
	v_lshlrev_b32_e32 v148, 16, v8
	v_and_b32_e32 v149, 0xffff0000, v8
	v_lshlrev_b32_e32 v150, 16, v9
	v_and_b32_e32 v151, 0xffff0000, v9
	v_lshlrev_b32_e32 v152, 16, v10
	v_and_b32_e32 v153, 0xffff0000, v10
	v_lshlrev_b32_e32 v154, 16, v11
	v_and_b32_e32 v155, 0xffff0000, v11
	v_fma_f32 v136, v136, s32, v148
	v_fma_f32 v137, v137, s32, v149
	v_fma_f32 v138, v138, s32, v150
	v_fma_f32 v139, v139, s32, v151
	v_fma_f32 v140, v140, s32, v152
	v_fma_f32 v141, v141, s32, v153
	v_fma_f32 v142, v142, s32, v154
	v_fma_f32 v143, v143, s32, v155
	v_cvt_pk_bf16_f32 v144, v136, v137
	v_cvt_pk_bf16_f32 v145, v138, v139
	v_cvt_pk_bf16_f32 v146, v140, v141
	v_cvt_pk_bf16_f32 v147, v142, v143
	global_store_dwordx4 v2, v[144:147], s[18:19] sc1
	s_add_u32 s18, s18, 0x20000
	s_addc_u32 s19, s19, 0
	v_lshlrev_b32_e32 v148, 16, v12
	v_and_b32_e32 v149, 0xffff0000, v12
	v_lshlrev_b32_e32 v150, 16, v13
	v_and_b32_e32 v151, 0xffff0000, v13
	v_lshlrev_b32_e32 v152, 16, v14
	v_and_b32_e32 v153, 0xffff0000, v14
	v_lshlrev_b32_e32 v154, 16, v15
	v_and_b32_e32 v155, 0xffff0000, v15
	v_fma_f32 v136, v136, s33, v148
	v_fma_f32 v137, v137, s33, v149
	v_fma_f32 v138, v138, s33, v150
	v_fma_f32 v139, v139, s33, v151
	v_fma_f32 v140, v140, s33, v152
	v_fma_f32 v141, v141, s33, v153
	v_fma_f32 v142, v142, s33, v154
	v_fma_f32 v143, v143, s33, v155
	v_cvt_pk_bf16_f32 v144, v136, v137
	v_cvt_pk_bf16_f32 v145, v138, v139
	v_cvt_pk_bf16_f32 v146, v140, v141
	v_cvt_pk_bf16_f32 v147, v142, v143
	global_store_dwordx4 v2, v[144:147], s[18:19] sc1
	s_add_u32 s18, s18, 0x20000
	s_addc_u32 s19, s19, 0
	v_lshlrev_b32_e32 v148, 16, v16
	v_and_b32_e32 v149, 0xffff0000, v16
	v_lshlrev_b32_e32 v150, 16, v17
	v_and_b32_e32 v151, 0xffff0000, v17
	v_lshlrev_b32_e32 v152, 16, v18
	v_and_b32_e32 v153, 0xffff0000, v18
	v_lshlrev_b32_e32 v154, 16, v19
	v_and_b32_e32 v155, 0xffff0000, v19
	v_fma_f32 v136, v136, s34, v148
	v_fma_f32 v137, v137, s34, v149
	v_fma_f32 v138, v138, s34, v150
	v_fma_f32 v139, v139, s34, v151
	v_fma_f32 v140, v140, s34, v152
	v_fma_f32 v141, v141, s34, v153
	v_fma_f32 v142, v142, s34, v154
	v_fma_f32 v143, v143, s34, v155
	v_cvt_pk_bf16_f32 v144, v136, v137
	v_cvt_pk_bf16_f32 v145, v138, v139
	v_cvt_pk_bf16_f32 v146, v140, v141
	v_cvt_pk_bf16_f32 v147, v142, v143
	global_store_dwordx4 v2, v[144:147], s[18:19] sc1
	s_add_u32 s18, s18, 0x20000
	s_addc_u32 s19, s19, 0
	v_lshlrev_b32_e32 v148, 16, v20
	v_and_b32_e32 v149, 0xffff0000, v20
	v_lshlrev_b32_e32 v150, 16, v21
	v_and_b32_e32 v151, 0xffff0000, v21
	v_lshlrev_b32_e32 v152, 16, v22
	v_and_b32_e32 v153, 0xffff0000, v22
	v_lshlrev_b32_e32 v154, 16, v23
	v_and_b32_e32 v155, 0xffff0000, v23
	v_fma_f32 v136, v136, s35, v148
	v_fma_f32 v137, v137, s35, v149
	v_fma_f32 v138, v138, s35, v150
	v_fma_f32 v139, v139, s35, v151
	v_fma_f32 v140, v140, s35, v152
	v_fma_f32 v141, v141, s35, v153
	v_fma_f32 v142, v142, s35, v154
	v_fma_f32 v143, v143, s35, v155
	v_cvt_pk_bf16_f32 v144, v136, v137
	v_cvt_pk_bf16_f32 v145, v138, v139
	v_cvt_pk_bf16_f32 v146, v140, v141
	v_cvt_pk_bf16_f32 v147, v142, v143
	global_store_dwordx4 v2, v[144:147], s[18:19] sc1
	s_add_u32 s18, s18, 0x20000
	s_addc_u32 s19, s19, 0
	v_lshlrev_b32_e32 v148, 16, v24
	v_and_b32_e32 v149, 0xffff0000, v24
	v_lshlrev_b32_e32 v150, 16, v25
	v_and_b32_e32 v151, 0xffff0000, v25
	v_lshlrev_b32_e32 v152, 16, v26
	v_and_b32_e32 v153, 0xffff0000, v26
	v_lshlrev_b32_e32 v154, 16, v27
	v_and_b32_e32 v155, 0xffff0000, v27
	v_fma_f32 v136, v136, s36, v148
	v_fma_f32 v137, v137, s36, v149
	v_fma_f32 v138, v138, s36, v150
	v_fma_f32 v139, v139, s36, v151
	v_fma_f32 v140, v140, s36, v152
	v_fma_f32 v141, v141, s36, v153
	v_fma_f32 v142, v142, s36, v154
	v_fma_f32 v143, v143, s36, v155
	v_cvt_pk_bf16_f32 v144, v136, v137
	v_cvt_pk_bf16_f32 v145, v138, v139
	v_cvt_pk_bf16_f32 v146, v140, v141
	v_cvt_pk_bf16_f32 v147, v142, v143
	global_store_dwordx4 v2, v[144:147], s[18:19] sc1
	s_add_u32 s18, s18, 0x20000
	s_addc_u32 s19, s19, 0
	v_lshlrev_b32_e32 v148, 16, v28
	v_and_b32_e32 v149, 0xffff0000, v28
	v_lshlrev_b32_e32 v150, 16, v29
	v_and_b32_e32 v151, 0xffff0000, v29
	v_lshlrev_b32_e32 v152, 16, v30
	v_and_b32_e32 v153, 0xffff0000, v30
	v_lshlrev_b32_e32 v154, 16, v31
	v_and_b32_e32 v155, 0xffff0000, v31
	v_fma_f32 v136, v136, s37, v148
	v_fma_f32 v137, v137, s37, v149
	v_fma_f32 v138, v138, s37, v150
	v_fma_f32 v139, v139, s37, v151
	v_fma_f32 v140, v140, s37, v152
	v_fma_f32 v141, v141, s37, v153
	v_fma_f32 v142, v142, s37, v154
	v_fma_f32 v143, v143, s37, v155
	v_cvt_pk_bf16_f32 v144, v136, v137
	v_cvt_pk_bf16_f32 v145, v138, v139
	v_cvt_pk_bf16_f32 v146, v140, v141
	v_cvt_pk_bf16_f32 v147, v142, v143
	global_store_dwordx4 v2, v[144:147], s[18:19] sc1
	s_add_u32 s18, s18, 0x20000
	s_addc_u32 s19, s19, 0
	v_lshlrev_b32_e32 v148, 16, v32
	v_and_b32_e32 v149, 0xffff0000, v32
	v_lshlrev_b32_e32 v150, 16, v33
	v_and_b32_e32 v151, 0xffff0000, v33
	v_lshlrev_b32_e32 v152, 16, v34
	v_and_b32_e32 v153, 0xffff0000, v34
	v_lshlrev_b32_e32 v154, 16, v35
	v_and_b32_e32 v155, 0xffff0000, v35
	v_fma_f32 v136, v136, s38, v148
	v_fma_f32 v137, v137, s38, v149
	v_fma_f32 v138, v138, s38, v150
	v_fma_f32 v139, v139, s38, v151
	v_fma_f32 v140, v140, s38, v152
	v_fma_f32 v141, v141, s38, v153
	v_fma_f32 v142, v142, s38, v154
	v_fma_f32 v143, v143, s38, v155
	v_cvt_pk_bf16_f32 v144, v136, v137
	v_cvt_pk_bf16_f32 v145, v138, v139
	v_cvt_pk_bf16_f32 v146, v140, v141
	v_cvt_pk_bf16_f32 v147, v142, v143
	global_store_dwordx4 v2, v[144:147], s[18:19] sc1
	s_add_u32 s18, s18, 0x20000
	s_addc_u32 s19, s19, 0
	v_lshlrev_b32_e32 v148, 16, v36
	v_and_b32_e32 v149, 0xffff0000, v36
	v_lshlrev_b32_e32 v150, 16, v37
	v_and_b32_e32 v151, 0xffff0000, v37
	v_lshlrev_b32_e32 v152, 16, v38
	v_and_b32_e32 v153, 0xffff0000, v38
	v_lshlrev_b32_e32 v154, 16, v39
	v_and_b32_e32 v155, 0xffff0000, v39
	v_fma_f32 v136, v136, s39, v148
	v_fma_f32 v137, v137, s39, v149
	v_fma_f32 v138, v138, s39, v150
	v_fma_f32 v139, v139, s39, v151
	v_fma_f32 v140, v140, s39, v152
	v_fma_f32 v141, v141, s39, v153
	v_fma_f32 v142, v142, s39, v154
	v_fma_f32 v143, v143, s39, v155
	global_load_dwordx4 v[8:11], v2, s[16:17]
	s_add_u32 s16, s16, 0x20000
	s_addc_u32 s17, s17, 0
	global_load_dwordx4 v[12:15], v2, s[16:17]
	s_add_u32 s16, s16, 0x20000
	s_addc_u32 s17, s17, 0
	global_load_dwordx4 v[16:19], v2, s[16:17]
	s_add_u32 s16, s16, 0x20000
	s_addc_u32 s17, s17, 0
	global_load_dwordx4 v[20:23], v2, s[16:17]
	s_add_u32 s16, s16, 0x20000
	s_addc_u32 s17, s17, 0
	global_load_dwordx4 v[24:27], v2, s[16:17]
	s_add_u32 s16, s16, 0x20000
	s_addc_u32 s17, s17, 0
	global_load_dwordx4 v[28:31], v2, s[16:17]
	s_add_u32 s16, s16, 0x20000
	s_addc_u32 s17, s17, 0
	global_load_dwordx4 v[32:35], v2, s[16:17]
	s_add_u32 s16, s16, 0x20000
	s_addc_u32 s17, s17, 0
	global_load_dwordx4 v[36:39], v2, s[16:17]
	s_add_u32 s16, s16, 0x20000
	s_addc_u32 s17, s17, 0
	s_load_dword s32, s[24:25], 0x0
	s_load_dword s33, s[24:25], 0x20
	s_load_dword s34, s[24:25], 0x40
	s_load_dword s35, s[24:25], 0x60
	s_load_dword s36, s[24:25], 0x80
	s_load_dword s37, s[24:25], 0xa0
	s_load_dword s38, s[24:25], 0xc0
	s_load_dword s39, s[24:25], 0xe0
	s_add_u32 s24, s24, 0x100
	s_addc_u32 s25, s25, 0
	s_waitcnt vmcnt(48) lgkmcnt(0)
	v_cvt_pk_bf16_f32 v144, v136, v137
	v_cvt_pk_bf16_f32 v145, v138, v139
	v_cvt_pk_bf16_f32 v146, v140, v141
	v_cvt_pk_bf16_f32 v147, v142, v143
	global_store_dwordx4 v2, v[144:147], s[18:19] sc1
	s_add_u32 s18, s18, 0x20000
	s_addc_u32 s19, s19, 0
	v_lshlrev_b32_e32 v148, 16, v40
	v_and_b32_e32 v149, 0xffff0000, v40
	v_lshlrev_b32_e32 v150, 16, v41
	v_and_b32_e32 v151, 0xffff0000, v41
	v_lshlrev_b32_e32 v152, 16, v42
	v_and_b32_e32 v153, 0xffff0000, v42
	v_lshlrev_b32_e32 v154, 16, v43
	v_and_b32_e32 v155, 0xffff0000, v43
	v_fma_f32 v136, v136, s40, v148
	v_fma_f32 v137, v137, s40, v149
	v_fma_f32 v138, v138, s40, v150
	v_fma_f32 v139, v139, s40, v151
	v_fma_f32 v140, v140, s40, v152
	v_fma_f32 v141, v141, s40, v153
	v_fma_f32 v142, v142, s40, v154
	v_fma_f32 v143, v143, s40, v155
	v_cvt_pk_bf16_f32 v144, v136, v137
	v_cvt_pk_bf16_f32 v145, v138, v139
	v_cvt_pk_bf16_f32 v146, v140, v141
	v_cvt_pk_bf16_f32 v147, v142, v143
	global_store_dwordx4 v2, v[144:147], s[18:19] sc1
	s_add_u32 s18, s18, 0x20000
	s_addc_u32 s19, s19, 0
	v_lshlrev_b32_e32 v148, 16, v44
	v_and_b32_e32 v149, 0xffff0000, v44
	v_lshlrev_b32_e32 v150, 16, v45
	v_and_b32_e32 v151, 0xffff0000, v45
	v_lshlrev_b32_e32 v152, 16, v46
	v_and_b32_e32 v153, 0xffff0000, v46
	v_lshlrev_b32_e32 v154, 16, v47
	v_and_b32_e32 v155, 0xffff0000, v47
	v_fma_f32 v136, v136, s41, v148
	v_fma_f32 v137, v137, s41, v149
	v_fma_f32 v138, v138, s41, v150
	v_fma_f32 v139, v139, s41, v151
	v_fma_f32 v140, v140, s41, v152
	v_fma_f32 v141, v141, s41, v153
	v_fma_f32 v142, v142, s41, v154
	v_fma_f32 v143, v143, s41, v155
	v_cvt_pk_bf16_f32 v144, v136, v137
	v_cvt_pk_bf16_f32 v145, v138, v139
	v_cvt_pk_bf16_f32 v146, v140, v141
	v_cvt_pk_bf16_f32 v147, v142, v143
	global_store_dwordx4 v2, v[144:147], s[18:19] sc1
	s_add_u32 s18, s18, 0x20000
	s_addc_u32 s19, s19, 0
	v_lshlrev_b32_e32 v148, 16, v48
	v_and_b32_e32 v149, 0xffff0000, v48
	v_lshlrev_b32_e32 v150, 16, v49
	v_and_b32_e32 v151, 0xffff0000, v49
	v_lshlrev_b32_e32 v152, 16, v50
	v_and_b32_e32 v153, 0xffff0000, v50
	v_lshlrev_b32_e32 v154, 16, v51
	v_and_b32_e32 v155, 0xffff0000, v51
	v_fma_f32 v136, v136, s42, v148
	v_fma_f32 v137, v137, s42, v149
	v_fma_f32 v138, v138, s42, v150
	v_fma_f32 v139, v139, s42, v151
	v_fma_f32 v140, v140, s42, v152
	v_fma_f32 v141, v141, s42, v153
	v_fma_f32 v142, v142, s42, v154
	v_fma_f32 v143, v143, s42, v155
	v_cvt_pk_bf16_f32 v144, v136, v137
	v_cvt_pk_bf16_f32 v145, v138, v139
	v_cvt_pk_bf16_f32 v146, v140, v141
	v_cvt_pk_bf16_f32 v147, v142, v143
	global_store_dwordx4 v2, v[144:147], s[18:19] sc1
	s_add_u32 s18, s18, 0x20000
	s_addc_u32 s19, s19, 0
	v_lshlrev_b32_e32 v148, 16, v52
	v_and_b32_e32 v149, 0xffff0000, v52
	v_lshlrev_b32_e32 v150, 16, v53
	v_and_b32_e32 v151, 0xffff0000, v53
	v_lshlrev_b32_e32 v152, 16, v54
	v_and_b32_e32 v153, 0xffff0000, v54
	v_lshlrev_b32_e32 v154, 16, v55
	v_and_b32_e32 v155, 0xffff0000, v55
	v_fma_f32 v136, v136, s43, v148
	v_fma_f32 v137, v137, s43, v149
	v_fma_f32 v138, v138, s43, v150
	v_fma_f32 v139, v139, s43, v151
	v_fma_f32 v140, v140, s43, v152
	v_fma_f32 v141, v141, s43, v153
	v_fma_f32 v142, v142, s43, v154
	v_fma_f32 v143, v143, s43, v155
	v_cvt_pk_bf16_f32 v144, v136, v137
	v_cvt_pk_bf16_f32 v145, v138, v139
	v_cvt_pk_bf16_f32 v146, v140, v141
	v_cvt_pk_bf16_f32 v147, v142, v143
	global_store_dwordx4 v2, v[144:147], s[18:19] sc1
	s_add_u32 s18, s18, 0x20000
	s_addc_u32 s19, s19, 0
	v_lshlrev_b32_e32 v148, 16, v56
	v_and_b32_e32 v149, 0xffff0000, v56
	v_lshlrev_b32_e32 v150, 16, v57
	v_and_b32_e32 v151, 0xffff0000, v57
	v_lshlrev_b32_e32 v152, 16, v58
	v_and_b32_e32 v153, 0xffff0000, v58
	v_lshlrev_b32_e32 v154, 16, v59
	v_and_b32_e32 v155, 0xffff0000, v59
	v_fma_f32 v136, v136, s44, v148
	v_fma_f32 v137, v137, s44, v149
	v_fma_f32 v138, v138, s44, v150
	v_fma_f32 v139, v139, s44, v151
	v_fma_f32 v140, v140, s44, v152
	v_fma_f32 v141, v141, s44, v153
	v_fma_f32 v142, v142, s44, v154
	v_fma_f32 v143, v143, s44, v155
	v_cvt_pk_bf16_f32 v144, v136, v137
	v_cvt_pk_bf16_f32 v145, v138, v139
	v_cvt_pk_bf16_f32 v146, v140, v141
	v_cvt_pk_bf16_f32 v147, v142, v143
	global_store_dwordx4 v2, v[144:147], s[18:19] sc1
	s_add_u32 s18, s18, 0x20000
	s_addc_u32 s19, s19, 0
	v_lshlrev_b32_e32 v148, 16, v60
	v_and_b32_e32 v149, 0xffff0000, v60
	v_lshlrev_b32_e32 v150, 16, v61
	v_and_b32_e32 v151, 0xffff0000, v61
	v_lshlrev_b32_e32 v152, 16, v62
	v_and_b32_e32 v153, 0xffff0000, v62
	v_lshlrev_b32_e32 v154, 16, v63
	v_and_b32_e32 v155, 0xffff0000, v63
	v_fma_f32 v136, v136, s45, v148
	v_fma_f32 v137, v137, s45, v149
	v_fma_f32 v138, v138, s45, v150
	v_fma_f32 v139, v139, s45, v151
	v_fma_f32 v140, v140, s45, v152
	v_fma_f32 v141, v141, s45, v153
	v_fma_f32 v142, v142, s45, v154
	v_fma_f32 v143, v143, s45, v155
	v_cvt_pk_bf16_f32 v144, v136, v137
	v_cvt_pk_bf16_f32 v145, v138, v139
	v_cvt_pk_bf16_f32 v146, v140, v141
	v_cvt_pk_bf16_f32 v147, v142, v143
	global_store_dwordx4 v2, v[144:147], s[18:19] sc1
	s_add_u32 s18, s18, 0x20000
	s_addc_u32 s19, s19, 0
	v_lshlrev_b32_e32 v148, 16, v64
	v_and_b32_e32 v149, 0xffff0000, v64
	v_lshlrev_b32_e32 v150, 16, v65
	v_and_b32_e32 v151, 0xffff0000, v65
	v_lshlrev_b32_e32 v152, 16, v66
	v_and_b32_e32 v153, 0xffff0000, v66
	v_lshlrev_b32_e32 v154, 16, v67
	v_and_b32_e32 v155, 0xffff0000, v67
	v_fma_f32 v136, v136, s46, v148
	v_fma_f32 v137, v137, s46, v149
	v_fma_f32 v138, v138, s46, v150
	v_fma_f32 v139, v139, s46, v151
	v_fma_f32 v140, v140, s46, v152
	v_fma_f32 v141, v141, s46, v153
	v_fma_f32 v142, v142, s46, v154
	v_fma_f32 v143, v143, s46, v155
	v_cvt_pk_bf16_f32 v144, v136, v137
	v_cvt_pk_bf16_f32 v145, v138, v139
	v_cvt_pk_bf16_f32 v146, v140, v141
	v_cvt_pk_bf16_f32 v147, v142, v143
	global_store_dwordx4 v2, v[144:147], s[18:19] sc1
	s_add_u32 s18, s18, 0x20000
	s_addc_u32 s19, s19, 0
	v_lshlrev_b32_e32 v148, 16, v68
	v_and_b32_e32 v149, 0xffff0000, v68
	v_lshlrev_b32_e32 v150, 16, v69
	v_and_b32_e32 v151, 0xffff0000, v69
	v_lshlrev_b32_e32 v152, 16, v70
	v_and_b32_e32 v153, 0xffff0000, v70
	v_lshlrev_b32_e32 v154, 16, v71
	v_and_b32_e32 v155, 0xffff0000, v71
	v_fma_f32 v136, v136, s47, v148
	v_fma_f32 v137, v137, s47, v149
	v_fma_f32 v138, v138, s47, v150
	v_fma_f32 v139, v139, s47, v151
	v_fma_f32 v140, v140, s47, v152
	v_fma_f32 v141, v141, s47, v153
	v_fma_f32 v142, v142, s47, v154
	v_fma_f32 v143, v143, s47, v155
	global_load_dwordx4 v[40:43], v2, s[16:17]
	s_add_u32 s16, s16, 0x20000
	s_addc_u32 s17, s17, 0
	global_load_dwordx4 v[44:47], v2, s[16:17]
	s_add_u32 s16, s16, 0x20000
	s_addc_u32 s17, s17, 0
	global_load_dwordx4 v[48:51], v2, s[16:17]
	s_add_u32 s16, s16, 0x20000
	s_addc_u32 s17, s17, 0
	global_load_dwordx4 v[52:55], v2, s[16:17]
	s_add_u32 s16, s16, 0x20000
	s_addc_u32 s17, s17, 0
	global_load_dwordx4 v[56:59], v2, s[16:17]
	s_add_u32 s16, s16, 0x20000
	s_addc_u32 s17, s17, 0
	global_load_dwordx4 v[60:63], v2, s[16:17]
	s_add_u32 s16, s16, 0x20000
	s_addc_u32 s17, s17, 0
	global_load_dwordx4 v[64:67], v2, s[16:17]
	s_add_u32 s16, s16, 0x20000
	s_addc_u32 s17, s17, 0
	global_load_dwordx4 v[68:71], v2, s[16:17]
	s_add_u32 s16, s16, 0x20000
	s_addc_u32 s17, s17, 0
	s_load_dword s40, s[24:25], 0x0
	s_load_dword s41, s[24:25], 0x20
	s_load_dword s42, s[24:25], 0x40
	s_load_dword s43, s[24:25], 0x60
	s_load_dword s44, s[24:25], 0x80
	s_load_dword s45, s[24:25], 0xa0
	s_load_dword s46, s[24:25], 0xc0
	s_load_dword s47, s[24:25], 0xe0
	s_add_u32 s24, s24, 0x100
	s_addc_u32 s25, s25, 0
	s_waitcnt vmcnt(48) lgkmcnt(0)
	v_cvt_pk_bf16_f32 v144, v136, v137
	v_cvt_pk_bf16_f32 v145, v138, v139
	v_cvt_pk_bf16_f32 v146, v140, v141
	v_cvt_pk_bf16_f32 v147, v142, v143
	global_store_dwordx4 v2, v[144:147], s[18:19] sc1
	s_add_u32 s18, s18, 0x20000
	s_addc_u32 s19, s19, 0
	v_lshlrev_b32_e32 v148, 16, v72
	v_and_b32_e32 v149, 0xffff0000, v72
	v_lshlrev_b32_e32 v150, 16, v73
	v_and_b32_e32 v151, 0xffff0000, v73
	v_lshlrev_b32_e32 v152, 16, v74
	v_and_b32_e32 v153, 0xffff0000, v74
	v_lshlrev_b32_e32 v154, 16, v75
	v_and_b32_e32 v155, 0xffff0000, v75
	v_fma_f32 v136, v136, s48, v148
	v_fma_f32 v137, v137, s48, v149
	v_fma_f32 v138, v138, s48, v150
	v_fma_f32 v139, v139, s48, v151
	v_fma_f32 v140, v140, s48, v152
	v_fma_f32 v141, v141, s48, v153
	v_fma_f32 v142, v142, s48, v154
	v_fma_f32 v143, v143, s48, v155
	v_cvt_pk_bf16_f32 v144, v136, v137
	v_cvt_pk_bf16_f32 v145, v138, v139
	v_cvt_pk_bf16_f32 v146, v140, v141
	v_cvt_pk_bf16_f32 v147, v142, v143
	global_store_dwordx4 v2, v[144:147], s[18:19] sc1
	s_add_u32 s18, s18, 0x20000
	s_addc_u32 s19, s19, 0
	v_lshlrev_b32_e32 v148, 16, v76
	v_and_b32_e32 v149, 0xffff0000, v76
	v_lshlrev_b32_e32 v150, 16, v77
	v_and_b32_e32 v151, 0xffff0000, v77
	v_lshlrev_b32_e32 v152, 16, v78
	v_and_b32_e32 v153, 0xffff0000, v78
	v_lshlrev_b32_e32 v154, 16, v79
	v_and_b32_e32 v155, 0xffff0000, v79
	v_fma_f32 v136, v136, s49, v148
	v_fma_f32 v137, v137, s49, v149
	v_fma_f32 v138, v138, s49, v150
	v_fma_f32 v139, v139, s49, v151
	v_fma_f32 v140, v140, s49, v152
	v_fma_f32 v141, v141, s49, v153
	v_fma_f32 v142, v142, s49, v154
	v_fma_f32 v143, v143, s49, v155
	v_cvt_pk_bf16_f32 v144, v136, v137
	v_cvt_pk_bf16_f32 v145, v138, v139
	v_cvt_pk_bf16_f32 v146, v140, v141
	v_cvt_pk_bf16_f32 v147, v142, v143
	global_store_dwordx4 v2, v[144:147], s[18:19] sc1
	s_add_u32 s18, s18, 0x20000
	s_addc_u32 s19, s19, 0
	v_lshlrev_b32_e32 v148, 16, v80
	v_and_b32_e32 v149, 0xffff0000, v80
	v_lshlrev_b32_e32 v150, 16, v81
	v_and_b32_e32 v151, 0xffff0000, v81
	v_lshlrev_b32_e32 v152, 16, v82
	v_and_b32_e32 v153, 0xffff0000, v82
	v_lshlrev_b32_e32 v154, 16, v83
	v_and_b32_e32 v155, 0xffff0000, v83
	v_fma_f32 v136, v136, s50, v148
	v_fma_f32 v137, v137, s50, v149
	v_fma_f32 v138, v138, s50, v150
	v_fma_f32 v139, v139, s50, v151
	v_fma_f32 v140, v140, s50, v152
	v_fma_f32 v141, v141, s50, v153
	v_fma_f32 v142, v142, s50, v154
	v_fma_f32 v143, v143, s50, v155
	v_cvt_pk_bf16_f32 v144, v136, v137
	v_cvt_pk_bf16_f32 v145, v138, v139
	v_cvt_pk_bf16_f32 v146, v140, v141
	v_cvt_pk_bf16_f32 v147, v142, v143
	global_store_dwordx4 v2, v[144:147], s[18:19] sc1
	s_add_u32 s18, s18, 0x20000
	s_addc_u32 s19, s19, 0
	v_lshlrev_b32_e32 v148, 16, v84
	v_and_b32_e32 v149, 0xffff0000, v84
	v_lshlrev_b32_e32 v150, 16, v85
	v_and_b32_e32 v151, 0xffff0000, v85
	v_lshlrev_b32_e32 v152, 16, v86
	v_and_b32_e32 v153, 0xffff0000, v86
	v_lshlrev_b32_e32 v154, 16, v87
	v_and_b32_e32 v155, 0xffff0000, v87
	v_fma_f32 v136, v136, s51, v148
	v_fma_f32 v137, v137, s51, v149
	v_fma_f32 v138, v138, s51, v150
	v_fma_f32 v139, v139, s51, v151
	v_fma_f32 v140, v140, s51, v152
	v_fma_f32 v141, v141, s51, v153
	v_fma_f32 v142, v142, s51, v154
	v_fma_f32 v143, v143, s51, v155
	v_cvt_pk_bf16_f32 v144, v136, v137
	v_cvt_pk_bf16_f32 v145, v138, v139
	v_cvt_pk_bf16_f32 v146, v140, v141
	v_cvt_pk_bf16_f32 v147, v142, v143
	global_store_dwordx4 v2, v[144:147], s[18:19] sc1
	s_add_u32 s18, s18, 0x20000
	s_addc_u32 s19, s19, 0
	v_lshlrev_b32_e32 v148, 16, v88
	v_and_b32_e32 v149, 0xffff0000, v88
	v_lshlrev_b32_e32 v150, 16, v89
	v_and_b32_e32 v151, 0xffff0000, v89
	v_lshlrev_b32_e32 v152, 16, v90
	v_and_b32_e32 v153, 0xffff0000, v90
	v_lshlrev_b32_e32 v154, 16, v91
	v_and_b32_e32 v155, 0xffff0000, v91
	v_fma_f32 v136, v136, s52, v148
	v_fma_f32 v137, v137, s52, v149
	v_fma_f32 v138, v138, s52, v150
	v_fma_f32 v139, v139, s52, v151
	v_fma_f32 v140, v140, s52, v152
	v_fma_f32 v141, v141, s52, v153
	v_fma_f32 v142, v142, s52, v154
	v_fma_f32 v143, v143, s52, v155
	v_cvt_pk_bf16_f32 v144, v136, v137
	v_cvt_pk_bf16_f32 v145, v138, v139
	v_cvt_pk_bf16_f32 v146, v140, v141
	v_cvt_pk_bf16_f32 v147, v142, v143
	global_store_dwordx4 v2, v[144:147], s[18:19] sc1
	s_add_u32 s18, s18, 0x20000
	s_addc_u32 s19, s19, 0
	v_lshlrev_b32_e32 v148, 16, v92
	v_and_b32_e32 v149, 0xffff0000, v92
	v_lshlrev_b32_e32 v150, 16, v93
	v_and_b32_e32 v151, 0xffff0000, v93
	v_lshlrev_b32_e32 v152, 16, v94
	v_and_b32_e32 v153, 0xffff0000, v94
	v_lshlrev_b32_e32 v154, 16, v95
	v_and_b32_e32 v155, 0xffff0000, v95
	v_fma_f32 v136, v136, s53, v148
	v_fma_f32 v137, v137, s53, v149
	v_fma_f32 v138, v138, s53, v150
	v_fma_f32 v139, v139, s53, v151
	v_fma_f32 v140, v140, s53, v152
	v_fma_f32 v141, v141, s53, v153
	v_fma_f32 v142, v142, s53, v154
	v_fma_f32 v143, v143, s53, v155
	v_cvt_pk_bf16_f32 v144, v136, v137
	v_cvt_pk_bf16_f32 v145, v138, v139
	v_cvt_pk_bf16_f32 v146, v140, v141
	v_cvt_pk_bf16_f32 v147, v142, v143
	global_store_dwordx4 v2, v[144:147], s[18:19] sc1
	s_add_u32 s18, s18, 0x20000
	s_addc_u32 s19, s19, 0
	v_lshlrev_b32_e32 v148, 16, v96
	v_and_b32_e32 v149, 0xffff0000, v96
	v_lshlrev_b32_e32 v150, 16, v97
	v_and_b32_e32 v151, 0xffff0000, v97
	v_lshlrev_b32_e32 v152, 16, v98
	v_and_b32_e32 v153, 0xffff0000, v98
	v_lshlrev_b32_e32 v154, 16, v99
	v_and_b32_e32 v155, 0xffff0000, v99
	v_fma_f32 v136, v136, s54, v148
	v_fma_f32 v137, v137, s54, v149
	v_fma_f32 v138, v138, s54, v150
	v_fma_f32 v139, v139, s54, v151
	v_fma_f32 v140, v140, s54, v152
	v_fma_f32 v141, v141, s54, v153
	v_fma_f32 v142, v142, s54, v154
	v_fma_f32 v143, v143, s54, v155
	v_cvt_pk_bf16_f32 v144, v136, v137
	v_cvt_pk_bf16_f32 v145, v138, v139
	v_cvt_pk_bf16_f32 v146, v140, v141
	v_cvt_pk_bf16_f32 v147, v142, v143
	global_store_dwordx4 v2, v[144:147], s[18:19] sc1
	s_add_u32 s18, s18, 0x20000
	s_addc_u32 s19, s19, 0
	v_lshlrev_b32_e32 v148, 16, v100
	v_and_b32_e32 v149, 0xffff0000, v100
	v_lshlrev_b32_e32 v150, 16, v101
	v_and_b32_e32 v151, 0xffff0000, v101
	v_lshlrev_b32_e32 v152, 16, v102
	v_and_b32_e32 v153, 0xffff0000, v102
	v_lshlrev_b32_e32 v154, 16, v103
	v_and_b32_e32 v155, 0xffff0000, v103
	v_fma_f32 v136, v136, s55, v148
	v_fma_f32 v137, v137, s55, v149
	v_fma_f32 v138, v138, s55, v150
	v_fma_f32 v139, v139, s55, v151
	v_fma_f32 v140, v140, s55, v152
	v_fma_f32 v141, v141, s55, v153
	v_fma_f32 v142, v142, s55, v154
	v_fma_f32 v143, v143, s55, v155
	global_load_dwordx4 v[72:75], v2, s[16:17]
	s_add_u32 s16, s16, 0x20000
	s_addc_u32 s17, s17, 0
	global_load_dwordx4 v[76:79], v2, s[16:17]
	s_add_u32 s16, s16, 0x20000
	s_addc_u32 s17, s17, 0
	global_load_dwordx4 v[80:83], v2, s[16:17]
	s_add_u32 s16, s16, 0x20000
	s_addc_u32 s17, s17, 0
	global_load_dwordx4 v[84:87], v2, s[16:17]
	s_add_u32 s16, s16, 0x20000
	s_addc_u32 s17, s17, 0
	global_load_dwordx4 v[88:91], v2, s[16:17]
	s_add_u32 s16, s16, 0x20000
	s_addc_u32 s17, s17, 0
	global_load_dwordx4 v[92:95], v2, s[16:17]
	s_add_u32 s16, s16, 0x20000
	s_addc_u32 s17, s17, 0
	global_load_dwordx4 v[96:99], v2, s[16:17]
	s_add_u32 s16, s16, 0x20000
	s_addc_u32 s17, s17, 0
	global_load_dwordx4 v[100:103], v2, s[16:17]
	s_add_u32 s16, s16, 0x20000
	s_addc_u32 s17, s17, 0
	s_load_dword s48, s[24:25], 0x0
	s_load_dword s49, s[24:25], 0x20
	s_load_dword s50, s[24:25], 0x40
	s_load_dword s51, s[24:25], 0x60
	s_load_dword s52, s[24:25], 0x80
	s_load_dword s53, s[24:25], 0xa0
	s_load_dword s54, s[24:25], 0xc0
	s_load_dword s55, s[24:25], 0xe0
	s_add_u32 s24, s24, 0x100
	s_addc_u32 s25, s25, 0
	s_waitcnt vmcnt(48) lgkmcnt(0)
	v_cvt_pk_bf16_f32 v144, v136, v137
	v_cvt_pk_bf16_f32 v145, v138, v139
	v_cvt_pk_bf16_f32 v146, v140, v141
	v_cvt_pk_bf16_f32 v147, v142, v143
	global_store_dwordx4 v2, v[144:147], s[18:19] sc1
	s_add_u32 s18, s18, 0x20000
	s_addc_u32 s19, s19, 0
	v_lshlrev_b32_e32 v148, 16, v104
	v_and_b32_e32 v149, 0xffff0000, v104
	v_lshlrev_b32_e32 v150, 16, v105
	v_and_b32_e32 v151, 0xffff0000, v105
	v_lshlrev_b32_e32 v152, 16, v106
	v_and_b32_e32 v153, 0xffff0000, v106
	v_lshlrev_b32_e32 v154, 16, v107
	v_and_b32_e32 v155, 0xffff0000, v107
	v_fma_f32 v136, v136, s56, v148
	v_fma_f32 v137, v137, s56, v149
	v_fma_f32 v138, v138, s56, v150
	v_fma_f32 v139, v139, s56, v151
	v_fma_f32 v140, v140, s56, v152
	v_fma_f32 v141, v141, s56, v153
	v_fma_f32 v142, v142, s56, v154
	v_fma_f32 v143, v143, s56, v155
	v_cvt_pk_bf16_f32 v144, v136, v137
	v_cvt_pk_bf16_f32 v145, v138, v139
	v_cvt_pk_bf16_f32 v146, v140, v141
	v_cvt_pk_bf16_f32 v147, v142, v143
	global_store_dwordx4 v2, v[144:147], s[18:19] sc1
	s_add_u32 s18, s18, 0x20000
	s_addc_u32 s19, s19, 0
	v_lshlrev_b32_e32 v148, 16, v108
	v_and_b32_e32 v149, 0xffff0000, v108
	v_lshlrev_b32_e32 v150, 16, v109
	v_and_b32_e32 v151, 0xffff0000, v109
	v_lshlrev_b32_e32 v152, 16, v110
	v_and_b32_e32 v153, 0xffff0000, v110
	v_lshlrev_b32_e32 v154, 16, v111
	v_and_b32_e32 v155, 0xffff0000, v111
	v_fma_f32 v136, v136, s57, v148
	v_fma_f32 v137, v137, s57, v149
	v_fma_f32 v138, v138, s57, v150
	v_fma_f32 v139, v139, s57, v151
	v_fma_f32 v140, v140, s57, v152
	v_fma_f32 v141, v141, s57, v153
	v_fma_f32 v142, v142, s57, v154
	v_fma_f32 v143, v143, s57, v155
	v_cvt_pk_bf16_f32 v144, v136, v137
	v_cvt_pk_bf16_f32 v145, v138, v139
	v_cvt_pk_bf16_f32 v146, v140, v141
	v_cvt_pk_bf16_f32 v147, v142, v143
	global_store_dwordx4 v2, v[144:147], s[18:19] sc1
	s_add_u32 s18, s18, 0x20000
	s_addc_u32 s19, s19, 0
	v_lshlrev_b32_e32 v148, 16, v112
	v_and_b32_e32 v149, 0xffff0000, v112
	v_lshlrev_b32_e32 v150, 16, v113
	v_and_b32_e32 v151, 0xffff0000, v113
	v_lshlrev_b32_e32 v152, 16, v114
	v_and_b32_e32 v153, 0xffff0000, v114
	v_lshlrev_b32_e32 v154, 16, v115
	v_and_b32_e32 v155, 0xffff0000, v115
	v_fma_f32 v136, v136, s58, v148
	v_fma_f32 v137, v137, s58, v149
	v_fma_f32 v138, v138, s58, v150
	v_fma_f32 v139, v139, s58, v151
	v_fma_f32 v140, v140, s58, v152
	v_fma_f32 v141, v141, s58, v153
	v_fma_f32 v142, v142, s58, v154
	v_fma_f32 v143, v143, s58, v155
	v_cvt_pk_bf16_f32 v144, v136, v137
	v_cvt_pk_bf16_f32 v145, v138, v139
	v_cvt_pk_bf16_f32 v146, v140, v141
	v_cvt_pk_bf16_f32 v147, v142, v143
	global_store_dwordx4 v2, v[144:147], s[18:19] sc1
	s_add_u32 s18, s18, 0x20000
	s_addc_u32 s19, s19, 0
	v_lshlrev_b32_e32 v148, 16, v116
	v_and_b32_e32 v149, 0xffff0000, v116
	v_lshlrev_b32_e32 v150, 16, v117
	v_and_b32_e32 v151, 0xffff0000, v117
	v_lshlrev_b32_e32 v152, 16, v118
	v_and_b32_e32 v153, 0xffff0000, v118
	v_lshlrev_b32_e32 v154, 16, v119
	v_and_b32_e32 v155, 0xffff0000, v119
	v_fma_f32 v136, v136, s59, v148
	v_fma_f32 v137, v137, s59, v149
	v_fma_f32 v138, v138, s59, v150
	v_fma_f32 v139, v139, s59, v151
	v_fma_f32 v140, v140, s59, v152
	v_fma_f32 v141, v141, s59, v153
	v_fma_f32 v142, v142, s59, v154
	v_fma_f32 v143, v143, s59, v155
	v_cvt_pk_bf16_f32 v144, v136, v137
	v_cvt_pk_bf16_f32 v145, v138, v139
	v_cvt_pk_bf16_f32 v146, v140, v141
	v_cvt_pk_bf16_f32 v147, v142, v143
	global_store_dwordx4 v2, v[144:147], s[18:19] sc1
	s_add_u32 s18, s18, 0x20000
	s_addc_u32 s19, s19, 0
	v_lshlrev_b32_e32 v148, 16, v120
	v_and_b32_e32 v149, 0xffff0000, v120
	v_lshlrev_b32_e32 v150, 16, v121
	v_and_b32_e32 v151, 0xffff0000, v121
	v_lshlrev_b32_e32 v152, 16, v122
	v_and_b32_e32 v153, 0xffff0000, v122
	v_lshlrev_b32_e32 v154, 16, v123
	v_and_b32_e32 v155, 0xffff0000, v123
	v_fma_f32 v136, v136, s60, v148
	v_fma_f32 v137, v137, s60, v149
	v_fma_f32 v138, v138, s60, v150
	v_fma_f32 v139, v139, s60, v151
	v_fma_f32 v140, v140, s60, v152
	v_fma_f32 v141, v141, s60, v153
	v_fma_f32 v142, v142, s60, v154
	v_fma_f32 v143, v143, s60, v155
	v_cvt_pk_bf16_f32 v144, v136, v137
	v_cvt_pk_bf16_f32 v145, v138, v139
	v_cvt_pk_bf16_f32 v146, v140, v141
	v_cvt_pk_bf16_f32 v147, v142, v143
	global_store_dwordx4 v2, v[144:147], s[18:19] sc1
	s_add_u32 s18, s18, 0x20000
	s_addc_u32 s19, s19, 0
	v_lshlrev_b32_e32 v148, 16, v124
	v_and_b32_e32 v149, 0xffff0000, v124
	v_lshlrev_b32_e32 v150, 16, v125
	v_and_b32_e32 v151, 0xffff0000, v125
	v_lshlrev_b32_e32 v152, 16, v126
	v_and_b32_e32 v153, 0xffff0000, v126
	v_lshlrev_b32_e32 v154, 16, v127
	v_and_b32_e32 v155, 0xffff0000, v127
	v_fma_f32 v136, v136, s61, v148
	v_fma_f32 v137, v137, s61, v149
	v_fma_f32 v138, v138, s61, v150
	v_fma_f32 v139, v139, s61, v151
	v_fma_f32 v140, v140, s61, v152
	v_fma_f32 v141, v141, s61, v153
	v_fma_f32 v142, v142, s61, v154
	v_fma_f32 v143, v143, s61, v155
	v_cvt_pk_bf16_f32 v144, v136, v137
	v_cvt_pk_bf16_f32 v145, v138, v139
	v_cvt_pk_bf16_f32 v146, v140, v141
	v_cvt_pk_bf16_f32 v147, v142, v143
	global_store_dwordx4 v2, v[144:147], s[18:19] sc1
	s_add_u32 s18, s18, 0x20000
	s_addc_u32 s19, s19, 0
	v_lshlrev_b32_e32 v148, 16, v128
	v_and_b32_e32 v149, 0xffff0000, v128
	v_lshlrev_b32_e32 v150, 16, v129
	v_and_b32_e32 v151, 0xffff0000, v129
	v_lshlrev_b32_e32 v152, 16, v130
	v_and_b32_e32 v153, 0xffff0000, v130
	v_lshlrev_b32_e32 v154, 16, v131
	v_and_b32_e32 v155, 0xffff0000, v131
	v_fma_f32 v136, v136, s62, v148
	v_fma_f32 v137, v137, s62, v149
	v_fma_f32 v138, v138, s62, v150
	v_fma_f32 v139, v139, s62, v151
	v_fma_f32 v140, v140, s62, v152
	v_fma_f32 v141, v141, s62, v153
	v_fma_f32 v142, v142, s62, v154
	v_fma_f32 v143, v143, s62, v155
	v_cvt_pk_bf16_f32 v144, v136, v137
	v_cvt_pk_bf16_f32 v145, v138, v139
	v_cvt_pk_bf16_f32 v146, v140, v141
	v_cvt_pk_bf16_f32 v147, v142, v143
	global_store_dwordx4 v2, v[144:147], s[18:19] sc1
	s_add_u32 s18, s18, 0x20000
	s_addc_u32 s19, s19, 0
	v_lshlrev_b32_e32 v148, 16, v132
	v_and_b32_e32 v149, 0xffff0000, v132
	v_lshlrev_b32_e32 v150, 16, v133
	v_and_b32_e32 v151, 0xffff0000, v133
	v_lshlrev_b32_e32 v152, 16, v134
	v_and_b32_e32 v153, 0xffff0000, v134
	v_lshlrev_b32_e32 v154, 16, v135
	v_and_b32_e32 v155, 0xffff0000, v135
	v_fma_f32 v136, v136, s63, v148
	v_fma_f32 v137, v137, s63, v149
	v_fma_f32 v138, v138, s63, v150
	v_fma_f32 v139, v139, s63, v151
	v_fma_f32 v140, v140, s63, v152
	v_fma_f32 v141, v141, s63, v153
	v_fma_f32 v142, v142, s63, v154
	v_fma_f32 v143, v143, s63, v155
	global_load_dwordx4 v[104:107], v2, s[16:17]
	s_add_u32 s16, s16, 0x20000
	s_addc_u32 s17, s17, 0
	global_load_dwordx4 v[108:111], v2, s[16:17]
	s_add_u32 s16, s16, 0x20000
	s_addc_u32 s17, s17, 0
	global_load_dwordx4 v[112:115], v2, s[16:17]
	s_add_u32 s16, s16, 0x20000
	s_addc_u32 s17, s17, 0
	global_load_dwordx4 v[116:119], v2, s[16:17]
	s_add_u32 s16, s16, 0x20000
	s_addc_u32 s17, s17, 0
	global_load_dwordx4 v[120:123], v2, s[16:17]
	s_add_u32 s16, s16, 0x20000
	s_addc_u32 s17, s17, 0
	global_load_dwordx4 v[124:127], v2, s[16:17]
	s_add_u32 s16, s16, 0x20000
	s_addc_u32 s17, s17, 0
	global_load_dwordx4 v[128:131], v2, s[16:17]
	s_add_u32 s16, s16, 0x20000
	s_addc_u32 s17, s17, 0
	global_load_dwordx4 v[132:135], v2, s[16:17]
	s_add_u32 s16, s16, 0x20000
	s_addc_u32 s17, s17, 0
	s_load_dword s56, s[24:25], 0x0
	s_load_dword s57, s[24:25], 0x20
	s_load_dword s58, s[24:25], 0x40
	s_load_dword s59, s[24:25], 0x60
	s_load_dword s60, s[24:25], 0x80
	s_load_dword s61, s[24:25], 0xa0
	s_load_dword s62, s[24:25], 0xc0
	s_load_dword s63, s[24:25], 0xe0
	s_add_u32 s24, s24, 0x100
	s_addc_u32 s25, s25, 0
	s_sub_u32 s22, s22, 1
	s_cmp_lg_u32 s22, 0
	s_cbranch_scc1 .Lp3_ssd_loop
	s_waitcnt vmcnt(48) lgkmcnt(0)
	v_cvt_pk_bf16_f32 v144, v136, v137
	v_cvt_pk_bf16_f32 v145, v138, v139
	v_cvt_pk_bf16_f32 v146, v140, v141
	v_cvt_pk_bf16_f32 v147, v142, v143
	global_store_dwordx4 v2, v[144:147], s[18:19] sc1
	s_add_u32 s18, s18, 0x20000
	s_addc_u32 s19, s19, 0
	v_lshlrev_b32_e32 v148, 16, v8
	v_and_b32_e32 v149, 0xffff0000, v8
	v_lshlrev_b32_e32 v150, 16, v9
	v_and_b32_e32 v151, 0xffff0000, v9
	v_lshlrev_b32_e32 v152, 16, v10
	v_and_b32_e32 v153, 0xffff0000, v10
	v_lshlrev_b32_e32 v154, 16, v11
	v_and_b32_e32 v155, 0xffff0000, v11
	v_fma_f32 v136, v136, s32, v148
	v_fma_f32 v137, v137, s32, v149
	v_fma_f32 v138, v138, s32, v150
	v_fma_f32 v139, v139, s32, v151
	v_fma_f32 v140, v140, s32, v152
	v_fma_f32 v141, v141, s32, v153
	v_fma_f32 v142, v142, s32, v154
	v_fma_f32 v143, v143, s32, v155
	v_cvt_pk_bf16_f32 v144, v136, v137
	v_cvt_pk_bf16_f32 v145, v138, v139
	v_cvt_pk_bf16_f32 v146, v140, v141
	v_cvt_pk_bf16_f32 v147, v142, v143
	global_store_dwordx4 v2, v[144:147], s[18:19] sc1
	s_add_u32 s18, s18, 0x20000
	s_addc_u32 s19, s19, 0
	v_lshlrev_b32_e32 v148, 16, v12
	v_and_b32_e32 v149, 0xffff0000, v12
	v_lshlrev_b32_e32 v150, 16, v13
	v_and_b32_e32 v151, 0xffff0000, v13
	v_lshlrev_b32_e32 v152, 16, v14
	v_and_b32_e32 v153, 0xffff0000, v14
	v_lshlrev_b32_e32 v154, 16, v15
	v_and_b32_e32 v155, 0xffff0000, v15
	v_fma_f32 v136, v136, s33, v148
	v_fma_f32 v137, v137, s33, v149
	v_fma_f32 v138, v138, s33, v150
	v_fma_f32 v139, v139, s33, v151
	v_fma_f32 v140, v140, s33, v152
	v_fma_f32 v141, v141, s33, v153
	v_fma_f32 v142, v142, s33, v154
	v_fma_f32 v143, v143, s33, v155
	v_cvt_pk_bf16_f32 v144, v136, v137
	v_cvt_pk_bf16_f32 v145, v138, v139
	v_cvt_pk_bf16_f32 v146, v140, v141
	v_cvt_pk_bf16_f32 v147, v142, v143
	global_store_dwordx4 v2, v[144:147], s[18:19] sc1
	s_add_u32 s18, s18, 0x20000
	s_addc_u32 s19, s19, 0
	v_lshlrev_b32_e32 v148, 16, v16
	v_and_b32_e32 v149, 0xffff0000, v16
	v_lshlrev_b32_e32 v150, 16, v17
	v_and_b32_e32 v151, 0xffff0000, v17
	v_lshlrev_b32_e32 v152, 16, v18
	v_and_b32_e32 v153, 0xffff0000, v18
	v_lshlrev_b32_e32 v154, 16, v19
	v_and_b32_e32 v155, 0xffff0000, v19
	v_fma_f32 v136, v136, s34, v148
	v_fma_f32 v137, v137, s34, v149
	v_fma_f32 v138, v138, s34, v150
	v_fma_f32 v139, v139, s34, v151
	v_fma_f32 v140, v140, s34, v152
	v_fma_f32 v141, v141, s34, v153
	v_fma_f32 v142, v142, s34, v154
	v_fma_f32 v143, v143, s34, v155
	v_cvt_pk_bf16_f32 v144, v136, v137
	v_cvt_pk_bf16_f32 v145, v138, v139
	v_cvt_pk_bf16_f32 v146, v140, v141
	v_cvt_pk_bf16_f32 v147, v142, v143
	global_store_dwordx4 v2, v[144:147], s[18:19] sc1
	s_add_u32 s18, s18, 0x20000
	s_addc_u32 s19, s19, 0
	v_lshlrev_b32_e32 v148, 16, v20
	v_and_b32_e32 v149, 0xffff0000, v20
	v_lshlrev_b32_e32 v150, 16, v21
	v_and_b32_e32 v151, 0xffff0000, v21
	v_lshlrev_b32_e32 v152, 16, v22
	v_and_b32_e32 v153, 0xffff0000, v22
	v_lshlrev_b32_e32 v154, 16, v23
	v_and_b32_e32 v155, 0xffff0000, v23
	v_fma_f32 v136, v136, s35, v148
	v_fma_f32 v137, v137, s35, v149
	v_fma_f32 v138, v138, s35, v150
	v_fma_f32 v139, v139, s35, v151
	v_fma_f32 v140, v140, s35, v152
	v_fma_f32 v141, v141, s35, v153
	v_fma_f32 v142, v142, s35, v154
	v_fma_f32 v143, v143, s35, v155
	v_cvt_pk_bf16_f32 v144, v136, v137
	v_cvt_pk_bf16_f32 v145, v138, v139
	v_cvt_pk_bf16_f32 v146, v140, v141
	v_cvt_pk_bf16_f32 v147, v142, v143
	global_store_dwordx4 v2, v[144:147], s[18:19] sc1
	s_add_u32 s18, s18, 0x20000
	s_addc_u32 s19, s19, 0
	v_lshlrev_b32_e32 v148, 16, v24
	v_and_b32_e32 v149, 0xffff0000, v24
	v_lshlrev_b32_e32 v150, 16, v25
	v_and_b32_e32 v151, 0xffff0000, v25
	v_lshlrev_b32_e32 v152, 16, v26
	v_and_b32_e32 v153, 0xffff0000, v26
	v_lshlrev_b32_e32 v154, 16, v27
	v_and_b32_e32 v155, 0xffff0000, v27
	v_fma_f32 v136, v136, s36, v148
	v_fma_f32 v137, v137, s36, v149
	v_fma_f32 v138, v138, s36, v150
	v_fma_f32 v139, v139, s36, v151
	v_fma_f32 v140, v140, s36, v152
	v_fma_f32 v141, v141, s36, v153
	v_fma_f32 v142, v142, s36, v154
	v_fma_f32 v143, v143, s36, v155
	v_cvt_pk_bf16_f32 v144, v136, v137
	v_cvt_pk_bf16_f32 v145, v138, v139
	v_cvt_pk_bf16_f32 v146, v140, v141
	v_cvt_pk_bf16_f32 v147, v142, v143
	global_store_dwordx4 v2, v[144:147], s[18:19] sc1
	s_add_u32 s18, s18, 0x20000
	s_addc_u32 s19, s19, 0
	v_lshlrev_b32_e32 v148, 16, v28
	v_and_b32_e32 v149, 0xffff0000, v28
	v_lshlrev_b32_e32 v150, 16, v29
	v_and_b32_e32 v151, 0xffff0000, v29
	v_lshlrev_b32_e32 v152, 16, v30
	v_and_b32_e32 v153, 0xffff0000, v30
	v_lshlrev_b32_e32 v154, 16, v31
	v_and_b32_e32 v155, 0xffff0000, v31
	v_fma_f32 v136, v136, s37, v148
	v_fma_f32 v137, v137, s37, v149
	v_fma_f32 v138, v138, s37, v150
	v_fma_f32 v139, v139, s37, v151
	v_fma_f32 v140, v140, s37, v152
	v_fma_f32 v141, v141, s37, v153
	v_fma_f32 v142, v142, s37, v154
	v_fma_f32 v143, v143, s37, v155
	v_cvt_pk_bf16_f32 v144, v136, v137
	v_cvt_pk_bf16_f32 v145, v138, v139
	v_cvt_pk_bf16_f32 v146, v140, v141
	v_cvt_pk_bf16_f32 v147, v142, v143
	global_store_dwordx4 v2, v[144:147], s[18:19] sc1
	s_add_u32 s18, s18, 0x20000
	s_addc_u32 s19, s19, 0
	v_lshlrev_b32_e32 v148, 16, v32
	v_and_b32_e32 v149, 0xffff0000, v32
	v_lshlrev_b32_e32 v150, 16, v33
	v_and_b32_e32 v151, 0xffff0000, v33
	v_lshlrev_b32_e32 v152, 16, v34
	v_and_b32_e32 v153, 0xffff0000, v34
	v_lshlrev_b32_e32 v154, 16, v35
	v_and_b32_e32 v155, 0xffff0000, v35
	v_fma_f32 v136, v136, s38, v148
	v_fma_f32 v137, v137, s38, v149
	v_fma_f32 v138, v138, s38, v150
	v_fma_f32 v139, v139, s38, v151
	v_fma_f32 v140, v140, s38, v152
	v_fma_f32 v141, v141, s38, v153
	v_fma_f32 v142, v142, s38, v154
	v_fma_f32 v143, v143, s38, v155
	v_cvt_pk_bf16_f32 v144, v136, v137
	v_cvt_pk_bf16_f32 v145, v138, v139
	v_cvt_pk_bf16_f32 v146, v140, v141
	v_cvt_pk_bf16_f32 v147, v142, v143
	global_store_dwordx4 v2, v[144:147], s[18:19] sc1
	s_add_u32 s18, s18, 0x20000
	s_addc_u32 s19, s19, 0
	v_lshlrev_b32_e32 v148, 16, v36
	v_and_b32_e32 v149, 0xffff0000, v36
	v_lshlrev_b32_e32 v150, 16, v37
	v_and_b32_e32 v151, 0xffff0000, v37
	v_lshlrev_b32_e32 v152, 16, v38
	v_and_b32_e32 v153, 0xffff0000, v38
	v_lshlrev_b32_e32 v154, 16, v39
	v_and_b32_e32 v155, 0xffff0000, v39
	v_fma_f32 v136, v136, s39, v148
	v_fma_f32 v137, v137, s39, v149
	v_fma_f32 v138, v138, s39, v150
	v_fma_f32 v139, v139, s39, v151
	v_fma_f32 v140, v140, s39, v152
	v_fma_f32 v141, v141, s39, v153
	v_fma_f32 v142, v142, s39, v154
	v_fma_f32 v143, v143, s39, v155
	s_waitcnt vmcnt(40) lgkmcnt(0)
	v_cvt_pk_bf16_f32 v144, v136, v137
	v_cvt_pk_bf16_f32 v145, v138, v139
	v_cvt_pk_bf16_f32 v146, v140, v141
	v_cvt_pk_bf16_f32 v147, v142, v143
	global_store_dwordx4 v2, v[144:147], s[18:19] sc1
	s_add_u32 s18, s18, 0x20000
	s_addc_u32 s19, s19, 0
	v_lshlrev_b32_e32 v148, 16, v40
	v_and_b32_e32 v149, 0xffff0000, v40
	v_lshlrev_b32_e32 v150, 16, v41
	v_and_b32_e32 v151, 0xffff0000, v41
	v_lshlrev_b32_e32 v152, 16, v42
	v_and_b32_e32 v153, 0xffff0000, v42
	v_lshlrev_b32_e32 v154, 16, v43
	v_and_b32_e32 v155, 0xffff0000, v43
	v_fma_f32 v136, v136, s40, v148
	v_fma_f32 v137, v137, s40, v149
	v_fma_f32 v138, v138, s40, v150
	v_fma_f32 v139, v139, s40, v151
	v_fma_f32 v140, v140, s40, v152
	v_fma_f32 v141, v141, s40, v153
	v_fma_f32 v142, v142, s40, v154
	v_fma_f32 v143, v143, s40, v155
	v_cvt_pk_bf16_f32 v144, v136, v137
	v_cvt_pk_bf16_f32 v145, v138, v139
	v_cvt_pk_bf16_f32 v146, v140, v141
	v_cvt_pk_bf16_f32 v147, v142, v143
	global_store_dwordx4 v2, v[144:147], s[18:19] sc1
	s_add_u32 s18, s18, 0x20000
	s_addc_u32 s19, s19, 0
	v_lshlrev_b32_e32 v148, 16, v44
	v_and_b32_e32 v149, 0xffff0000, v44
	v_lshlrev_b32_e32 v150, 16, v45
	v_and_b32_e32 v151, 0xffff0000, v45
	v_lshlrev_b32_e32 v152, 16, v46
	v_and_b32_e32 v153, 0xffff0000, v46
	v_lshlrev_b32_e32 v154, 16, v47
	v_and_b32_e32 v155, 0xffff0000, v47
	v_fma_f32 v136, v136, s41, v148
	v_fma_f32 v137, v137, s41, v149
	v_fma_f32 v138, v138, s41, v150
	v_fma_f32 v139, v139, s41, v151
	v_fma_f32 v140, v140, s41, v152
	v_fma_f32 v141, v141, s41, v153
	v_fma_f32 v142, v142, s41, v154
	v_fma_f32 v143, v143, s41, v155
	v_cvt_pk_bf16_f32 v144, v136, v137
	v_cvt_pk_bf16_f32 v145, v138, v139
	v_cvt_pk_bf16_f32 v146, v140, v141
	v_cvt_pk_bf16_f32 v147, v142, v143
	global_store_dwordx4 v2, v[144:147], s[18:19] sc1
	s_add_u32 s18, s18, 0x20000
	s_addc_u32 s19, s19, 0
	v_lshlrev_b32_e32 v148, 16, v48
	v_and_b32_e32 v149, 0xffff0000, v48
	v_lshlrev_b32_e32 v150, 16, v49
	v_and_b32_e32 v151, 0xffff0000, v49
	v_lshlrev_b32_e32 v152, 16, v50
	v_and_b32_e32 v153, 0xffff0000, v50
	v_lshlrev_b32_e32 v154, 16, v51
	v_and_b32_e32 v155, 0xffff0000, v51
	v_fma_f32 v136, v136, s42, v148
	v_fma_f32 v137, v137, s42, v149
	v_fma_f32 v138, v138, s42, v150
	v_fma_f32 v139, v139, s42, v151
	v_fma_f32 v140, v140, s42, v152
	v_fma_f32 v141, v141, s42, v153
	v_fma_f32 v142, v142, s42, v154
	v_fma_f32 v143, v143, s42, v155
	v_cvt_pk_bf16_f32 v144, v136, v137
	v_cvt_pk_bf16_f32 v145, v138, v139
	v_cvt_pk_bf16_f32 v146, v140, v141
	v_cvt_pk_bf16_f32 v147, v142, v143
	global_store_dwordx4 v2, v[144:147], s[18:19] sc1
	s_add_u32 s18, s18, 0x20000
	s_addc_u32 s19, s19, 0
	v_lshlrev_b32_e32 v148, 16, v52
	v_and_b32_e32 v149, 0xffff0000, v52
	v_lshlrev_b32_e32 v150, 16, v53
	v_and_b32_e32 v151, 0xffff0000, v53
	v_lshlrev_b32_e32 v152, 16, v54
	v_and_b32_e32 v153, 0xffff0000, v54
	v_lshlrev_b32_e32 v154, 16, v55
	v_and_b32_e32 v155, 0xffff0000, v55
	v_fma_f32 v136, v136, s43, v148
	v_fma_f32 v137, v137, s43, v149
	v_fma_f32 v138, v138, s43, v150
	v_fma_f32 v139, v139, s43, v151
	v_fma_f32 v140, v140, s43, v152
	v_fma_f32 v141, v141, s43, v153
	v_fma_f32 v142, v142, s43, v154
	v_fma_f32 v143, v143, s43, v155
	v_cvt_pk_bf16_f32 v144, v136, v137
	v_cvt_pk_bf16_f32 v145, v138, v139
	v_cvt_pk_bf16_f32 v146, v140, v141
	v_cvt_pk_bf16_f32 v147, v142, v143
	global_store_dwordx4 v2, v[144:147], s[18:19] sc1
	s_add_u32 s18, s18, 0x20000
	s_addc_u32 s19, s19, 0
	v_lshlrev_b32_e32 v148, 16, v56
	v_and_b32_e32 v149, 0xffff0000, v56
	v_lshlrev_b32_e32 v150, 16, v57
	v_and_b32_e32 v151, 0xffff0000, v57
	v_lshlrev_b32_e32 v152, 16, v58
	v_and_b32_e32 v153, 0xffff0000, v58
	v_lshlrev_b32_e32 v154, 16, v59
	v_and_b32_e32 v155, 0xffff0000, v59
	v_fma_f32 v136, v136, s44, v148
	v_fma_f32 v137, v137, s44, v149
	v_fma_f32 v138, v138, s44, v150
	v_fma_f32 v139, v139, s44, v151
	v_fma_f32 v140, v140, s44, v152
	v_fma_f32 v141, v141, s44, v153
	v_fma_f32 v142, v142, s44, v154
	v_fma_f32 v143, v143, s44, v155
	v_cvt_pk_bf16_f32 v144, v136, v137
	v_cvt_pk_bf16_f32 v145, v138, v139
	v_cvt_pk_bf16_f32 v146, v140, v141
	v_cvt_pk_bf16_f32 v147, v142, v143
	global_store_dwordx4 v2, v[144:147], s[18:19] sc1
	s_add_u32 s18, s18, 0x20000
	s_addc_u32 s19, s19, 0
	v_lshlrev_b32_e32 v148, 16, v60
	v_and_b32_e32 v149, 0xffff0000, v60
	v_lshlrev_b32_e32 v150, 16, v61
	v_and_b32_e32 v151, 0xffff0000, v61
	v_lshlrev_b32_e32 v152, 16, v62
	v_and_b32_e32 v153, 0xffff0000, v62
	v_lshlrev_b32_e32 v154, 16, v63
	v_and_b32_e32 v155, 0xffff0000, v63
	v_fma_f32 v136, v136, s45, v148
	v_fma_f32 v137, v137, s45, v149
	v_fma_f32 v138, v138, s45, v150
	v_fma_f32 v139, v139, s45, v151
	v_fma_f32 v140, v140, s45, v152
	v_fma_f32 v141, v141, s45, v153
	v_fma_f32 v142, v142, s45, v154
	v_fma_f32 v143, v143, s45, v155
	v_cvt_pk_bf16_f32 v144, v136, v137
	v_cvt_pk_bf16_f32 v145, v138, v139
	v_cvt_pk_bf16_f32 v146, v140, v141
	v_cvt_pk_bf16_f32 v147, v142, v143
	global_store_dwordx4 v2, v[144:147], s[18:19] sc1
	s_add_u32 s18, s18, 0x20000
	s_addc_u32 s19, s19, 0
	v_lshlrev_b32_e32 v148, 16, v64
	v_and_b32_e32 v149, 0xffff0000, v64
	v_lshlrev_b32_e32 v150, 16, v65
	v_and_b32_e32 v151, 0xffff0000, v65
	v_lshlrev_b32_e32 v152, 16, v66
	v_and_b32_e32 v153, 0xffff0000, v66
	v_lshlrev_b32_e32 v154, 16, v67
	v_and_b32_e32 v155, 0xffff0000, v67
	v_fma_f32 v136, v136, s46, v148
	v_fma_f32 v137, v137, s46, v149
	v_fma_f32 v138, v138, s46, v150
	v_fma_f32 v139, v139, s46, v151
	v_fma_f32 v140, v140, s46, v152
	v_fma_f32 v141, v141, s46, v153
	v_fma_f32 v142, v142, s46, v154
	v_fma_f32 v143, v143, s46, v155
	v_cvt_pk_bf16_f32 v144, v136, v137
	v_cvt_pk_bf16_f32 v145, v138, v139
	v_cvt_pk_bf16_f32 v146, v140, v141
	v_cvt_pk_bf16_f32 v147, v142, v143
	global_store_dwordx4 v2, v[144:147], s[18:19] sc1
	s_add_u32 s18, s18, 0x20000
	s_addc_u32 s19, s19, 0
	v_lshlrev_b32_e32 v148, 16, v68
	v_and_b32_e32 v149, 0xffff0000, v68
	v_lshlrev_b32_e32 v150, 16, v69
	v_and_b32_e32 v151, 0xffff0000, v69
	v_lshlrev_b32_e32 v152, 16, v70
	v_and_b32_e32 v153, 0xffff0000, v70
	v_lshlrev_b32_e32 v154, 16, v71
	v_and_b32_e32 v155, 0xffff0000, v71
	v_fma_f32 v136, v136, s47, v148
	v_fma_f32 v137, v137, s47, v149
	v_fma_f32 v138, v138, s47, v150
	v_fma_f32 v139, v139, s47, v151
	v_fma_f32 v140, v140, s47, v152
	v_fma_f32 v141, v141, s47, v153
	v_fma_f32 v142, v142, s47, v154
	v_fma_f32 v143, v143, s47, v155
	s_waitcnt vmcnt(32) lgkmcnt(0)
	v_cvt_pk_bf16_f32 v144, v136, v137
	v_cvt_pk_bf16_f32 v145, v138, v139
	v_cvt_pk_bf16_f32 v146, v140, v141
	v_cvt_pk_bf16_f32 v147, v142, v143
	global_store_dwordx4 v2, v[144:147], s[18:19] sc1
	s_add_u32 s18, s18, 0x20000
	s_addc_u32 s19, s19, 0
	v_lshlrev_b32_e32 v148, 16, v72
	v_and_b32_e32 v149, 0xffff0000, v72
	v_lshlrev_b32_e32 v150, 16, v73
	v_and_b32_e32 v151, 0xffff0000, v73
	v_lshlrev_b32_e32 v152, 16, v74
	v_and_b32_e32 v153, 0xffff0000, v74
	v_lshlrev_b32_e32 v154, 16, v75
	v_and_b32_e32 v155, 0xffff0000, v75
	v_fma_f32 v136, v136, s48, v148
	v_fma_f32 v137, v137, s48, v149
	v_fma_f32 v138, v138, s48, v150
	v_fma_f32 v139, v139, s48, v151
	v_fma_f32 v140, v140, s48, v152
	v_fma_f32 v141, v141, s48, v153
	v_fma_f32 v142, v142, s48, v154
	v_fma_f32 v143, v143, s48, v155
	v_cvt_pk_bf16_f32 v144, v136, v137
	v_cvt_pk_bf16_f32 v145, v138, v139
	v_cvt_pk_bf16_f32 v146, v140, v141
	v_cvt_pk_bf16_f32 v147, v142, v143
	global_store_dwordx4 v2, v[144:147], s[18:19] sc1
	s_add_u32 s18, s18, 0x20000
	s_addc_u32 s19, s19, 0
	v_lshlrev_b32_e32 v148, 16, v76
	v_and_b32_e32 v149, 0xffff0000, v76
	v_lshlrev_b32_e32 v150, 16, v77
	v_and_b32_e32 v151, 0xffff0000, v77
	v_lshlrev_b32_e32 v152, 16, v78
	v_and_b32_e32 v153, 0xffff0000, v78
	v_lshlrev_b32_e32 v154, 16, v79
	v_and_b32_e32 v155, 0xffff0000, v79
	v_fma_f32 v136, v136, s49, v148
	v_fma_f32 v137, v137, s49, v149
	v_fma_f32 v138, v138, s49, v150
	v_fma_f32 v139, v139, s49, v151
	v_fma_f32 v140, v140, s49, v152
	v_fma_f32 v141, v141, s49, v153
	v_fma_f32 v142, v142, s49, v154
	v_fma_f32 v143, v143, s49, v155
	v_cvt_pk_bf16_f32 v144, v136, v137
	v_cvt_pk_bf16_f32 v145, v138, v139
	v_cvt_pk_bf16_f32 v146, v140, v141
	v_cvt_pk_bf16_f32 v147, v142, v143
	global_store_dwordx4 v2, v[144:147], s[18:19] sc1
	s_add_u32 s18, s18, 0x20000
	s_addc_u32 s19, s19, 0
	v_lshlrev_b32_e32 v148, 16, v80
	v_and_b32_e32 v149, 0xffff0000, v80
	v_lshlrev_b32_e32 v150, 16, v81
	v_and_b32_e32 v151, 0xffff0000, v81
	v_lshlrev_b32_e32 v152, 16, v82
	v_and_b32_e32 v153, 0xffff0000, v82
	v_lshlrev_b32_e32 v154, 16, v83
	v_and_b32_e32 v155, 0xffff0000, v83
	v_fma_f32 v136, v136, s50, v148
	v_fma_f32 v137, v137, s50, v149
	v_fma_f32 v138, v138, s50, v150
	v_fma_f32 v139, v139, s50, v151
	v_fma_f32 v140, v140, s50, v152
	v_fma_f32 v141, v141, s50, v153
	v_fma_f32 v142, v142, s50, v154
	v_fma_f32 v143, v143, s50, v155
	v_cvt_pk_bf16_f32 v144, v136, v137
	v_cvt_pk_bf16_f32 v145, v138, v139
	v_cvt_pk_bf16_f32 v146, v140, v141
	v_cvt_pk_bf16_f32 v147, v142, v143
	global_store_dwordx4 v2, v[144:147], s[18:19] sc1
	s_add_u32 s18, s18, 0x20000
	s_addc_u32 s19, s19, 0
	v_lshlrev_b32_e32 v148, 16, v84
	v_and_b32_e32 v149, 0xffff0000, v84
	v_lshlrev_b32_e32 v150, 16, v85
	v_and_b32_e32 v151, 0xffff0000, v85
	v_lshlrev_b32_e32 v152, 16, v86
	v_and_b32_e32 v153, 0xffff0000, v86
	v_lshlrev_b32_e32 v154, 16, v87
	v_and_b32_e32 v155, 0xffff0000, v87
	v_fma_f32 v136, v136, s51, v148
	v_fma_f32 v137, v137, s51, v149
	v_fma_f32 v138, v138, s51, v150
	v_fma_f32 v139, v139, s51, v151
	v_fma_f32 v140, v140, s51, v152
	v_fma_f32 v141, v141, s51, v153
	v_fma_f32 v142, v142, s51, v154
	v_fma_f32 v143, v143, s51, v155
	v_cvt_pk_bf16_f32 v144, v136, v137
	v_cvt_pk_bf16_f32 v145, v138, v139
	v_cvt_pk_bf16_f32 v146, v140, v141
	v_cvt_pk_bf16_f32 v147, v142, v143
	global_store_dwordx4 v2, v[144:147], s[18:19] sc1
	s_add_u32 s18, s18, 0x20000
	s_addc_u32 s19, s19, 0
	v_lshlrev_b32_e32 v148, 16, v88
	v_and_b32_e32 v149, 0xffff0000, v88
	v_lshlrev_b32_e32 v150, 16, v89
	v_and_b32_e32 v151, 0xffff0000, v89
	v_lshlrev_b32_e32 v152, 16, v90
	v_and_b32_e32 v153, 0xffff0000, v90
	v_lshlrev_b32_e32 v154, 16, v91
	v_and_b32_e32 v155, 0xffff0000, v91
	v_fma_f32 v136, v136, s52, v148
	v_fma_f32 v137, v137, s52, v149
	v_fma_f32 v138, v138, s52, v150
	v_fma_f32 v139, v139, s52, v151
	v_fma_f32 v140, v140, s52, v152
	v_fma_f32 v141, v141, s52, v153
	v_fma_f32 v142, v142, s52, v154
	v_fma_f32 v143, v143, s52, v155
	v_cvt_pk_bf16_f32 v144, v136, v137
	v_cvt_pk_bf16_f32 v145, v138, v139
	v_cvt_pk_bf16_f32 v146, v140, v141
	v_cvt_pk_bf16_f32 v147, v142, v143
	global_store_dwordx4 v2, v[144:147], s[18:19] sc1
	s_add_u32 s18, s18, 0x20000
	s_addc_u32 s19, s19, 0
	v_lshlrev_b32_e32 v148, 16, v92
	v_and_b32_e32 v149, 0xffff0000, v92
	v_lshlrev_b32_e32 v150, 16, v93
	v_and_b32_e32 v151, 0xffff0000, v93
	v_lshlrev_b32_e32 v152, 16, v94
	v_and_b32_e32 v153, 0xffff0000, v94
	v_lshlrev_b32_e32 v154, 16, v95
	v_and_b32_e32 v155, 0xffff0000, v95
	v_fma_f32 v136, v136, s53, v148
	v_fma_f32 v137, v137, s53, v149
	v_fma_f32 v138, v138, s53, v150
	v_fma_f32 v139, v139, s53, v151
	v_fma_f32 v140, v140, s53, v152
	v_fma_f32 v141, v141, s53, v153
	v_fma_f32 v142, v142, s53, v154
	v_fma_f32 v143, v143, s53, v155
	v_cvt_pk_bf16_f32 v144, v136, v137
	v_cvt_pk_bf16_f32 v145, v138, v139
	v_cvt_pk_bf16_f32 v146, v140, v141
	v_cvt_pk_bf16_f32 v147, v142, v143
	global_store_dwordx4 v2, v[144:147], s[18:19] sc1
	s_add_u32 s18, s18, 0x20000
	s_addc_u32 s19, s19, 0
	v_lshlrev_b32_e32 v148, 16, v96
	v_and_b32_e32 v149, 0xffff0000, v96
	v_lshlrev_b32_e32 v150, 16, v97
	v_and_b32_e32 v151, 0xffff0000, v97
	v_lshlrev_b32_e32 v152, 16, v98
	v_and_b32_e32 v153, 0xffff0000, v98
	v_lshlrev_b32_e32 v154, 16, v99
	v_and_b32_e32 v155, 0xffff0000, v99
	v_fma_f32 v136, v136, s54, v148
	v_fma_f32 v137, v137, s54, v149
	v_fma_f32 v138, v138, s54, v150
	v_fma_f32 v139, v139, s54, v151
	v_fma_f32 v140, v140, s54, v152
	v_fma_f32 v141, v141, s54, v153
	v_fma_f32 v142, v142, s54, v154
	v_fma_f32 v143, v143, s54, v155
	v_cvt_pk_bf16_f32 v144, v136, v137
	v_cvt_pk_bf16_f32 v145, v138, v139
	v_cvt_pk_bf16_f32 v146, v140, v141
	v_cvt_pk_bf16_f32 v147, v142, v143
	global_store_dwordx4 v2, v[144:147], s[18:19] sc1
	s_add_u32 s18, s18, 0x20000
	s_addc_u32 s19, s19, 0
	v_lshlrev_b32_e32 v148, 16, v100
	v_and_b32_e32 v149, 0xffff0000, v100
	v_lshlrev_b32_e32 v150, 16, v101
	v_and_b32_e32 v151, 0xffff0000, v101
	v_lshlrev_b32_e32 v152, 16, v102
	v_and_b32_e32 v153, 0xffff0000, v102
	v_lshlrev_b32_e32 v154, 16, v103
	v_and_b32_e32 v155, 0xffff0000, v103
	v_fma_f32 v136, v136, s55, v148
	v_fma_f32 v137, v137, s55, v149
	v_fma_f32 v138, v138, s55, v150
	v_fma_f32 v139, v139, s55, v151
	v_fma_f32 v140, v140, s55, v152
	v_fma_f32 v141, v141, s55, v153
	v_fma_f32 v142, v142, s55, v154
	v_fma_f32 v143, v143, s55, v155
	s_waitcnt vmcnt(24) lgkmcnt(0)
	v_cvt_pk_bf16_f32 v144, v136, v137
	v_cvt_pk_bf16_f32 v145, v138, v139
	v_cvt_pk_bf16_f32 v146, v140, v141
	v_cvt_pk_bf16_f32 v147, v142, v143
	global_store_dwordx4 v2, v[144:147], s[18:19] sc1
	s_add_u32 s18, s18, 0x20000
	s_addc_u32 s19, s19, 0
	v_lshlrev_b32_e32 v148, 16, v104
	v_and_b32_e32 v149, 0xffff0000, v104
	v_lshlrev_b32_e32 v150, 16, v105
	v_and_b32_e32 v151, 0xffff0000, v105
	v_lshlrev_b32_e32 v152, 16, v106
	v_and_b32_e32 v153, 0xffff0000, v106
	v_lshlrev_b32_e32 v154, 16, v107
	v_and_b32_e32 v155, 0xffff0000, v107
	v_fma_f32 v136, v136, s56, v148
	v_fma_f32 v137, v137, s56, v149
	v_fma_f32 v138, v138, s56, v150
	v_fma_f32 v139, v139, s56, v151
	v_fma_f32 v140, v140, s56, v152
	v_fma_f32 v141, v141, s56, v153
	v_fma_f32 v142, v142, s56, v154
	v_fma_f32 v143, v143, s56, v155
	v_cvt_pk_bf16_f32 v144, v136, v137
	v_cvt_pk_bf16_f32 v145, v138, v139
	v_cvt_pk_bf16_f32 v146, v140, v141
	v_cvt_pk_bf16_f32 v147, v142, v143
	global_store_dwordx4 v2, v[144:147], s[18:19] sc1
	s_add_u32 s18, s18, 0x20000
	s_addc_u32 s19, s19, 0
	v_lshlrev_b32_e32 v148, 16, v108
	v_and_b32_e32 v149, 0xffff0000, v108
	v_lshlrev_b32_e32 v150, 16, v109
	v_and_b32_e32 v151, 0xffff0000, v109
	v_lshlrev_b32_e32 v152, 16, v110
	v_and_b32_e32 v153, 0xffff0000, v110
	v_lshlrev_b32_e32 v154, 16, v111
	v_and_b32_e32 v155, 0xffff0000, v111
	v_fma_f32 v136, v136, s57, v148
	v_fma_f32 v137, v137, s57, v149
	v_fma_f32 v138, v138, s57, v150
	v_fma_f32 v139, v139, s57, v151
	v_fma_f32 v140, v140, s57, v152
	v_fma_f32 v141, v141, s57, v153
	v_fma_f32 v142, v142, s57, v154
	v_fma_f32 v143, v143, s57, v155
	v_cvt_pk_bf16_f32 v144, v136, v137
	v_cvt_pk_bf16_f32 v145, v138, v139
	v_cvt_pk_bf16_f32 v146, v140, v141
	v_cvt_pk_bf16_f32 v147, v142, v143
	global_store_dwordx4 v2, v[144:147], s[18:19] sc1
	s_add_u32 s18, s18, 0x20000
	s_addc_u32 s19, s19, 0
	v_lshlrev_b32_e32 v148, 16, v112
	v_and_b32_e32 v149, 0xffff0000, v112
	v_lshlrev_b32_e32 v150, 16, v113
	v_and_b32_e32 v151, 0xffff0000, v113
	v_lshlrev_b32_e32 v152, 16, v114
	v_and_b32_e32 v153, 0xffff0000, v114
	v_lshlrev_b32_e32 v154, 16, v115
	v_and_b32_e32 v155, 0xffff0000, v115
	v_fma_f32 v136, v136, s58, v148
	v_fma_f32 v137, v137, s58, v149
	v_fma_f32 v138, v138, s58, v150
	v_fma_f32 v139, v139, s58, v151
	v_fma_f32 v140, v140, s58, v152
	v_fma_f32 v141, v141, s58, v153
	v_fma_f32 v142, v142, s58, v154
	v_fma_f32 v143, v143, s58, v155
	v_cvt_pk_bf16_f32 v144, v136, v137
	v_cvt_pk_bf16_f32 v145, v138, v139
	v_cvt_pk_bf16_f32 v146, v140, v141
	v_cvt_pk_bf16_f32 v147, v142, v143
	global_store_dwordx4 v2, v[144:147], s[18:19] sc1
	s_add_u32 s18, s18, 0x20000
	s_addc_u32 s19, s19, 0
	v_lshlrev_b32_e32 v148, 16, v116
	v_and_b32_e32 v149, 0xffff0000, v116
	v_lshlrev_b32_e32 v150, 16, v117
	v_and_b32_e32 v151, 0xffff0000, v117
	v_lshlrev_b32_e32 v152, 16, v118
	v_and_b32_e32 v153, 0xffff0000, v118
	v_lshlrev_b32_e32 v154, 16, v119
	v_and_b32_e32 v155, 0xffff0000, v119
	v_fma_f32 v136, v136, s59, v148
	v_fma_f32 v137, v137, s59, v149
	v_fma_f32 v138, v138, s59, v150
	v_fma_f32 v139, v139, s59, v151
	v_fma_f32 v140, v140, s59, v152
	v_fma_f32 v141, v141, s59, v153
	v_fma_f32 v142, v142, s59, v154
	v_fma_f32 v143, v143, s59, v155
	v_cvt_pk_bf16_f32 v144, v136, v137
	v_cvt_pk_bf16_f32 v145, v138, v139
	v_cvt_pk_bf16_f32 v146, v140, v141
	v_cvt_pk_bf16_f32 v147, v142, v143
	global_store_dwordx4 v2, v[144:147], s[18:19] sc1
	s_add_u32 s18, s18, 0x20000
	s_addc_u32 s19, s19, 0
	v_lshlrev_b32_e32 v148, 16, v120
	v_and_b32_e32 v149, 0xffff0000, v120
	v_lshlrev_b32_e32 v150, 16, v121
	v_and_b32_e32 v151, 0xffff0000, v121
	v_lshlrev_b32_e32 v152, 16, v122
	v_and_b32_e32 v153, 0xffff0000, v122
	v_lshlrev_b32_e32 v154, 16, v123
	v_and_b32_e32 v155, 0xffff0000, v123
	v_fma_f32 v136, v136, s60, v148
	v_fma_f32 v137, v137, s60, v149
	v_fma_f32 v138, v138, s60, v150
	v_fma_f32 v139, v139, s60, v151
	v_fma_f32 v140, v140, s60, v152
	v_fma_f32 v141, v141, s60, v153
	v_fma_f32 v142, v142, s60, v154
	v_fma_f32 v143, v143, s60, v155
	v_cvt_pk_bf16_f32 v144, v136, v137
	v_cvt_pk_bf16_f32 v145, v138, v139
	v_cvt_pk_bf16_f32 v146, v140, v141
	v_cvt_pk_bf16_f32 v147, v142, v143
	global_store_dwordx4 v2, v[144:147], s[18:19] sc1
	s_add_u32 s18, s18, 0x20000
	s_addc_u32 s19, s19, 0
	v_lshlrev_b32_e32 v148, 16, v124
	v_and_b32_e32 v149, 0xffff0000, v124
	v_lshlrev_b32_e32 v150, 16, v125
	v_and_b32_e32 v151, 0xffff0000, v125
	v_lshlrev_b32_e32 v152, 16, v126
	v_and_b32_e32 v153, 0xffff0000, v126
	v_lshlrev_b32_e32 v154, 16, v127
	v_and_b32_e32 v155, 0xffff0000, v127
	v_fma_f32 v136, v136, s61, v148
	v_fma_f32 v137, v137, s61, v149
	v_fma_f32 v138, v138, s61, v150
	v_fma_f32 v139, v139, s61, v151
	v_fma_f32 v140, v140, s61, v152
	v_fma_f32 v141, v141, s61, v153
	v_fma_f32 v142, v142, s61, v154
	v_fma_f32 v143, v143, s61, v155
	v_cvt_pk_bf16_f32 v144, v136, v137
	v_cvt_pk_bf16_f32 v145, v138, v139
	v_cvt_pk_bf16_f32 v146, v140, v141
	v_cvt_pk_bf16_f32 v147, v142, v143
	global_store_dwordx4 v2, v[144:147], s[18:19] sc1
	s_add_u32 s18, s18, 0x20000
	s_addc_u32 s19, s19, 0
	v_lshlrev_b32_e32 v148, 16, v128
	v_and_b32_e32 v149, 0xffff0000, v128
	v_lshlrev_b32_e32 v150, 16, v129
	v_and_b32_e32 v151, 0xffff0000, v129
	v_lshlrev_b32_e32 v152, 16, v130
	v_and_b32_e32 v153, 0xffff0000, v130
	v_lshlrev_b32_e32 v154, 16, v131
	v_and_b32_e32 v155, 0xffff0000, v131
	v_fma_f32 v136, v136, s62, v148
	v_fma_f32 v137, v137, s62, v149
	v_fma_f32 v138, v138, s62, v150
	v_fma_f32 v139, v139, s62, v151
	v_fma_f32 v140, v140, s62, v152
	v_fma_f32 v141, v141, s62, v153
	v_fma_f32 v142, v142, s62, v154
	v_fma_f32 v143, v143, s62, v155
	v_cvt_pk_bf16_f32 v144, v136, v137
	v_cvt_pk_bf16_f32 v145, v138, v139
	v_cvt_pk_bf16_f32 v146, v140, v141
	v_cvt_pk_bf16_f32 v147, v142, v143
	global_store_dwordx4 v2, v[144:147], s[18:19] sc1
	s_add_u32 s18, s18, 0x20000
	s_addc_u32 s19, s19, 0
	v_lshlrev_b32_e32 v148, 16, v132
	v_and_b32_e32 v149, 0xffff0000, v132
	v_lshlrev_b32_e32 v150, 16, v133
	v_and_b32_e32 v151, 0xffff0000, v133
	v_lshlrev_b32_e32 v152, 16, v134
	v_and_b32_e32 v153, 0xffff0000, v134
	v_lshlrev_b32_e32 v154, 16, v135
	v_and_b32_e32 v155, 0xffff0000, v135
	v_fma_f32 v136, v136, s63, v148
	v_fma_f32 v137, v137, s63, v149
	v_fma_f32 v138, v138, s63, v150
	v_fma_f32 v139, v139, s63, v151
	v_fma_f32 v140, v140, s63, v152
	v_fma_f32 v141, v141, s63, v153
	v_fma_f32 v142, v142, s63, v154
	v_fma_f32 v143, v143, s63, v155
